# PEER u and v phases both hand-written with per-XCD L2-resident column slices, 16-deep row-load ring, coalesced partial-dot stores, separate combine and norm phases
# speedup vs baseline: 1.0741x; 1.0741x over previous
; DI void phase_peer_v(const Args& a, int layer, int ci) {
;     ...
;     const unsigned char* V = ws + WS_V + (size_t)layer * NEXP * D + ci * 1024;
;     const unsigned lo16 = (unsigned)lane * 16u;
;     const int* IDX = (const int*)(ws + WS_IDX);
;     const float* GH = (const float*)(ws + WS_GATE);
;     int m = gw;
;     if (m < M) {
;         int idA = IDX[(size_t)m * 128 + lane], idB = IDX[(size_t)m * 128 + 64 + lane];
;         u32x4 cur[8];
;         gat_loadh(V, idA, idB, 0, lo16, cur);
; #pragma unroll 1
;         for (; m < M; m += NGW) {
;             const int mn = m + NGW < M ? m + NGW : m;
;             const int idAn = IDX[(size_t)mn * 128 + lane], idBn = IDX[(size_t)mn * 128 + 64 + lane];
;             const float ghA = GH[(size_t)m * 128 + lane], ghB = GH[(size_t)m * 128 + 64 + lane];
;             float acc[16];
; #pragma unroll
;             for (int i = 0; i < 16; ++i) acc[i] = 0.f;
; #pragma unroll 1
;             for (int g8 = 0; g8 < 16; ++g8) {
;                 u32x4 nxt[8];
;                 if (g8 < 15) gat_loadh(V, idA, idB, g8 + 1, lo16, nxt); else gat_loadh(V, idAn, idBn, 0, lo16, nxt);
.Lpv_entry:
	v_readlane_b32 s1, v252, 0
	v_readlane_b32 s19, v255, 12
	v_lshrrev_b32_e32 v5, 6, v185
	v_and_b32_e32 v6, 63, v185
	v_and_b32_e32 v7, 7, v6
	v_lshrrev_b32_e32 v6, 3, v6
	v_readfirstlane_b32 s44, v5
	v_lshlrev_b32_e32 v0, 4, v7
	v_lshlrev_b32_e32 v1, 9, v6
	v_lshlrev_b32_e32 v2, 13, v6
	v_lshl_or_b32 v2, v7, 6, v2
	s_lshr_b32 s45, s1, 3
	s_lshl_b32 s45, s45, 3
	s_add_u32 s45, s45, s44
	s_lshl_b32 s8, s45, 12
	s_and_b32 s9, s1, 7
	s_lshl_b32 s9, s9, 1
	s_lshl_b32 s46, s19, 25
	s_add_u32 s16, s98, 0x10000000
	s_addc_u32 s17, s99, 0
	s_add_u32 s16, s16, s46
	s_addc_u32 s17, s17, 0
	s_mov_b32 s0, 0
	s_bfe_u32 s45, s0, 0x40003
	s_lshl_b32 s45, s45, 20
	s_and_b32 s46, s0, 7
	s_lshl_b32 s46, s46, 6
	s_add_u32 s45, s45, s46
	s_add_u32 s45, s45, s8
	s_add_u32 s45, s45, 0x6000000
	s_add_u32 s22, s98, s45
	s_addc_u32 s23, s99, 0
	global_load_dwordx4 v[72:75], v1, s[22:23]
	global_load_dwordx4 v[76:79], v1, s[22:23] offset:16
	global_load_dwordx4 v[80:83], v1, s[22:23] offset:32
	global_load_dwordx4 v[84:87], v1, s[22:23] offset:48
	global_load_dwordx4 v[88:91], v1, s[22:23] offset:64
	global_load_dwordx4 v[92:95], v1, s[22:23] offset:80
	global_load_dwordx4 v[96:99], v1, s[22:23] offset:96
	global_load_dwordx4 v[100:103], v1, s[22:23] offset:112
	s_bfe_u32 s45, s0, 0x40003
	s_lshl_b32 s45, s45, 20
	s_and_b32 s46, s0, 7
	s_lshl_b32 s46, s46, 6
	s_add_u32 s45, s45, s46
	s_add_u32 s45, s45, s8
	s_add_u32 s45, s45, 0x7000000
	s_add_u32 s24, s98, s45
	s_addc_u32 s25, s99, 0
	global_load_dwordx4 v[104:107], v1, s[24:25]
	global_load_dwordx4 v[108:111], v1, s[24:25] offset:16
	global_load_dwordx4 v[112:115], v1, s[24:25] offset:32
	global_load_dwordx4 v[116:119], v1, s[24:25] offset:48
	s_lshr_b32 s46, s0, 7
	s_add_u32 s46, s46, s9
	s_lshl_b32 s46, s46, 21
	s_add_u32 s40, s16, s46
	s_addc_u32 s41, s17, 0
	v_mov_b64_e32 v[156:157], 0
	v_mov_b64_e32 v[158:159], 0
	v_mov_b64_e32 v[160:161], 0
	v_mov_b64_e32 v[162:163], 0
	v_mov_b64_e32 v[166:167], 0
	v_mov_b64_e32 v[168:169], 0
	v_mov_b64_e32 v[170:171], 0
	v_mov_b64_e32 v[172:173], 0
	s_waitcnt vmcnt(4)
	v_lshl_add_u32 v3, v72, 7, v0
	global_load_dwordx4 v[8:11], v3, s[40:41]
	v_lshl_add_u32 v4, v73, 7, v0
	global_load_dwordx4 v[12:15], v4, s[40:41]
	v_lshl_add_u32 v3, v74, 7, v0
	global_load_dwordx4 v[16:19], v3, s[40:41]
	v_lshl_add_u32 v4, v75, 7, v0
	global_load_dwordx4 v[20:23], v4, s[40:41]
	v_lshl_add_u32 v3, v76, 7, v0
	global_load_dwordx4 v[24:27], v3, s[40:41]
	v_lshl_add_u32 v4, v77, 7, v0
	global_load_dwordx4 v[28:31], v4, s[40:41]
	v_lshl_add_u32 v3, v78, 7, v0
	global_load_dwordx4 v[32:35], v3, s[40:41]
	v_lshl_add_u32 v4, v79, 7, v0
	global_load_dwordx4 v[36:39], v4, s[40:41]
	v_lshl_add_u32 v3, v80, 7, v0
	global_load_dwordx4 v[40:43], v3, s[40:41]
	v_lshl_add_u32 v4, v81, 7, v0
	global_load_dwordx4 v[44:47], v4, s[40:41]
	v_lshl_add_u32 v3, v82, 7, v0
	global_load_dwordx4 v[48:51], v3, s[40:41]
	v_lshl_add_u32 v4, v83, 7, v0
	global_load_dwordx4 v[52:55], v4, s[40:41]
	v_lshl_add_u32 v3, v84, 7, v0
	global_load_dwordx4 v[56:59], v3, s[40:41]
	v_lshl_add_u32 v4, v85, 7, v0
	global_load_dwordx4 v[60:63], v4, s[40:41]
	v_lshl_add_u32 v3, v86, 7, v0
	global_load_dwordx4 v[64:67], v3, s[40:41]
	v_lshl_add_u32 v4, v87, 7, v0
	global_load_dwordx4 v[68:71], v4, s[40:41]
.Lpv_loop:
	s_add_u32 s44, s0, 1
	s_min_u32 s44, s44, 0xff
	s_bfe_u32 s45, s44, 0x40003
	s_lshl_b32 s45, s45, 20
	s_and_b32 s46, s44, 7
	s_lshl_b32 s46, s46, 6
	s_add_u32 s45, s45, s46
	s_add_u32 s45, s45, s8
	s_add_u32 s45, s45, 0x7000000
	s_add_u32 s24, s98, s45
	s_addc_u32 s25, s99, 0
	s_lshr_b32 s46, s44, 7
	s_add_u32 s46, s46, s9
	s_lshl_b32 s46, s46, 21
	s_add_u32 s40, s16, s46
	s_addc_u32 s41, s17, 0
	s_add_u32 s44, s0, 2
	s_min_u32 s44, s44, 0xff
	s_bfe_u32 s45, s44, 0x40003
	s_lshl_b32 s45, s45, 20
	s_and_b32 s46, s44, 7
	s_lshl_b32 s46, s46, 6
	s_add_u32 s45, s45, s46
	s_add_u32 s45, s45, s8
	s_add_u32 s45, s45, 0x6000000
	s_add_u32 s22, s98, s45
	s_addc_u32 s23, s99, 0
	s_and_b32 s47, s0, 7
	s_cmp_eq_u32 s47, 7
	s_cbranch_scc0 .Lpv_b0_noout
	s_bfe_u32 s45, s0, 0x40003
	s_lshl_b32 s45, s45, 24
	s_lshl_b32 s46, s8, 4
	s_add_u32 s45, s45, s46
	s_lshr_b32 s46, s0, 7
	s_add_u32 s46, s46, s9
	s_lshl_b32 s46, s46, 9
	s_add_u32 s45, s45, s46
	s_add_u32 s42, s96, s45
	s_addc_u32 s43, s97, 0
	global_load_dwordx4 v[216:219], v2, s[42:43]
	global_load_dwordx4 v[220:223], v2, s[42:43] offset:16
	global_load_dwordx4 v[224:227], v2, s[42:43] offset:32
	global_load_dwordx4 v[174:177], v2, s[42:43] offset:48
; #define FP8_LO(w) __builtin_amdgcn_cvt_pk_f32_fp8((int)(w), false)
; #define FP8_HI(w) __builtin_amdgcn_cvt_pk_f32_fp8((int)(w), true)
; DI void axpy16h(float (&acc)[16], float g, const u32x4 w) {
;     const f32x2 a0 = FP8_LO(w.x), a1 = FP8_HI(w.x), a2 = FP8_LO(w.y), a3 = FP8_HI(w.y), a4 = FP8_LO(w.z), a5 = FP8_HI(w.z), a6 = FP8_LO(w.w), a7 = FP8_HI(w.w);
;     acc[0] += g * a0.x; acc[1] += g * a0.y; acc[2] += g * a1.x; acc[3] += g * a1.y; acc[4] += g * a2.x; acc[5] += g * a2.y; acc[6] += g * a3.x; acc[7] += g * a3.y;
;     acc[8] += g * a4.x; acc[9] += g * a4.y; acc[10] += g * a5.x; acc[11] += g * a5.y; acc[12] += g * a6.x; acc[13] += g * a6.y; acc[14] += g * a7.x; acc[15] += g * a7.y;
; }
; DI void phase_peer_v(const Args& a, int layer, int ci) {
;     ...
;             for (int g8 = 0; g8 < 16; ++g8) {
;                 u32x4 nxt[8];
;                 if (g8 < 15) gat_loadh(V, idA, idB, g8 + 1, lo16, nxt); else gat_loadh(V, idAn, idBn, 0, lo16, nxt);
;                 const float ghs = g8 < 8 ? ghA : ghB;
; #pragma unroll
;                 for (int j = 0; j < 8; ++j) { const float gv = __shfl(ghs, (g8 & 7) * 8 + j); axpy16h(acc, gv, cur[j]); if (j & 1) __builtin_amdgcn_sched_barrier(0); }
; #pragma unroll
;                 for (int j = 0; j < 8; ++j) cur[j] = nxt[j];
.Lpv_b0_noout:
	global_load_dwordx4 v[140:143], v1, s[24:25]
	global_load_dwordx4 v[144:147], v1, s[24:25] offset:16
	global_load_dwordx4 v[148:151], v1, s[24:25] offset:32
	global_load_dwordx4 v[152:155], v1, s[24:25] offset:48
	global_load_dwordx4 v[72:75], v1, s[22:23]
	global_load_dwordx4 v[76:79], v1, s[22:23] offset:16
	global_load_dwordx4 v[80:83], v1, s[22:23] offset:32
	global_load_dwordx4 v[84:87], v1, s[22:23] offset:48
	s_waitcnt vmcnt(23)
	v_cvt_pk_f32_fp8_e32 v[120:121], v8
	v_cvt_pk_f32_fp8_sdwa v[122:123], v8 src0_sel:WORD_1
	v_cvt_pk_f32_fp8_e32 v[124:125], v9
	v_cvt_pk_f32_fp8_sdwa v[126:127], v9 src0_sel:WORD_1
	v_pk_fma_f32 v[156:157], v[120:121], v[104:105], v[156:157] op_sel_hi:[1,0,1]
	v_pk_fma_f32 v[158:159], v[122:123], v[104:105], v[158:159] op_sel_hi:[1,0,1]
	v_pk_fma_f32 v[160:161], v[124:125], v[104:105], v[160:161] op_sel_hi:[1,0,1]
	v_pk_fma_f32 v[162:163], v[126:127], v[104:105], v[162:163] op_sel_hi:[1,0,1]
	v_cvt_pk_f32_fp8_e32 v[120:121], v10
	v_cvt_pk_f32_fp8_sdwa v[122:123], v10 src0_sel:WORD_1
	v_cvt_pk_f32_fp8_e32 v[124:125], v11
	v_cvt_pk_f32_fp8_sdwa v[126:127], v11 src0_sel:WORD_1
	v_pk_fma_f32 v[166:167], v[120:121], v[104:105], v[166:167] op_sel_hi:[1,0,1]
	v_pk_fma_f32 v[168:169], v[122:123], v[104:105], v[168:169] op_sel_hi:[1,0,1]
	v_pk_fma_f32 v[170:171], v[124:125], v[104:105], v[170:171] op_sel_hi:[1,0,1]
	v_pk_fma_f32 v[172:173], v[126:127], v[104:105], v[172:173] op_sel_hi:[1,0,1]
	v_lshl_add_u32 v3, v88, 7, v0
	global_load_dwordx4 v[8:11], v3, s[40:41]
	s_waitcnt vmcnt(23)
	v_cvt_pk_f32_fp8_e32 v[120:121], v12
	v_cvt_pk_f32_fp8_sdwa v[122:123], v12 src0_sel:WORD_1
	v_cvt_pk_f32_fp8_e32 v[124:125], v13
	v_cvt_pk_f32_fp8_sdwa v[126:127], v13 src0_sel:WORD_1
	v_pk_fma_f32 v[156:157], v[120:121], v[104:105], v[156:157] op_sel:[0,1,0] op_sel_hi:[1,1,1]
	v_pk_fma_f32 v[158:159], v[122:123], v[104:105], v[158:159] op_sel:[0,1,0] op_sel_hi:[1,1,1]
	v_pk_fma_f32 v[160:161], v[124:125], v[104:105], v[160:161] op_sel:[0,1,0] op_sel_hi:[1,1,1]
	v_pk_fma_f32 v[162:163], v[126:127], v[104:105], v[162:163] op_sel:[0,1,0] op_sel_hi:[1,1,1]
	v_cvt_pk_f32_fp8_e32 v[120:121], v14
	v_cvt_pk_f32_fp8_sdwa v[122:123], v14 src0_sel:WORD_1
	v_cvt_pk_f32_fp8_e32 v[124:125], v15
	v_cvt_pk_f32_fp8_sdwa v[126:127], v15 src0_sel:WORD_1
	v_pk_fma_f32 v[166:167], v[120:121], v[104:105], v[166:167] op_sel:[0,1,0] op_sel_hi:[1,1,1]
	v_pk_fma_f32 v[168:169], v[122:123], v[104:105], v[168:169] op_sel:[0,1,0] op_sel_hi:[1,1,1]
	v_pk_fma_f32 v[170:171], v[124:125], v[104:105], v[170:171] op_sel:[0,1,0] op_sel_hi:[1,1,1]
	v_pk_fma_f32 v[172:173], v[126:127], v[104:105], v[172:173] op_sel:[0,1,0] op_sel_hi:[1,1,1]
	v_lshl_add_u32 v4, v89, 7, v0
	global_load_dwordx4 v[12:15], v4, s[40:41]
	s_waitcnt vmcnt(23)
	v_cvt_pk_f32_fp8_e32 v[120:121], v16
	v_cvt_pk_f32_fp8_sdwa v[122:123], v16 src0_sel:WORD_1
	v_cvt_pk_f32_fp8_e32 v[124:125], v17
	v_cvt_pk_f32_fp8_sdwa v[126:127], v17 src0_sel:WORD_1
	v_pk_fma_f32 v[156:157], v[120:121], v[106:107], v[156:157] op_sel_hi:[1,0,1]
	v_pk_fma_f32 v[158:159], v[122:123], v[106:107], v[158:159] op_sel_hi:[1,0,1]
	v_pk_fma_f32 v[160:161], v[124:125], v[106:107], v[160:161] op_sel_hi:[1,0,1]
	v_pk_fma_f32 v[162:163], v[126:127], v[106:107], v[162:163] op_sel_hi:[1,0,1]
	v_cvt_pk_f32_fp8_e32 v[120:121], v18
	v_cvt_pk_f32_fp8_sdwa v[122:123], v18 src0_sel:WORD_1
	v_cvt_pk_f32_fp8_e32 v[124:125], v19
	v_cvt_pk_f32_fp8_sdwa v[126:127], v19 src0_sel:WORD_1
	v_pk_fma_f32 v[166:167], v[120:121], v[106:107], v[166:167] op_sel_hi:[1,0,1]
	v_pk_fma_f32 v[168:169], v[122:123], v[106:107], v[168:169] op_sel_hi:[1,0,1]
	v_pk_fma_f32 v[170:171], v[124:125], v[106:107], v[170:171] op_sel_hi:[1,0,1]
	v_pk_fma_f32 v[172:173], v[126:127], v[106:107], v[172:173] op_sel_hi:[1,0,1]
	v_lshl_add_u32 v3, v90, 7, v0
	global_load_dwordx4 v[16:19], v3, s[40:41]
	s_waitcnt vmcnt(23)
	v_cvt_pk_f32_fp8_e32 v[120:121], v20
	v_cvt_pk_f32_fp8_sdwa v[122:123], v20 src0_sel:WORD_1
	v_cvt_pk_f32_fp8_e32 v[124:125], v21
	v_cvt_pk_f32_fp8_sdwa v[126:127], v21 src0_sel:WORD_1
	v_pk_fma_f32 v[156:157], v[120:121], v[106:107], v[156:157] op_sel:[0,1,0] op_sel_hi:[1,1,1]
	v_pk_fma_f32 v[158:159], v[122:123], v[106:107], v[158:159] op_sel:[0,1,0] op_sel_hi:[1,1,1]
	v_pk_fma_f32 v[160:161], v[124:125], v[106:107], v[160:161] op_sel:[0,1,0] op_sel_hi:[1,1,1]
	v_pk_fma_f32 v[162:163], v[126:127], v[106:107], v[162:163] op_sel:[0,1,0] op_sel_hi:[1,1,1]
	v_cvt_pk_f32_fp8_e32 v[120:121], v22
	v_cvt_pk_f32_fp8_sdwa v[122:123], v22 src0_sel:WORD_1
	v_cvt_pk_f32_fp8_e32 v[124:125], v23
	v_cvt_pk_f32_fp8_sdwa v[126:127], v23 src0_sel:WORD_1
	v_pk_fma_f32 v[166:167], v[120:121], v[106:107], v[166:167] op_sel:[0,1,0] op_sel_hi:[1,1,1]
	v_pk_fma_f32 v[168:169], v[122:123], v[106:107], v[168:169] op_sel:[0,1,0] op_sel_hi:[1,1,1]
	v_pk_fma_f32 v[170:171], v[124:125], v[106:107], v[170:171] op_sel:[0,1,0] op_sel_hi:[1,1,1]
	v_pk_fma_f32 v[172:173], v[126:127], v[106:107], v[172:173] op_sel:[0,1,0] op_sel_hi:[1,1,1]
	v_lshl_add_u32 v4, v91, 7, v0
	global_load_dwordx4 v[20:23], v4, s[40:41]
	s_waitcnt vmcnt(23)
; #define FP8_LO(w) __builtin_amdgcn_cvt_pk_f32_fp8((int)(w), false)
; #define FP8_HI(w) __builtin_amdgcn_cvt_pk_f32_fp8((int)(w), true)
; DI void axpy16h(float (&acc)[16], float g, const u32x4 w) {
;     const f32x2 a0 = FP8_LO(w.x), a1 = FP8_HI(w.x), a2 = FP8_LO(w.y), a3 = FP8_HI(w.y), a4 = FP8_LO(w.z), a5 = FP8_HI(w.z), a6 = FP8_LO(w.w), a7 = FP8_HI(w.w);
;     acc[0] += g * a0.x; acc[1] += g * a0.y; acc[2] += g * a1.x; acc[3] += g * a1.y; acc[4] += g * a2.x; acc[5] += g * a2.y; acc[6] += g * a3.x; acc[7] += g * a3.y;
;     acc[8] += g * a4.x; acc[9] += g * a4.y; acc[10] += g * a5.x; acc[11] += g * a5.y; acc[12] += g * a6.x; acc[13] += g * a6.y; acc[14] += g * a7.x; acc[15] += g * a7.y;
; }
; DI void phase_peer_v(const Args& a, int layer, int ci) {
;     ...
;             for (int g8 = 0; g8 < 16; ++g8) {
;                 u32x4 nxt[8];
;                 if (g8 < 15) gat_loadh(V, idA, idB, g8 + 1, lo16, nxt); else gat_loadh(V, idAn, idBn, 0, lo16, nxt);
;                 const float ghs = g8 < 8 ? ghA : ghB;
; #pragma unroll
;                 for (int j = 0; j < 8; ++j) { const float gv = __shfl(ghs, (g8 & 7) * 8 + j); axpy16h(acc, gv, cur[j]); if (j & 1) __builtin_amdgcn_sched_barrier(0); }
; #pragma unroll
;                 for (int j = 0; j < 8; ++j) cur[j] = nxt[j];
	v_cvt_pk_f32_fp8_e32 v[120:121], v24
	v_cvt_pk_f32_fp8_sdwa v[122:123], v24 src0_sel:WORD_1
	v_cvt_pk_f32_fp8_e32 v[124:125], v25
	v_cvt_pk_f32_fp8_sdwa v[126:127], v25 src0_sel:WORD_1
	v_pk_fma_f32 v[156:157], v[120:121], v[108:109], v[156:157] op_sel_hi:[1,0,1]
	v_pk_fma_f32 v[158:159], v[122:123], v[108:109], v[158:159] op_sel_hi:[1,0,1]
	v_pk_fma_f32 v[160:161], v[124:125], v[108:109], v[160:161] op_sel_hi:[1,0,1]
	v_pk_fma_f32 v[162:163], v[126:127], v[108:109], v[162:163] op_sel_hi:[1,0,1]
	v_cvt_pk_f32_fp8_e32 v[120:121], v26
	v_cvt_pk_f32_fp8_sdwa v[122:123], v26 src0_sel:WORD_1
	v_cvt_pk_f32_fp8_e32 v[124:125], v27
	v_cvt_pk_f32_fp8_sdwa v[126:127], v27 src0_sel:WORD_1
	v_pk_fma_f32 v[166:167], v[120:121], v[108:109], v[166:167] op_sel_hi:[1,0,1]
	v_pk_fma_f32 v[168:169], v[122:123], v[108:109], v[168:169] op_sel_hi:[1,0,1]
	v_pk_fma_f32 v[170:171], v[124:125], v[108:109], v[170:171] op_sel_hi:[1,0,1]
	v_pk_fma_f32 v[172:173], v[126:127], v[108:109], v[172:173] op_sel_hi:[1,0,1]
	v_lshl_add_u32 v3, v92, 7, v0
	global_load_dwordx4 v[24:27], v3, s[40:41]
	s_waitcnt vmcnt(23)
	v_cvt_pk_f32_fp8_e32 v[120:121], v28
	v_cvt_pk_f32_fp8_sdwa v[122:123], v28 src0_sel:WORD_1
	v_cvt_pk_f32_fp8_e32 v[124:125], v29
	v_cvt_pk_f32_fp8_sdwa v[126:127], v29 src0_sel:WORD_1
	v_pk_fma_f32 v[156:157], v[120:121], v[108:109], v[156:157] op_sel:[0,1,0] op_sel_hi:[1,1,1]
	v_pk_fma_f32 v[158:159], v[122:123], v[108:109], v[158:159] op_sel:[0,1,0] op_sel_hi:[1,1,1]
	v_pk_fma_f32 v[160:161], v[124:125], v[108:109], v[160:161] op_sel:[0,1,0] op_sel_hi:[1,1,1]
	v_pk_fma_f32 v[162:163], v[126:127], v[108:109], v[162:163] op_sel:[0,1,0] op_sel_hi:[1,1,1]
	v_cvt_pk_f32_fp8_e32 v[120:121], v30
	v_cvt_pk_f32_fp8_sdwa v[122:123], v30 src0_sel:WORD_1
	v_cvt_pk_f32_fp8_e32 v[124:125], v31
	v_cvt_pk_f32_fp8_sdwa v[126:127], v31 src0_sel:WORD_1
	v_pk_fma_f32 v[166:167], v[120:121], v[108:109], v[166:167] op_sel:[0,1,0] op_sel_hi:[1,1,1]
	v_pk_fma_f32 v[168:169], v[122:123], v[108:109], v[168:169] op_sel:[0,1,0] op_sel_hi:[1,1,1]
	v_pk_fma_f32 v[170:171], v[124:125], v[108:109], v[170:171] op_sel:[0,1,0] op_sel_hi:[1,1,1]
	v_pk_fma_f32 v[172:173], v[126:127], v[108:109], v[172:173] op_sel:[0,1,0] op_sel_hi:[1,1,1]
	v_lshl_add_u32 v4, v93, 7, v0
	global_load_dwordx4 v[28:31], v4, s[40:41]
	s_waitcnt vmcnt(23)
	v_cvt_pk_f32_fp8_e32 v[120:121], v32
	v_cvt_pk_f32_fp8_sdwa v[122:123], v32 src0_sel:WORD_1
	v_cvt_pk_f32_fp8_e32 v[124:125], v33
	v_cvt_pk_f32_fp8_sdwa v[126:127], v33 src0_sel:WORD_1
	v_pk_fma_f32 v[156:157], v[120:121], v[110:111], v[156:157] op_sel_hi:[1,0,1]
	v_pk_fma_f32 v[158:159], v[122:123], v[110:111], v[158:159] op_sel_hi:[1,0,1]
	v_pk_fma_f32 v[160:161], v[124:125], v[110:111], v[160:161] op_sel_hi:[1,0,1]
	v_pk_fma_f32 v[162:163], v[126:127], v[110:111], v[162:163] op_sel_hi:[1,0,1]
	v_cvt_pk_f32_fp8_e32 v[120:121], v34
	v_cvt_pk_f32_fp8_sdwa v[122:123], v34 src0_sel:WORD_1
	v_cvt_pk_f32_fp8_e32 v[124:125], v35
	v_cvt_pk_f32_fp8_sdwa v[126:127], v35 src0_sel:WORD_1
	v_pk_fma_f32 v[166:167], v[120:121], v[110:111], v[166:167] op_sel_hi:[1,0,1]
	v_pk_fma_f32 v[168:169], v[122:123], v[110:111], v[168:169] op_sel_hi:[1,0,1]
	v_pk_fma_f32 v[170:171], v[124:125], v[110:111], v[170:171] op_sel_hi:[1,0,1]
	v_pk_fma_f32 v[172:173], v[126:127], v[110:111], v[172:173] op_sel_hi:[1,0,1]
	v_lshl_add_u32 v3, v94, 7, v0
	global_load_dwordx4 v[32:35], v3, s[40:41]
	s_waitcnt vmcnt(23)
	v_cvt_pk_f32_fp8_e32 v[120:121], v36
	v_cvt_pk_f32_fp8_sdwa v[122:123], v36 src0_sel:WORD_1
	v_cvt_pk_f32_fp8_e32 v[124:125], v37
	v_cvt_pk_f32_fp8_sdwa v[126:127], v37 src0_sel:WORD_1
	v_pk_fma_f32 v[156:157], v[120:121], v[110:111], v[156:157] op_sel:[0,1,0] op_sel_hi:[1,1,1]
	v_pk_fma_f32 v[158:159], v[122:123], v[110:111], v[158:159] op_sel:[0,1,0] op_sel_hi:[1,1,1]
	v_pk_fma_f32 v[160:161], v[124:125], v[110:111], v[160:161] op_sel:[0,1,0] op_sel_hi:[1,1,1]
	v_pk_fma_f32 v[162:163], v[126:127], v[110:111], v[162:163] op_sel:[0,1,0] op_sel_hi:[1,1,1]
	v_cvt_pk_f32_fp8_e32 v[120:121], v38
	v_cvt_pk_f32_fp8_sdwa v[122:123], v38 src0_sel:WORD_1
	v_cvt_pk_f32_fp8_e32 v[124:125], v39
	v_cvt_pk_f32_fp8_sdwa v[126:127], v39 src0_sel:WORD_1
	v_pk_fma_f32 v[166:167], v[120:121], v[110:111], v[166:167] op_sel:[0,1,0] op_sel_hi:[1,1,1]
	v_pk_fma_f32 v[168:169], v[122:123], v[110:111], v[168:169] op_sel:[0,1,0] op_sel_hi:[1,1,1]
	v_pk_fma_f32 v[170:171], v[124:125], v[110:111], v[170:171] op_sel:[0,1,0] op_sel_hi:[1,1,1]
	v_pk_fma_f32 v[172:173], v[126:127], v[110:111], v[172:173] op_sel:[0,1,0] op_sel_hi:[1,1,1]
	v_lshl_add_u32 v4, v95, 7, v0
	global_load_dwordx4 v[36:39], v4, s[40:41]
	s_waitcnt vmcnt(23)
	v_cvt_pk_f32_fp8_e32 v[120:121], v40
	v_cvt_pk_f32_fp8_sdwa v[122:123], v40 src0_sel:WORD_1
	v_cvt_pk_f32_fp8_e32 v[124:125], v41
	v_cvt_pk_f32_fp8_sdwa v[126:127], v41 src0_sel:WORD_1
	v_pk_fma_f32 v[156:157], v[120:121], v[112:113], v[156:157] op_sel_hi:[1,0,1]
	v_pk_fma_f32 v[158:159], v[122:123], v[112:113], v[158:159] op_sel_hi:[1,0,1]
	v_pk_fma_f32 v[160:161], v[124:125], v[112:113], v[160:161] op_sel_hi:[1,0,1]
	v_pk_fma_f32 v[162:163], v[126:127], v[112:113], v[162:163] op_sel_hi:[1,0,1]
	v_cvt_pk_f32_fp8_e32 v[120:121], v42
	v_cvt_pk_f32_fp8_sdwa v[122:123], v42 src0_sel:WORD_1
	v_cvt_pk_f32_fp8_e32 v[124:125], v43
	v_cvt_pk_f32_fp8_sdwa v[126:127], v43 src0_sel:WORD_1
	v_pk_fma_f32 v[166:167], v[120:121], v[112:113], v[166:167] op_sel_hi:[1,0,1]
	v_pk_fma_f32 v[168:169], v[122:123], v[112:113], v[168:169] op_sel_hi:[1,0,1]
	v_pk_fma_f32 v[170:171], v[124:125], v[112:113], v[170:171] op_sel_hi:[1,0,1]
	v_pk_fma_f32 v[172:173], v[126:127], v[112:113], v[172:173] op_sel_hi:[1,0,1]
	v_lshl_add_u32 v3, v96, 7, v0
	global_load_dwordx4 v[40:43], v3, s[40:41]
	s_waitcnt vmcnt(23)
; #define FP8_LO(w) __builtin_amdgcn_cvt_pk_f32_fp8((int)(w), false)
; #define FP8_HI(w) __builtin_amdgcn_cvt_pk_f32_fp8((int)(w), true)
; DI void axpy16h(float (&acc)[16], float g, const u32x4 w) {
;     const f32x2 a0 = FP8_LO(w.x), a1 = FP8_HI(w.x), a2 = FP8_LO(w.y), a3 = FP8_HI(w.y), a4 = FP8_LO(w.z), a5 = FP8_HI(w.z), a6 = FP8_LO(w.w), a7 = FP8_HI(w.w);
;     acc[0] += g * a0.x; acc[1] += g * a0.y; acc[2] += g * a1.x; acc[3] += g * a1.y; acc[4] += g * a2.x; acc[5] += g * a2.y; acc[6] += g * a3.x; acc[7] += g * a3.y;
;     acc[8] += g * a4.x; acc[9] += g * a4.y; acc[10] += g * a5.x; acc[11] += g * a5.y; acc[12] += g * a6.x; acc[13] += g * a6.y; acc[14] += g * a7.x; acc[15] += g * a7.y;
; }
; DI void phase_peer_v(const Args& a, int layer, int ci) {
;     ...
;             for (int g8 = 0; g8 < 16; ++g8) {
;                 u32x4 nxt[8];
;                 if (g8 < 15) gat_loadh(V, idA, idB, g8 + 1, lo16, nxt); else gat_loadh(V, idAn, idBn, 0, lo16, nxt);
;                 const float ghs = g8 < 8 ? ghA : ghB;
; #pragma unroll
;                 for (int j = 0; j < 8; ++j) { const float gv = __shfl(ghs, (g8 & 7) * 8 + j); axpy16h(acc, gv, cur[j]); if (j & 1) __builtin_amdgcn_sched_barrier(0); }
; #pragma unroll
;                 for (int j = 0; j < 8; ++j) cur[j] = nxt[j];
	v_cvt_pk_f32_fp8_e32 v[120:121], v44
	v_cvt_pk_f32_fp8_sdwa v[122:123], v44 src0_sel:WORD_1
	v_cvt_pk_f32_fp8_e32 v[124:125], v45
	v_cvt_pk_f32_fp8_sdwa v[126:127], v45 src0_sel:WORD_1
	v_pk_fma_f32 v[156:157], v[120:121], v[112:113], v[156:157] op_sel:[0,1,0] op_sel_hi:[1,1,1]
	v_pk_fma_f32 v[158:159], v[122:123], v[112:113], v[158:159] op_sel:[0,1,0] op_sel_hi:[1,1,1]
	v_pk_fma_f32 v[160:161], v[124:125], v[112:113], v[160:161] op_sel:[0,1,0] op_sel_hi:[1,1,1]
	v_pk_fma_f32 v[162:163], v[126:127], v[112:113], v[162:163] op_sel:[0,1,0] op_sel_hi:[1,1,1]
	v_cvt_pk_f32_fp8_e32 v[120:121], v46
	v_cvt_pk_f32_fp8_sdwa v[122:123], v46 src0_sel:WORD_1
	v_cvt_pk_f32_fp8_e32 v[124:125], v47
	v_cvt_pk_f32_fp8_sdwa v[126:127], v47 src0_sel:WORD_1
	v_pk_fma_f32 v[166:167], v[120:121], v[112:113], v[166:167] op_sel:[0,1,0] op_sel_hi:[1,1,1]
	v_pk_fma_f32 v[168:169], v[122:123], v[112:113], v[168:169] op_sel:[0,1,0] op_sel_hi:[1,1,1]
	v_pk_fma_f32 v[170:171], v[124:125], v[112:113], v[170:171] op_sel:[0,1,0] op_sel_hi:[1,1,1]
	v_pk_fma_f32 v[172:173], v[126:127], v[112:113], v[172:173] op_sel:[0,1,0] op_sel_hi:[1,1,1]
	v_lshl_add_u32 v4, v97, 7, v0
	global_load_dwordx4 v[44:47], v4, s[40:41]
	s_waitcnt vmcnt(23)
	v_cvt_pk_f32_fp8_e32 v[120:121], v48
	v_cvt_pk_f32_fp8_sdwa v[122:123], v48 src0_sel:WORD_1
	v_cvt_pk_f32_fp8_e32 v[124:125], v49
	v_cvt_pk_f32_fp8_sdwa v[126:127], v49 src0_sel:WORD_1
	v_pk_fma_f32 v[156:157], v[120:121], v[114:115], v[156:157] op_sel_hi:[1,0,1]
	v_pk_fma_f32 v[158:159], v[122:123], v[114:115], v[158:159] op_sel_hi:[1,0,1]
	v_pk_fma_f32 v[160:161], v[124:125], v[114:115], v[160:161] op_sel_hi:[1,0,1]
	v_pk_fma_f32 v[162:163], v[126:127], v[114:115], v[162:163] op_sel_hi:[1,0,1]
	v_cvt_pk_f32_fp8_e32 v[120:121], v50
	v_cvt_pk_f32_fp8_sdwa v[122:123], v50 src0_sel:WORD_1
	v_cvt_pk_f32_fp8_e32 v[124:125], v51
	v_cvt_pk_f32_fp8_sdwa v[126:127], v51 src0_sel:WORD_1
	v_pk_fma_f32 v[166:167], v[120:121], v[114:115], v[166:167] op_sel_hi:[1,0,1]
	v_pk_fma_f32 v[168:169], v[122:123], v[114:115], v[168:169] op_sel_hi:[1,0,1]
	v_pk_fma_f32 v[170:171], v[124:125], v[114:115], v[170:171] op_sel_hi:[1,0,1]
	v_pk_fma_f32 v[172:173], v[126:127], v[114:115], v[172:173] op_sel_hi:[1,0,1]
	v_lshl_add_u32 v3, v98, 7, v0
	global_load_dwordx4 v[48:51], v3, s[40:41]
	s_waitcnt vmcnt(23)
	v_cvt_pk_f32_fp8_e32 v[120:121], v52
	v_cvt_pk_f32_fp8_sdwa v[122:123], v52 src0_sel:WORD_1
	v_cvt_pk_f32_fp8_e32 v[124:125], v53
	v_cvt_pk_f32_fp8_sdwa v[126:127], v53 src0_sel:WORD_1
	v_pk_fma_f32 v[156:157], v[120:121], v[114:115], v[156:157] op_sel:[0,1,0] op_sel_hi:[1,1,1]
	v_pk_fma_f32 v[158:159], v[122:123], v[114:115], v[158:159] op_sel:[0,1,0] op_sel_hi:[1,1,1]
	v_pk_fma_f32 v[160:161], v[124:125], v[114:115], v[160:161] op_sel:[0,1,0] op_sel_hi:[1,1,1]
	v_pk_fma_f32 v[162:163], v[126:127], v[114:115], v[162:163] op_sel:[0,1,0] op_sel_hi:[1,1,1]
	v_cvt_pk_f32_fp8_e32 v[120:121], v54
	v_cvt_pk_f32_fp8_sdwa v[122:123], v54 src0_sel:WORD_1
	v_cvt_pk_f32_fp8_e32 v[124:125], v55
	v_cvt_pk_f32_fp8_sdwa v[126:127], v55 src0_sel:WORD_1
	v_pk_fma_f32 v[166:167], v[120:121], v[114:115], v[166:167] op_sel:[0,1,0] op_sel_hi:[1,1,1]
	v_pk_fma_f32 v[168:169], v[122:123], v[114:115], v[168:169] op_sel:[0,1,0] op_sel_hi:[1,1,1]
	v_pk_fma_f32 v[170:171], v[124:125], v[114:115], v[170:171] op_sel:[0,1,0] op_sel_hi:[1,1,1]
	v_pk_fma_f32 v[172:173], v[126:127], v[114:115], v[172:173] op_sel:[0,1,0] op_sel_hi:[1,1,1]
	v_lshl_add_u32 v4, v99, 7, v0
	global_load_dwordx4 v[52:55], v4, s[40:41]
	s_waitcnt vmcnt(23)
	v_cvt_pk_f32_fp8_e32 v[120:121], v56
	v_cvt_pk_f32_fp8_sdwa v[122:123], v56 src0_sel:WORD_1
	v_cvt_pk_f32_fp8_e32 v[124:125], v57
	v_cvt_pk_f32_fp8_sdwa v[126:127], v57 src0_sel:WORD_1
	v_pk_fma_f32 v[156:157], v[120:121], v[116:117], v[156:157] op_sel_hi:[1,0,1]
	v_pk_fma_f32 v[158:159], v[122:123], v[116:117], v[158:159] op_sel_hi:[1,0,1]
	v_pk_fma_f32 v[160:161], v[124:125], v[116:117], v[160:161] op_sel_hi:[1,0,1]
	v_pk_fma_f32 v[162:163], v[126:127], v[116:117], v[162:163] op_sel_hi:[1,0,1]
	v_cvt_pk_f32_fp8_e32 v[120:121], v58
	v_cvt_pk_f32_fp8_sdwa v[122:123], v58 src0_sel:WORD_1
	v_cvt_pk_f32_fp8_e32 v[124:125], v59
	v_cvt_pk_f32_fp8_sdwa v[126:127], v59 src0_sel:WORD_1
	v_pk_fma_f32 v[166:167], v[120:121], v[116:117], v[166:167] op_sel_hi:[1,0,1]
	v_pk_fma_f32 v[168:169], v[122:123], v[116:117], v[168:169] op_sel_hi:[1,0,1]
	v_pk_fma_f32 v[170:171], v[124:125], v[116:117], v[170:171] op_sel_hi:[1,0,1]
	v_pk_fma_f32 v[172:173], v[126:127], v[116:117], v[172:173] op_sel_hi:[1,0,1]
	v_lshl_add_u32 v3, v100, 7, v0
	global_load_dwordx4 v[56:59], v3, s[40:41]
	s_waitcnt vmcnt(23)
	v_cvt_pk_f32_fp8_e32 v[120:121], v60
	v_cvt_pk_f32_fp8_sdwa v[122:123], v60 src0_sel:WORD_1
	v_cvt_pk_f32_fp8_e32 v[124:125], v61
	v_cvt_pk_f32_fp8_sdwa v[126:127], v61 src0_sel:WORD_1
	v_pk_fma_f32 v[156:157], v[120:121], v[116:117], v[156:157] op_sel:[0,1,0] op_sel_hi:[1,1,1]
	v_pk_fma_f32 v[158:159], v[122:123], v[116:117], v[158:159] op_sel:[0,1,0] op_sel_hi:[1,1,1]
	v_pk_fma_f32 v[160:161], v[124:125], v[116:117], v[160:161] op_sel:[0,1,0] op_sel_hi:[1,1,1]
	v_pk_fma_f32 v[162:163], v[126:127], v[116:117], v[162:163] op_sel:[0,1,0] op_sel_hi:[1,1,1]
	v_cvt_pk_f32_fp8_e32 v[120:121], v62
	v_cvt_pk_f32_fp8_sdwa v[122:123], v62 src0_sel:WORD_1
	v_cvt_pk_f32_fp8_e32 v[124:125], v63
	v_cvt_pk_f32_fp8_sdwa v[126:127], v63 src0_sel:WORD_1
	v_pk_fma_f32 v[166:167], v[120:121], v[116:117], v[166:167] op_sel:[0,1,0] op_sel_hi:[1,1,1]
	v_pk_fma_f32 v[168:169], v[122:123], v[116:117], v[168:169] op_sel:[0,1,0] op_sel_hi:[1,1,1]
	v_pk_fma_f32 v[170:171], v[124:125], v[116:117], v[170:171] op_sel:[0,1,0] op_sel_hi:[1,1,1]
	v_pk_fma_f32 v[172:173], v[126:127], v[116:117], v[172:173] op_sel:[0,1,0] op_sel_hi:[1,1,1]
	v_lshl_add_u32 v4, v101, 7, v0
	global_load_dwordx4 v[60:63], v4, s[40:41]
	s_waitcnt vmcnt(23)
; DI void phase_peer_v(const Args& a, int layer, int ci) {
;     ...
;                 for (int j = 0; j < 8; ++j) { const float gv = __shfl(ghs, (g8 & 7) * 8 + j); axpy16h(acc, gv, cur[j]); if (j & 1) __builtin_amdgcn_sched_barrier(0); }
; #pragma unroll
;                 for (int j = 0; j < 8; ++j) cur[j] = nxt[j];
;             }
;             idA = idAn; idB = idBn;
;             float* hrow = a.out + (size_t)m * D;
;             const int col = ci * 1024 + lane * 16;
;             float ss = 0.f;
; #pragma unroll
;             for (int q = 0; q < 4; ++q) { const f32x4 h = *(const f32x4*)(hrow + col + 4 * q);
;                 acc[4 * q] += h.x; acc[4 * q + 1] += h.y; acc[4 * q + 2] += h.z; acc[4 * q + 3] += h.w; }
;             if (ci == 0) {
; #pragma unroll
;                 for (int q = 0; q < 4; ++q) { f32x4 h; h.x = acc[4 * q]; h.y = acc[4 * q + 1]; h.z = acc[4 * q + 2]; h.w = acc[4 * q + 3]; *(f32x4*)(hrow + col + 4 * q) = h; }
	v_cvt_pk_f32_fp8_e32 v[120:121], v64
	v_cvt_pk_f32_fp8_sdwa v[122:123], v64 src0_sel:WORD_1
	v_cvt_pk_f32_fp8_e32 v[124:125], v65
	v_cvt_pk_f32_fp8_sdwa v[126:127], v65 src0_sel:WORD_1
	v_pk_fma_f32 v[156:157], v[120:121], v[118:119], v[156:157] op_sel_hi:[1,0,1]
	v_pk_fma_f32 v[158:159], v[122:123], v[118:119], v[158:159] op_sel_hi:[1,0,1]
	v_pk_fma_f32 v[160:161], v[124:125], v[118:119], v[160:161] op_sel_hi:[1,0,1]
	v_pk_fma_f32 v[162:163], v[126:127], v[118:119], v[162:163] op_sel_hi:[1,0,1]
	v_cvt_pk_f32_fp8_e32 v[120:121], v66
	v_cvt_pk_f32_fp8_sdwa v[122:123], v66 src0_sel:WORD_1
	v_cvt_pk_f32_fp8_e32 v[124:125], v67
	v_cvt_pk_f32_fp8_sdwa v[126:127], v67 src0_sel:WORD_1
	v_pk_fma_f32 v[166:167], v[120:121], v[118:119], v[166:167] op_sel_hi:[1,0,1]
	v_pk_fma_f32 v[168:169], v[122:123], v[118:119], v[168:169] op_sel_hi:[1,0,1]
	v_pk_fma_f32 v[170:171], v[124:125], v[118:119], v[170:171] op_sel_hi:[1,0,1]
	v_pk_fma_f32 v[172:173], v[126:127], v[118:119], v[172:173] op_sel_hi:[1,0,1]
	v_lshl_add_u32 v3, v102, 7, v0
	global_load_dwordx4 v[64:67], v3, s[40:41]
	s_waitcnt vmcnt(23)
	v_cvt_pk_f32_fp8_e32 v[120:121], v68
	v_cvt_pk_f32_fp8_sdwa v[122:123], v68 src0_sel:WORD_1
	v_cvt_pk_f32_fp8_e32 v[124:125], v69
	v_cvt_pk_f32_fp8_sdwa v[126:127], v69 src0_sel:WORD_1
	v_pk_fma_f32 v[156:157], v[120:121], v[118:119], v[156:157] op_sel:[0,1,0] op_sel_hi:[1,1,1]
	v_pk_fma_f32 v[158:159], v[122:123], v[118:119], v[158:159] op_sel:[0,1,0] op_sel_hi:[1,1,1]
	v_pk_fma_f32 v[160:161], v[124:125], v[118:119], v[160:161] op_sel:[0,1,0] op_sel_hi:[1,1,1]
	v_pk_fma_f32 v[162:163], v[126:127], v[118:119], v[162:163] op_sel:[0,1,0] op_sel_hi:[1,1,1]
	v_cvt_pk_f32_fp8_e32 v[120:121], v70
	v_cvt_pk_f32_fp8_sdwa v[122:123], v70 src0_sel:WORD_1
	v_cvt_pk_f32_fp8_e32 v[124:125], v71
	v_cvt_pk_f32_fp8_sdwa v[126:127], v71 src0_sel:WORD_1
	v_pk_fma_f32 v[166:167], v[120:121], v[118:119], v[166:167] op_sel:[0,1,0] op_sel_hi:[1,1,1]
	v_pk_fma_f32 v[168:169], v[122:123], v[118:119], v[168:169] op_sel:[0,1,0] op_sel_hi:[1,1,1]
	v_pk_fma_f32 v[170:171], v[124:125], v[118:119], v[170:171] op_sel:[0,1,0] op_sel_hi:[1,1,1]
	v_pk_fma_f32 v[172:173], v[126:127], v[118:119], v[172:173] op_sel:[0,1,0] op_sel_hi:[1,1,1]
	v_lshl_add_u32 v4, v103, 7, v0
	global_load_dwordx4 v[68:71], v4, s[40:41]
	s_cmp_eq_u32 s47, 7
	s_cbranch_scc0 .Lpv_b0_nost
	v_pk_add_f32 v[216:217], v[216:217], v[156:157]
	v_pk_add_f32 v[218:219], v[218:219], v[158:159]
	v_pk_add_f32 v[220:221], v[220:221], v[160:161]
	v_pk_add_f32 v[222:223], v[222:223], v[162:163]
	v_pk_add_f32 v[224:225], v[224:225], v[166:167]
	v_pk_add_f32 v[226:227], v[226:227], v[168:169]
	v_pk_add_f32 v[174:175], v[174:175], v[170:171]
	v_pk_add_f32 v[176:177], v[176:177], v[172:173]
	v_mov_b64_e32 v[156:157], 0
	v_mov_b64_e32 v[158:159], 0
	v_mov_b64_e32 v[160:161], 0
	v_mov_b64_e32 v[162:163], 0
	v_mov_b64_e32 v[166:167], 0
	v_mov_b64_e32 v[168:169], 0
	v_mov_b64_e32 v[170:171], 0
	v_mov_b64_e32 v[172:173], 0
	global_store_dwordx4 v2, v[216:219], s[42:43]
	global_store_dwordx4 v2, v[220:223], s[42:43] offset:16
	global_store_dwordx4 v2, v[224:227], s[42:43] offset:32
	global_store_dwordx4 v2, v[174:177], s[42:43] offset:48
.Lpv_b0_nost:
	s_add_u32 s0, s0, 1
	s_add_u32 s44, s0, 1
	s_min_u32 s44, s44, 0xff
	s_bfe_u32 s45, s44, 0x40003
	s_lshl_b32 s45, s45, 20
	s_and_b32 s46, s44, 7
	s_lshl_b32 s46, s46, 6
	s_add_u32 s45, s45, s46
	s_add_u32 s45, s45, s8
	s_add_u32 s45, s45, 0x7000000
	s_add_u32 s24, s98, s45
	s_addc_u32 s25, s99, 0
	s_lshr_b32 s46, s44, 7
	s_add_u32 s46, s46, s9
	s_lshl_b32 s46, s46, 21
	s_add_u32 s40, s16, s46
	s_addc_u32 s41, s17, 0
	s_add_u32 s44, s0, 2
	s_min_u32 s44, s44, 0xff
	s_bfe_u32 s45, s44, 0x40003
	s_lshl_b32 s45, s45, 20
	s_and_b32 s46, s44, 7
	s_lshl_b32 s46, s46, 6
	s_add_u32 s45, s45, s46
	s_add_u32 s45, s45, s8
	s_add_u32 s45, s45, 0x6000000
	s_add_u32 s22, s98, s45
	s_addc_u32 s23, s99, 0
	s_and_b32 s47, s0, 7
	s_cmp_eq_u32 s47, 7
	s_cbranch_scc0 .Lpv_b1_noout
	s_bfe_u32 s45, s0, 0x40003
	s_lshl_b32 s45, s45, 24
	s_lshl_b32 s46, s8, 4
	s_add_u32 s45, s45, s46
	s_lshr_b32 s46, s0, 7
	s_add_u32 s46, s46, s9
	s_lshl_b32 s46, s46, 9
	s_add_u32 s45, s45, s46
	s_add_u32 s42, s96, s45
	s_addc_u32 s43, s97, 0
	global_load_dwordx4 v[216:219], v2, s[42:43]
	global_load_dwordx4 v[220:223], v2, s[42:43] offset:16
	global_load_dwordx4 v[224:227], v2, s[42:43] offset:32
	global_load_dwordx4 v[174:177], v2, s[42:43] offset:48
; #define FP8_LO(w) __builtin_amdgcn_cvt_pk_f32_fp8((int)(w), false)
; #define FP8_HI(w) __builtin_amdgcn_cvt_pk_f32_fp8((int)(w), true)
; DI void axpy16h(float (&acc)[16], float g, const u32x4 w) {
;     const f32x2 a0 = FP8_LO(w.x), a1 = FP8_HI(w.x), a2 = FP8_LO(w.y), a3 = FP8_HI(w.y), a4 = FP8_LO(w.z), a5 = FP8_HI(w.z), a6 = FP8_LO(w.w), a7 = FP8_HI(w.w);
;     acc[0] += g * a0.x; acc[1] += g * a0.y; acc[2] += g * a1.x; acc[3] += g * a1.y; acc[4] += g * a2.x; acc[5] += g * a2.y; acc[6] += g * a3.x; acc[7] += g * a3.y;
;     acc[8] += g * a4.x; acc[9] += g * a4.y; acc[10] += g * a5.x; acc[11] += g * a5.y; acc[12] += g * a6.x; acc[13] += g * a6.y; acc[14] += g * a7.x; acc[15] += g * a7.y;
; }
; DI void phase_peer_v(const Args& a, int layer, int ci) {
;     ...
;             for (int g8 = 0; g8 < 16; ++g8) {
;                 u32x4 nxt[8];
;                 if (g8 < 15) gat_loadh(V, idA, idB, g8 + 1, lo16, nxt); else gat_loadh(V, idAn, idBn, 0, lo16, nxt);
;                 const float ghs = g8 < 8 ? ghA : ghB;
; #pragma unroll
;                 for (int j = 0; j < 8; ++j) { const float gv = __shfl(ghs, (g8 & 7) * 8 + j); axpy16h(acc, gv, cur[j]); if (j & 1) __builtin_amdgcn_sched_barrier(0); }
; #pragma unroll
;                 for (int j = 0; j < 8; ++j) cur[j] = nxt[j];
.Lpv_b1_noout:
	global_load_dwordx4 v[104:107], v1, s[24:25]
	global_load_dwordx4 v[108:111], v1, s[24:25] offset:16
	global_load_dwordx4 v[112:115], v1, s[24:25] offset:32
	global_load_dwordx4 v[116:119], v1, s[24:25] offset:48
	global_load_dwordx4 v[88:91], v1, s[22:23]
	global_load_dwordx4 v[92:95], v1, s[22:23] offset:16
	global_load_dwordx4 v[96:99], v1, s[22:23] offset:32
	global_load_dwordx4 v[100:103], v1, s[22:23] offset:48
	s_waitcnt vmcnt(23)
	v_cvt_pk_f32_fp8_e32 v[120:121], v8
	v_cvt_pk_f32_fp8_sdwa v[122:123], v8 src0_sel:WORD_1
	v_cvt_pk_f32_fp8_e32 v[124:125], v9
	v_cvt_pk_f32_fp8_sdwa v[126:127], v9 src0_sel:WORD_1
	v_pk_fma_f32 v[156:157], v[120:121], v[140:141], v[156:157] op_sel_hi:[1,0,1]
	v_pk_fma_f32 v[158:159], v[122:123], v[140:141], v[158:159] op_sel_hi:[1,0,1]
	v_pk_fma_f32 v[160:161], v[124:125], v[140:141], v[160:161] op_sel_hi:[1,0,1]
	v_pk_fma_f32 v[162:163], v[126:127], v[140:141], v[162:163] op_sel_hi:[1,0,1]
	v_cvt_pk_f32_fp8_e32 v[120:121], v10
	v_cvt_pk_f32_fp8_sdwa v[122:123], v10 src0_sel:WORD_1
	v_cvt_pk_f32_fp8_e32 v[124:125], v11
	v_cvt_pk_f32_fp8_sdwa v[126:127], v11 src0_sel:WORD_1
	v_pk_fma_f32 v[166:167], v[120:121], v[140:141], v[166:167] op_sel_hi:[1,0,1]
	v_pk_fma_f32 v[168:169], v[122:123], v[140:141], v[168:169] op_sel_hi:[1,0,1]
	v_pk_fma_f32 v[170:171], v[124:125], v[140:141], v[170:171] op_sel_hi:[1,0,1]
	v_pk_fma_f32 v[172:173], v[126:127], v[140:141], v[172:173] op_sel_hi:[1,0,1]
	v_lshl_add_u32 v3, v72, 7, v0
	global_load_dwordx4 v[8:11], v3, s[40:41]
	s_waitcnt vmcnt(23)
	v_cvt_pk_f32_fp8_e32 v[120:121], v12
	v_cvt_pk_f32_fp8_sdwa v[122:123], v12 src0_sel:WORD_1
	v_cvt_pk_f32_fp8_e32 v[124:125], v13
	v_cvt_pk_f32_fp8_sdwa v[126:127], v13 src0_sel:WORD_1
	v_pk_fma_f32 v[156:157], v[120:121], v[140:141], v[156:157] op_sel:[0,1,0] op_sel_hi:[1,1,1]
	v_pk_fma_f32 v[158:159], v[122:123], v[140:141], v[158:159] op_sel:[0,1,0] op_sel_hi:[1,1,1]
	v_pk_fma_f32 v[160:161], v[124:125], v[140:141], v[160:161] op_sel:[0,1,0] op_sel_hi:[1,1,1]
	v_pk_fma_f32 v[162:163], v[126:127], v[140:141], v[162:163] op_sel:[0,1,0] op_sel_hi:[1,1,1]
	v_cvt_pk_f32_fp8_e32 v[120:121], v14
	v_cvt_pk_f32_fp8_sdwa v[122:123], v14 src0_sel:WORD_1
	v_cvt_pk_f32_fp8_e32 v[124:125], v15
	v_cvt_pk_f32_fp8_sdwa v[126:127], v15 src0_sel:WORD_1
	v_pk_fma_f32 v[166:167], v[120:121], v[140:141], v[166:167] op_sel:[0,1,0] op_sel_hi:[1,1,1]
	v_pk_fma_f32 v[168:169], v[122:123], v[140:141], v[168:169] op_sel:[0,1,0] op_sel_hi:[1,1,1]
	v_pk_fma_f32 v[170:171], v[124:125], v[140:141], v[170:171] op_sel:[0,1,0] op_sel_hi:[1,1,1]
	v_pk_fma_f32 v[172:173], v[126:127], v[140:141], v[172:173] op_sel:[0,1,0] op_sel_hi:[1,1,1]
	v_lshl_add_u32 v4, v73, 7, v0
	global_load_dwordx4 v[12:15], v4, s[40:41]
	s_waitcnt vmcnt(23)
	v_cvt_pk_f32_fp8_e32 v[120:121], v16
	v_cvt_pk_f32_fp8_sdwa v[122:123], v16 src0_sel:WORD_1
	v_cvt_pk_f32_fp8_e32 v[124:125], v17
	v_cvt_pk_f32_fp8_sdwa v[126:127], v17 src0_sel:WORD_1
	v_pk_fma_f32 v[156:157], v[120:121], v[142:143], v[156:157] op_sel_hi:[1,0,1]
	v_pk_fma_f32 v[158:159], v[122:123], v[142:143], v[158:159] op_sel_hi:[1,0,1]
	v_pk_fma_f32 v[160:161], v[124:125], v[142:143], v[160:161] op_sel_hi:[1,0,1]
	v_pk_fma_f32 v[162:163], v[126:127], v[142:143], v[162:163] op_sel_hi:[1,0,1]
	v_cvt_pk_f32_fp8_e32 v[120:121], v18
	v_cvt_pk_f32_fp8_sdwa v[122:123], v18 src0_sel:WORD_1
	v_cvt_pk_f32_fp8_e32 v[124:125], v19
	v_cvt_pk_f32_fp8_sdwa v[126:127], v19 src0_sel:WORD_1
	v_pk_fma_f32 v[166:167], v[120:121], v[142:143], v[166:167] op_sel_hi:[1,0,1]
	v_pk_fma_f32 v[168:169], v[122:123], v[142:143], v[168:169] op_sel_hi:[1,0,1]
	v_pk_fma_f32 v[170:171], v[124:125], v[142:143], v[170:171] op_sel_hi:[1,0,1]
	v_pk_fma_f32 v[172:173], v[126:127], v[142:143], v[172:173] op_sel_hi:[1,0,1]
	v_lshl_add_u32 v3, v74, 7, v0
	global_load_dwordx4 v[16:19], v3, s[40:41]
	s_waitcnt vmcnt(23)
	v_cvt_pk_f32_fp8_e32 v[120:121], v20
	v_cvt_pk_f32_fp8_sdwa v[122:123], v20 src0_sel:WORD_1
	v_cvt_pk_f32_fp8_e32 v[124:125], v21
	v_cvt_pk_f32_fp8_sdwa v[126:127], v21 src0_sel:WORD_1
	v_pk_fma_f32 v[156:157], v[120:121], v[142:143], v[156:157] op_sel:[0,1,0] op_sel_hi:[1,1,1]
	v_pk_fma_f32 v[158:159], v[122:123], v[142:143], v[158:159] op_sel:[0,1,0] op_sel_hi:[1,1,1]
	v_pk_fma_f32 v[160:161], v[124:125], v[142:143], v[160:161] op_sel:[0,1,0] op_sel_hi:[1,1,1]
	v_pk_fma_f32 v[162:163], v[126:127], v[142:143], v[162:163] op_sel:[0,1,0] op_sel_hi:[1,1,1]
	v_cvt_pk_f32_fp8_e32 v[120:121], v22
	v_cvt_pk_f32_fp8_sdwa v[122:123], v22 src0_sel:WORD_1
	v_cvt_pk_f32_fp8_e32 v[124:125], v23
	v_cvt_pk_f32_fp8_sdwa v[126:127], v23 src0_sel:WORD_1
	v_pk_fma_f32 v[166:167], v[120:121], v[142:143], v[166:167] op_sel:[0,1,0] op_sel_hi:[1,1,1]
	v_pk_fma_f32 v[168:169], v[122:123], v[142:143], v[168:169] op_sel:[0,1,0] op_sel_hi:[1,1,1]
	v_pk_fma_f32 v[170:171], v[124:125], v[142:143], v[170:171] op_sel:[0,1,0] op_sel_hi:[1,1,1]
	v_pk_fma_f32 v[172:173], v[126:127], v[142:143], v[172:173] op_sel:[0,1,0] op_sel_hi:[1,1,1]
	v_lshl_add_u32 v4, v75, 7, v0
	global_load_dwordx4 v[20:23], v4, s[40:41]
	s_waitcnt vmcnt(23)
; #define FP8_LO(w) __builtin_amdgcn_cvt_pk_f32_fp8((int)(w), false)
; #define FP8_HI(w) __builtin_amdgcn_cvt_pk_f32_fp8((int)(w), true)
; DI void axpy16h(float (&acc)[16], float g, const u32x4 w) {
;     const f32x2 a0 = FP8_LO(w.x), a1 = FP8_HI(w.x), a2 = FP8_LO(w.y), a3 = FP8_HI(w.y), a4 = FP8_LO(w.z), a5 = FP8_HI(w.z), a6 = FP8_LO(w.w), a7 = FP8_HI(w.w);
;     acc[0] += g * a0.x; acc[1] += g * a0.y; acc[2] += g * a1.x; acc[3] += g * a1.y; acc[4] += g * a2.x; acc[5] += g * a2.y; acc[6] += g * a3.x; acc[7] += g * a3.y;
;     acc[8] += g * a4.x; acc[9] += g * a4.y; acc[10] += g * a5.x; acc[11] += g * a5.y; acc[12] += g * a6.x; acc[13] += g * a6.y; acc[14] += g * a7.x; acc[15] += g * a7.y;
; }
; DI void phase_peer_v(const Args& a, int layer, int ci) {
;     ...
;             for (int g8 = 0; g8 < 16; ++g8) {
;                 u32x4 nxt[8];
;                 if (g8 < 15) gat_loadh(V, idA, idB, g8 + 1, lo16, nxt); else gat_loadh(V, idAn, idBn, 0, lo16, nxt);
;                 const float ghs = g8 < 8 ? ghA : ghB;
; #pragma unroll
;                 for (int j = 0; j < 8; ++j) { const float gv = __shfl(ghs, (g8 & 7) * 8 + j); axpy16h(acc, gv, cur[j]); if (j & 1) __builtin_amdgcn_sched_barrier(0); }
; #pragma unroll
;                 for (int j = 0; j < 8; ++j) cur[j] = nxt[j];
	v_cvt_pk_f32_fp8_e32 v[120:121], v24
	v_cvt_pk_f32_fp8_sdwa v[122:123], v24 src0_sel:WORD_1
	v_cvt_pk_f32_fp8_e32 v[124:125], v25
	v_cvt_pk_f32_fp8_sdwa v[126:127], v25 src0_sel:WORD_1
	v_pk_fma_f32 v[156:157], v[120:121], v[144:145], v[156:157] op_sel_hi:[1,0,1]
	v_pk_fma_f32 v[158:159], v[122:123], v[144:145], v[158:159] op_sel_hi:[1,0,1]
	v_pk_fma_f32 v[160:161], v[124:125], v[144:145], v[160:161] op_sel_hi:[1,0,1]
	v_pk_fma_f32 v[162:163], v[126:127], v[144:145], v[162:163] op_sel_hi:[1,0,1]
	v_cvt_pk_f32_fp8_e32 v[120:121], v26
	v_cvt_pk_f32_fp8_sdwa v[122:123], v26 src0_sel:WORD_1
	v_cvt_pk_f32_fp8_e32 v[124:125], v27
	v_cvt_pk_f32_fp8_sdwa v[126:127], v27 src0_sel:WORD_1
	v_pk_fma_f32 v[166:167], v[120:121], v[144:145], v[166:167] op_sel_hi:[1,0,1]
	v_pk_fma_f32 v[168:169], v[122:123], v[144:145], v[168:169] op_sel_hi:[1,0,1]
	v_pk_fma_f32 v[170:171], v[124:125], v[144:145], v[170:171] op_sel_hi:[1,0,1]
	v_pk_fma_f32 v[172:173], v[126:127], v[144:145], v[172:173] op_sel_hi:[1,0,1]
	v_lshl_add_u32 v3, v76, 7, v0
	global_load_dwordx4 v[24:27], v3, s[40:41]
	s_waitcnt vmcnt(23)
	v_cvt_pk_f32_fp8_e32 v[120:121], v28
	v_cvt_pk_f32_fp8_sdwa v[122:123], v28 src0_sel:WORD_1
	v_cvt_pk_f32_fp8_e32 v[124:125], v29
	v_cvt_pk_f32_fp8_sdwa v[126:127], v29 src0_sel:WORD_1
	v_pk_fma_f32 v[156:157], v[120:121], v[144:145], v[156:157] op_sel:[0,1,0] op_sel_hi:[1,1,1]
	v_pk_fma_f32 v[158:159], v[122:123], v[144:145], v[158:159] op_sel:[0,1,0] op_sel_hi:[1,1,1]
	v_pk_fma_f32 v[160:161], v[124:125], v[144:145], v[160:161] op_sel:[0,1,0] op_sel_hi:[1,1,1]
	v_pk_fma_f32 v[162:163], v[126:127], v[144:145], v[162:163] op_sel:[0,1,0] op_sel_hi:[1,1,1]
	v_cvt_pk_f32_fp8_e32 v[120:121], v30
	v_cvt_pk_f32_fp8_sdwa v[122:123], v30 src0_sel:WORD_1
	v_cvt_pk_f32_fp8_e32 v[124:125], v31
	v_cvt_pk_f32_fp8_sdwa v[126:127], v31 src0_sel:WORD_1
	v_pk_fma_f32 v[166:167], v[120:121], v[144:145], v[166:167] op_sel:[0,1,0] op_sel_hi:[1,1,1]
	v_pk_fma_f32 v[168:169], v[122:123], v[144:145], v[168:169] op_sel:[0,1,0] op_sel_hi:[1,1,1]
	v_pk_fma_f32 v[170:171], v[124:125], v[144:145], v[170:171] op_sel:[0,1,0] op_sel_hi:[1,1,1]
	v_pk_fma_f32 v[172:173], v[126:127], v[144:145], v[172:173] op_sel:[0,1,0] op_sel_hi:[1,1,1]
	v_lshl_add_u32 v4, v77, 7, v0
	global_load_dwordx4 v[28:31], v4, s[40:41]
	s_waitcnt vmcnt(23)
	v_cvt_pk_f32_fp8_e32 v[120:121], v32
	v_cvt_pk_f32_fp8_sdwa v[122:123], v32 src0_sel:WORD_1
	v_cvt_pk_f32_fp8_e32 v[124:125], v33
	v_cvt_pk_f32_fp8_sdwa v[126:127], v33 src0_sel:WORD_1
	v_pk_fma_f32 v[156:157], v[120:121], v[146:147], v[156:157] op_sel_hi:[1,0,1]
	v_pk_fma_f32 v[158:159], v[122:123], v[146:147], v[158:159] op_sel_hi:[1,0,1]
	v_pk_fma_f32 v[160:161], v[124:125], v[146:147], v[160:161] op_sel_hi:[1,0,1]
	v_pk_fma_f32 v[162:163], v[126:127], v[146:147], v[162:163] op_sel_hi:[1,0,1]
	v_cvt_pk_f32_fp8_e32 v[120:121], v34
	v_cvt_pk_f32_fp8_sdwa v[122:123], v34 src0_sel:WORD_1
	v_cvt_pk_f32_fp8_e32 v[124:125], v35
	v_cvt_pk_f32_fp8_sdwa v[126:127], v35 src0_sel:WORD_1
	v_pk_fma_f32 v[166:167], v[120:121], v[146:147], v[166:167] op_sel_hi:[1,0,1]
	v_pk_fma_f32 v[168:169], v[122:123], v[146:147], v[168:169] op_sel_hi:[1,0,1]
	v_pk_fma_f32 v[170:171], v[124:125], v[146:147], v[170:171] op_sel_hi:[1,0,1]
	v_pk_fma_f32 v[172:173], v[126:127], v[146:147], v[172:173] op_sel_hi:[1,0,1]
	v_lshl_add_u32 v3, v78, 7, v0
	global_load_dwordx4 v[32:35], v3, s[40:41]
	s_waitcnt vmcnt(23)
	v_cvt_pk_f32_fp8_e32 v[120:121], v36
	v_cvt_pk_f32_fp8_sdwa v[122:123], v36 src0_sel:WORD_1
	v_cvt_pk_f32_fp8_e32 v[124:125], v37
	v_cvt_pk_f32_fp8_sdwa v[126:127], v37 src0_sel:WORD_1
	v_pk_fma_f32 v[156:157], v[120:121], v[146:147], v[156:157] op_sel:[0,1,0] op_sel_hi:[1,1,1]
	v_pk_fma_f32 v[158:159], v[122:123], v[146:147], v[158:159] op_sel:[0,1,0] op_sel_hi:[1,1,1]
	v_pk_fma_f32 v[160:161], v[124:125], v[146:147], v[160:161] op_sel:[0,1,0] op_sel_hi:[1,1,1]
	v_pk_fma_f32 v[162:163], v[126:127], v[146:147], v[162:163] op_sel:[0,1,0] op_sel_hi:[1,1,1]
	v_cvt_pk_f32_fp8_e32 v[120:121], v38
	v_cvt_pk_f32_fp8_sdwa v[122:123], v38 src0_sel:WORD_1
	v_cvt_pk_f32_fp8_e32 v[124:125], v39
	v_cvt_pk_f32_fp8_sdwa v[126:127], v39 src0_sel:WORD_1
	v_pk_fma_f32 v[166:167], v[120:121], v[146:147], v[166:167] op_sel:[0,1,0] op_sel_hi:[1,1,1]
	v_pk_fma_f32 v[168:169], v[122:123], v[146:147], v[168:169] op_sel:[0,1,0] op_sel_hi:[1,1,1]
	v_pk_fma_f32 v[170:171], v[124:125], v[146:147], v[170:171] op_sel:[0,1,0] op_sel_hi:[1,1,1]
	v_pk_fma_f32 v[172:173], v[126:127], v[146:147], v[172:173] op_sel:[0,1,0] op_sel_hi:[1,1,1]
	v_lshl_add_u32 v4, v79, 7, v0
	global_load_dwordx4 v[36:39], v4, s[40:41]
	s_waitcnt vmcnt(23)
	v_cvt_pk_f32_fp8_e32 v[120:121], v40
	v_cvt_pk_f32_fp8_sdwa v[122:123], v40 src0_sel:WORD_1
	v_cvt_pk_f32_fp8_e32 v[124:125], v41
	v_cvt_pk_f32_fp8_sdwa v[126:127], v41 src0_sel:WORD_1
	v_pk_fma_f32 v[156:157], v[120:121], v[148:149], v[156:157] op_sel_hi:[1,0,1]
	v_pk_fma_f32 v[158:159], v[122:123], v[148:149], v[158:159] op_sel_hi:[1,0,1]
	v_pk_fma_f32 v[160:161], v[124:125], v[148:149], v[160:161] op_sel_hi:[1,0,1]
	v_pk_fma_f32 v[162:163], v[126:127], v[148:149], v[162:163] op_sel_hi:[1,0,1]
	v_cvt_pk_f32_fp8_e32 v[120:121], v42
	v_cvt_pk_f32_fp8_sdwa v[122:123], v42 src0_sel:WORD_1
	v_cvt_pk_f32_fp8_e32 v[124:125], v43
	v_cvt_pk_f32_fp8_sdwa v[126:127], v43 src0_sel:WORD_1
	v_pk_fma_f32 v[166:167], v[120:121], v[148:149], v[166:167] op_sel_hi:[1,0,1]
	v_pk_fma_f32 v[168:169], v[122:123], v[148:149], v[168:169] op_sel_hi:[1,0,1]
	v_pk_fma_f32 v[170:171], v[124:125], v[148:149], v[170:171] op_sel_hi:[1,0,1]
	v_pk_fma_f32 v[172:173], v[126:127], v[148:149], v[172:173] op_sel_hi:[1,0,1]
	v_lshl_add_u32 v3, v80, 7, v0
	global_load_dwordx4 v[40:43], v3, s[40:41]
	s_waitcnt vmcnt(23)
; #define FP8_LO(w) __builtin_amdgcn_cvt_pk_f32_fp8((int)(w), false)
; #define FP8_HI(w) __builtin_amdgcn_cvt_pk_f32_fp8((int)(w), true)
; DI void axpy16h(float (&acc)[16], float g, const u32x4 w) {
;     const f32x2 a0 = FP8_LO(w.x), a1 = FP8_HI(w.x), a2 = FP8_LO(w.y), a3 = FP8_HI(w.y), a4 = FP8_LO(w.z), a5 = FP8_HI(w.z), a6 = FP8_LO(w.w), a7 = FP8_HI(w.w);
;     acc[0] += g * a0.x; acc[1] += g * a0.y; acc[2] += g * a1.x; acc[3] += g * a1.y; acc[4] += g * a2.x; acc[5] += g * a2.y; acc[6] += g * a3.x; acc[7] += g * a3.y;
;     acc[8] += g * a4.x; acc[9] += g * a4.y; acc[10] += g * a5.x; acc[11] += g * a5.y; acc[12] += g * a6.x; acc[13] += g * a6.y; acc[14] += g * a7.x; acc[15] += g * a7.y;
; }
; DI void phase_peer_v(const Args& a, int layer, int ci) {
;     ...
;             for (int g8 = 0; g8 < 16; ++g8) {
;                 u32x4 nxt[8];
;                 if (g8 < 15) gat_loadh(V, idA, idB, g8 + 1, lo16, nxt); else gat_loadh(V, idAn, idBn, 0, lo16, nxt);
;                 const float ghs = g8 < 8 ? ghA : ghB;
; #pragma unroll
;                 for (int j = 0; j < 8; ++j) { const float gv = __shfl(ghs, (g8 & 7) * 8 + j); axpy16h(acc, gv, cur[j]); if (j & 1) __builtin_amdgcn_sched_barrier(0); }
; #pragma unroll
;                 for (int j = 0; j < 8; ++j) cur[j] = nxt[j];
	v_cvt_pk_f32_fp8_e32 v[120:121], v44
	v_cvt_pk_f32_fp8_sdwa v[122:123], v44 src0_sel:WORD_1
	v_cvt_pk_f32_fp8_e32 v[124:125], v45
	v_cvt_pk_f32_fp8_sdwa v[126:127], v45 src0_sel:WORD_1
	v_pk_fma_f32 v[156:157], v[120:121], v[148:149], v[156:157] op_sel:[0,1,0] op_sel_hi:[1,1,1]
	v_pk_fma_f32 v[158:159], v[122:123], v[148:149], v[158:159] op_sel:[0,1,0] op_sel_hi:[1,1,1]
	v_pk_fma_f32 v[160:161], v[124:125], v[148:149], v[160:161] op_sel:[0,1,0] op_sel_hi:[1,1,1]
	v_pk_fma_f32 v[162:163], v[126:127], v[148:149], v[162:163] op_sel:[0,1,0] op_sel_hi:[1,1,1]
	v_cvt_pk_f32_fp8_e32 v[120:121], v46
	v_cvt_pk_f32_fp8_sdwa v[122:123], v46 src0_sel:WORD_1
	v_cvt_pk_f32_fp8_e32 v[124:125], v47
	v_cvt_pk_f32_fp8_sdwa v[126:127], v47 src0_sel:WORD_1
	v_pk_fma_f32 v[166:167], v[120:121], v[148:149], v[166:167] op_sel:[0,1,0] op_sel_hi:[1,1,1]
	v_pk_fma_f32 v[168:169], v[122:123], v[148:149], v[168:169] op_sel:[0,1,0] op_sel_hi:[1,1,1]
	v_pk_fma_f32 v[170:171], v[124:125], v[148:149], v[170:171] op_sel:[0,1,0] op_sel_hi:[1,1,1]
	v_pk_fma_f32 v[172:173], v[126:127], v[148:149], v[172:173] op_sel:[0,1,0] op_sel_hi:[1,1,1]
	v_lshl_add_u32 v4, v81, 7, v0
	global_load_dwordx4 v[44:47], v4, s[40:41]
	s_waitcnt vmcnt(23)
	v_cvt_pk_f32_fp8_e32 v[120:121], v48
	v_cvt_pk_f32_fp8_sdwa v[122:123], v48 src0_sel:WORD_1
	v_cvt_pk_f32_fp8_e32 v[124:125], v49
	v_cvt_pk_f32_fp8_sdwa v[126:127], v49 src0_sel:WORD_1
	v_pk_fma_f32 v[156:157], v[120:121], v[150:151], v[156:157] op_sel_hi:[1,0,1]
	v_pk_fma_f32 v[158:159], v[122:123], v[150:151], v[158:159] op_sel_hi:[1,0,1]
	v_pk_fma_f32 v[160:161], v[124:125], v[150:151], v[160:161] op_sel_hi:[1,0,1]
	v_pk_fma_f32 v[162:163], v[126:127], v[150:151], v[162:163] op_sel_hi:[1,0,1]
	v_cvt_pk_f32_fp8_e32 v[120:121], v50
	v_cvt_pk_f32_fp8_sdwa v[122:123], v50 src0_sel:WORD_1
	v_cvt_pk_f32_fp8_e32 v[124:125], v51
	v_cvt_pk_f32_fp8_sdwa v[126:127], v51 src0_sel:WORD_1
	v_pk_fma_f32 v[166:167], v[120:121], v[150:151], v[166:167] op_sel_hi:[1,0,1]
	v_pk_fma_f32 v[168:169], v[122:123], v[150:151], v[168:169] op_sel_hi:[1,0,1]
	v_pk_fma_f32 v[170:171], v[124:125], v[150:151], v[170:171] op_sel_hi:[1,0,1]
	v_pk_fma_f32 v[172:173], v[126:127], v[150:151], v[172:173] op_sel_hi:[1,0,1]
	v_lshl_add_u32 v3, v82, 7, v0
	global_load_dwordx4 v[48:51], v3, s[40:41]
	s_waitcnt vmcnt(23)
	v_cvt_pk_f32_fp8_e32 v[120:121], v52
	v_cvt_pk_f32_fp8_sdwa v[122:123], v52 src0_sel:WORD_1
	v_cvt_pk_f32_fp8_e32 v[124:125], v53
	v_cvt_pk_f32_fp8_sdwa v[126:127], v53 src0_sel:WORD_1
	v_pk_fma_f32 v[156:157], v[120:121], v[150:151], v[156:157] op_sel:[0,1,0] op_sel_hi:[1,1,1]
	v_pk_fma_f32 v[158:159], v[122:123], v[150:151], v[158:159] op_sel:[0,1,0] op_sel_hi:[1,1,1]
	v_pk_fma_f32 v[160:161], v[124:125], v[150:151], v[160:161] op_sel:[0,1,0] op_sel_hi:[1,1,1]
	v_pk_fma_f32 v[162:163], v[126:127], v[150:151], v[162:163] op_sel:[0,1,0] op_sel_hi:[1,1,1]
	v_cvt_pk_f32_fp8_e32 v[120:121], v54
	v_cvt_pk_f32_fp8_sdwa v[122:123], v54 src0_sel:WORD_1
	v_cvt_pk_f32_fp8_e32 v[124:125], v55
	v_cvt_pk_f32_fp8_sdwa v[126:127], v55 src0_sel:WORD_1
	v_pk_fma_f32 v[166:167], v[120:121], v[150:151], v[166:167] op_sel:[0,1,0] op_sel_hi:[1,1,1]
	v_pk_fma_f32 v[168:169], v[122:123], v[150:151], v[168:169] op_sel:[0,1,0] op_sel_hi:[1,1,1]
	v_pk_fma_f32 v[170:171], v[124:125], v[150:151], v[170:171] op_sel:[0,1,0] op_sel_hi:[1,1,1]
	v_pk_fma_f32 v[172:173], v[126:127], v[150:151], v[172:173] op_sel:[0,1,0] op_sel_hi:[1,1,1]
	v_lshl_add_u32 v4, v83, 7, v0
	global_load_dwordx4 v[52:55], v4, s[40:41]
	s_waitcnt vmcnt(23)
	v_cvt_pk_f32_fp8_e32 v[120:121], v56
	v_cvt_pk_f32_fp8_sdwa v[122:123], v56 src0_sel:WORD_1
	v_cvt_pk_f32_fp8_e32 v[124:125], v57
	v_cvt_pk_f32_fp8_sdwa v[126:127], v57 src0_sel:WORD_1
	v_pk_fma_f32 v[156:157], v[120:121], v[152:153], v[156:157] op_sel_hi:[1,0,1]
	v_pk_fma_f32 v[158:159], v[122:123], v[152:153], v[158:159] op_sel_hi:[1,0,1]
	v_pk_fma_f32 v[160:161], v[124:125], v[152:153], v[160:161] op_sel_hi:[1,0,1]
	v_pk_fma_f32 v[162:163], v[126:127], v[152:153], v[162:163] op_sel_hi:[1,0,1]
	v_cvt_pk_f32_fp8_e32 v[120:121], v58
	v_cvt_pk_f32_fp8_sdwa v[122:123], v58 src0_sel:WORD_1
	v_cvt_pk_f32_fp8_e32 v[124:125], v59
	v_cvt_pk_f32_fp8_sdwa v[126:127], v59 src0_sel:WORD_1
	v_pk_fma_f32 v[166:167], v[120:121], v[152:153], v[166:167] op_sel_hi:[1,0,1]
	v_pk_fma_f32 v[168:169], v[122:123], v[152:153], v[168:169] op_sel_hi:[1,0,1]
	v_pk_fma_f32 v[170:171], v[124:125], v[152:153], v[170:171] op_sel_hi:[1,0,1]
	v_pk_fma_f32 v[172:173], v[126:127], v[152:153], v[172:173] op_sel_hi:[1,0,1]
	v_lshl_add_u32 v3, v84, 7, v0
	global_load_dwordx4 v[56:59], v3, s[40:41]
	s_waitcnt vmcnt(23)
; DI void phase_peer_v(const Args& a, int layer, int ci) {
;     ...
;                 for (int j = 0; j < 8; ++j) { const float gv = __shfl(ghs, (g8 & 7) * 8 + j); axpy16h(acc, gv, cur[j]); if (j & 1) __builtin_amdgcn_sched_barrier(0); }
; #pragma unroll
;                 for (int j = 0; j < 8; ++j) cur[j] = nxt[j];
;             }
;             idA = idAn; idB = idBn;
;             float* hrow = a.out + (size_t)m * D;
;             const int col = ci * 1024 + lane * 16;
;             float ss = 0.f;
; #pragma unroll
;             for (int q = 0; q < 4; ++q) { const f32x4 h = *(const f32x4*)(hrow + col + 4 * q);
;                 acc[4 * q] += h.x; acc[4 * q + 1] += h.y; acc[4 * q + 2] += h.z; acc[4 * q + 3] += h.w; }
;             if (ci == 0) {
; #pragma unroll
;                 for (int q = 0; q < 4; ++q) { f32x4 h; h.x = acc[4 * q]; h.y = acc[4 * q + 1]; h.z = acc[4 * q + 2]; h.w = acc[4 * q + 3]; *(f32x4*)(hrow + col + 4 * q) = h; }
	v_cvt_pk_f32_fp8_e32 v[120:121], v60
	v_cvt_pk_f32_fp8_sdwa v[122:123], v60 src0_sel:WORD_1
	v_cvt_pk_f32_fp8_e32 v[124:125], v61
	v_cvt_pk_f32_fp8_sdwa v[126:127], v61 src0_sel:WORD_1
	v_pk_fma_f32 v[156:157], v[120:121], v[152:153], v[156:157] op_sel:[0,1,0] op_sel_hi:[1,1,1]
	v_pk_fma_f32 v[158:159], v[122:123], v[152:153], v[158:159] op_sel:[0,1,0] op_sel_hi:[1,1,1]
	v_pk_fma_f32 v[160:161], v[124:125], v[152:153], v[160:161] op_sel:[0,1,0] op_sel_hi:[1,1,1]
	v_pk_fma_f32 v[162:163], v[126:127], v[152:153], v[162:163] op_sel:[0,1,0] op_sel_hi:[1,1,1]
	v_cvt_pk_f32_fp8_e32 v[120:121], v62
	v_cvt_pk_f32_fp8_sdwa v[122:123], v62 src0_sel:WORD_1
	v_cvt_pk_f32_fp8_e32 v[124:125], v63
	v_cvt_pk_f32_fp8_sdwa v[126:127], v63 src0_sel:WORD_1
	v_pk_fma_f32 v[166:167], v[120:121], v[152:153], v[166:167] op_sel:[0,1,0] op_sel_hi:[1,1,1]
	v_pk_fma_f32 v[168:169], v[122:123], v[152:153], v[168:169] op_sel:[0,1,0] op_sel_hi:[1,1,1]
	v_pk_fma_f32 v[170:171], v[124:125], v[152:153], v[170:171] op_sel:[0,1,0] op_sel_hi:[1,1,1]
	v_pk_fma_f32 v[172:173], v[126:127], v[152:153], v[172:173] op_sel:[0,1,0] op_sel_hi:[1,1,1]
	v_lshl_add_u32 v4, v85, 7, v0
	global_load_dwordx4 v[60:63], v4, s[40:41]
	s_waitcnt vmcnt(23)
	v_cvt_pk_f32_fp8_e32 v[120:121], v64
	v_cvt_pk_f32_fp8_sdwa v[122:123], v64 src0_sel:WORD_1
	v_cvt_pk_f32_fp8_e32 v[124:125], v65
	v_cvt_pk_f32_fp8_sdwa v[126:127], v65 src0_sel:WORD_1
	v_pk_fma_f32 v[156:157], v[120:121], v[154:155], v[156:157] op_sel_hi:[1,0,1]
	v_pk_fma_f32 v[158:159], v[122:123], v[154:155], v[158:159] op_sel_hi:[1,0,1]
	v_pk_fma_f32 v[160:161], v[124:125], v[154:155], v[160:161] op_sel_hi:[1,0,1]
	v_pk_fma_f32 v[162:163], v[126:127], v[154:155], v[162:163] op_sel_hi:[1,0,1]
	v_cvt_pk_f32_fp8_e32 v[120:121], v66
	v_cvt_pk_f32_fp8_sdwa v[122:123], v66 src0_sel:WORD_1
	v_cvt_pk_f32_fp8_e32 v[124:125], v67
	v_cvt_pk_f32_fp8_sdwa v[126:127], v67 src0_sel:WORD_1
	v_pk_fma_f32 v[166:167], v[120:121], v[154:155], v[166:167] op_sel_hi:[1,0,1]
	v_pk_fma_f32 v[168:169], v[122:123], v[154:155], v[168:169] op_sel_hi:[1,0,1]
	v_pk_fma_f32 v[170:171], v[124:125], v[154:155], v[170:171] op_sel_hi:[1,0,1]
	v_pk_fma_f32 v[172:173], v[126:127], v[154:155], v[172:173] op_sel_hi:[1,0,1]
	v_lshl_add_u32 v3, v86, 7, v0
	global_load_dwordx4 v[64:67], v3, s[40:41]
	s_waitcnt vmcnt(23)
	v_cvt_pk_f32_fp8_e32 v[120:121], v68
	v_cvt_pk_f32_fp8_sdwa v[122:123], v68 src0_sel:WORD_1
	v_cvt_pk_f32_fp8_e32 v[124:125], v69
	v_cvt_pk_f32_fp8_sdwa v[126:127], v69 src0_sel:WORD_1
	v_pk_fma_f32 v[156:157], v[120:121], v[154:155], v[156:157] op_sel:[0,1,0] op_sel_hi:[1,1,1]
	v_pk_fma_f32 v[158:159], v[122:123], v[154:155], v[158:159] op_sel:[0,1,0] op_sel_hi:[1,1,1]
	v_pk_fma_f32 v[160:161], v[124:125], v[154:155], v[160:161] op_sel:[0,1,0] op_sel_hi:[1,1,1]
	v_pk_fma_f32 v[162:163], v[126:127], v[154:155], v[162:163] op_sel:[0,1,0] op_sel_hi:[1,1,1]
	v_cvt_pk_f32_fp8_e32 v[120:121], v70
	v_cvt_pk_f32_fp8_sdwa v[122:123], v70 src0_sel:WORD_1
	v_cvt_pk_f32_fp8_e32 v[124:125], v71
	v_cvt_pk_f32_fp8_sdwa v[126:127], v71 src0_sel:WORD_1
	v_pk_fma_f32 v[166:167], v[120:121], v[154:155], v[166:167] op_sel:[0,1,0] op_sel_hi:[1,1,1]
	v_pk_fma_f32 v[168:169], v[122:123], v[154:155], v[168:169] op_sel:[0,1,0] op_sel_hi:[1,1,1]
	v_pk_fma_f32 v[170:171], v[124:125], v[154:155], v[170:171] op_sel:[0,1,0] op_sel_hi:[1,1,1]
	v_pk_fma_f32 v[172:173], v[126:127], v[154:155], v[172:173] op_sel:[0,1,0] op_sel_hi:[1,1,1]
	v_lshl_add_u32 v4, v87, 7, v0
	global_load_dwordx4 v[68:71], v4, s[40:41]
	s_cmp_eq_u32 s47, 7
	s_cbranch_scc0 .Lpv_b1_nost
	v_pk_add_f32 v[216:217], v[216:217], v[156:157]
	v_pk_add_f32 v[218:219], v[218:219], v[158:159]
	v_pk_add_f32 v[220:221], v[220:221], v[160:161]
	v_pk_add_f32 v[222:223], v[222:223], v[162:163]
	v_pk_add_f32 v[224:225], v[224:225], v[166:167]
	v_pk_add_f32 v[226:227], v[226:227], v[168:169]
	v_pk_add_f32 v[174:175], v[174:175], v[170:171]
	v_pk_add_f32 v[176:177], v[176:177], v[172:173]
	v_mov_b64_e32 v[156:157], 0
	v_mov_b64_e32 v[158:159], 0
	v_mov_b64_e32 v[160:161], 0
	v_mov_b64_e32 v[162:163], 0
	v_mov_b64_e32 v[166:167], 0
	v_mov_b64_e32 v[168:169], 0
	v_mov_b64_e32 v[170:171], 0
	v_mov_b64_e32 v[172:173], 0
	global_store_dwordx4 v2, v[216:219], s[42:43]
	global_store_dwordx4 v2, v[220:223], s[42:43] offset:16
	global_store_dwordx4 v2, v[224:227], s[42:43] offset:32
	global_store_dwordx4 v2, v[174:177], s[42:43] offset:48
.Lpv_b1_nost:
	s_add_u32 s0, s0, 1
	s_cmpk_lt_u32 s0, 0x100
	s_cbranch_scc1 .Lpv_loop
	s_waitcnt vmcnt(0)
	s_branch .LBB0_495

; __device__ __forceinline__ int opaque_tid() { int t = threadIdx.x; asm volatile("" : "+v"(t)); return t; }
; DI void phase_peer_u(const Args& a, int layer, int ci) {
;     const int tid = opaque_tid(), lane = tid & 63, wave = tid >> 6;
;     const int gw = blockIdx.x * 8 + wave, NGW = gridDim.x * 8;
;     unsigned char* ws = a.ws;
;     const bf16_t* XN = (const bf16_t*)(ws + WS_XN) + ci * 1024 + lane * 16;
;     const unsigned char* U = ws + WS_U + (size_t)layer * NEXP * D + ci * 1024;
;     const unsigned lo16 = (unsigned)lane * 16u;
;     const int* IDX = (const int*)(ws + WS_IDX);
;     float* GATE = (float*)(ws + WS_GATE);
;     float* PD = (float*)(ws + WS_PD);
;     const float* GSUM = (const float*)(ws + WS_GSUM);
;     int m = gw;
;     if (m < M) {
;         int idA = IDX[(size_t)m * 128 + lane], idB = IDX[(size_t)m * 128 + 64 + lane];
;         u32x4 xa = *(const u32x4*)(XN + (size_t)m * D), xb = *(const u32x4*)(XN + (size_t)m * D + 8);
;         u32x4 cur[8];
;         gat_loadhu(U, idA, idB, 0, lo16, cur);
; #pragma unroll 1
;         for (; m < M; m += NGW) {
;             const int mn = m + NGW < M ? m + NGW : m;
;             const int idAn = IDX[(size_t)mn * 128 + lane], idBn = IDX[(size_t)mn * 128 + 64 + lane];
;             const u32x4 xan = *(const u32x4*)(XN + (size_t)mn * D), xbn = *(const u32x4*)(XN + (size_t)mn * D + 8);
.LBB0_460:
	s_andn2_b64 vcc, exec, s[0:1]
	s_cbranch_vccnz .LBB0_495
	v_readlane_b32 s0, v255, 14
	s_cmp_eq_u32 s0, 9
	s_cbranch_scc1 .Lpuc_entry
.Lpu_entry:
	v_readlane_b32 s1, v252, 0
	v_readlane_b32 s19, v255, 12
	v_lshrrev_b32_e32 v5, 6, v185
	v_and_b32_e32 v6, 63, v185
	v_and_b32_e32 v7, 7, v6
	v_lshrrev_b32_e32 v6, 3, v6
	v_readfirstlane_b32 s44, v5
	v_lshlrev_b32_e32 v0, 4, v7
	v_lshlrev_b32_e32 v1, 9, v6
	v_lshl_or_b32 v2, v7, 4, v1
	v_lshlrev_b32_e32 v236, 12, v6
	v_lshl_or_b32 v236, v7, 5, v236
	v_and_b32_e32 v5, 1, v7
	v_cmp_ne_u32_e64 s[34:35], 0, v5
	v_and_b32_e32 v5, 2, v7
	v_cmp_ne_u32_e64 s[48:49], 0, v5
	v_and_b32_e32 v5, 4, v7
	v_cmp_ne_u32_e64 s[50:51], 0, v5
	s_lshr_b32 s45, s1, 3
	s_lshl_b32 s45, s45, 3
	s_add_u32 s45, s45, s44
	s_lshl_b32 s8, s45, 12
	s_and_b32 s9, s1, 7
	s_lshl_b32 s9, s9, 1
	s_lshl_b32 s46, s19, 25
	s_add_u32 s16, s98, 0x8000000
	s_addc_u32 s17, s99, 0
	s_add_u32 s16, s16, s46
	s_addc_u32 s17, s17, 0
	s_mov_b32 s0, 0
	s_bfe_u32 s45, s0, 0x40003
	s_lshl_b32 s45, s45, 20
	s_and_b32 s46, s0, 7
	s_lshl_b32 s46, s46, 6
	s_add_u32 s45, s45, s46
	s_add_u32 s45, s45, s8
	s_add_u32 s45, s45, 0x6000000
	s_add_u32 s22, s98, s45
	s_addc_u32 s23, s99, 0
	global_load_dwordx4 v[72:75], v1, s[22:23]
	global_load_dwordx4 v[76:79], v1, s[22:23] offset:16
	global_load_dwordx4 v[80:83], v1, s[22:23] offset:32
	global_load_dwordx4 v[84:87], v1, s[22:23] offset:48
	global_load_dwordx4 v[88:91], v1, s[22:23] offset:64
	global_load_dwordx4 v[92:95], v1, s[22:23] offset:80
	global_load_dwordx4 v[96:99], v1, s[22:23] offset:96
	global_load_dwordx4 v[100:103], v1, s[22:23] offset:112
	s_and_b32 s45, s0, 15
	s_lshl_b32 s45, s45, 23
	s_lshl_b32 s46, s8, 3
	s_add_u32 s45, s45, s46
	s_lshr_b32 s46, s0, 4
	s_add_u32 s46, s46, s9
	s_lshl_b32 s46, s46, 8
	s_add_u32 s45, s45, s46
	s_add_u32 s24, s20, s45
	s_addc_u32 s25, s21, 0
	global_load_dwordx4 v[120:123], v236, s[24:25]
	global_load_dwordx4 v[124:127], v236, s[24:25] offset:16
	s_lshr_b32 s46, s0, 7
	s_add_u32 s46, s46, s9
	s_lshl_b32 s46, s46, 21
	s_add_u32 s40, s16, s46
	s_addc_u32 s41, s17, 0
	s_waitcnt vmcnt(0)
	v_lshlrev_b32_e32 v104, 16, v120
	v_and_b32_e32 v105, 0xffff0000, v120
	v_lshlrev_b32_e32 v106, 16, v121
	v_and_b32_e32 v107, 0xffff0000, v121
	v_lshlrev_b32_e32 v108, 16, v122
	v_and_b32_e32 v109, 0xffff0000, v122
	v_lshlrev_b32_e32 v110, 16, v123
	v_and_b32_e32 v111, 0xffff0000, v123
	v_lshlrev_b32_e32 v112, 16, v124
	v_and_b32_e32 v113, 0xffff0000, v124
	v_lshlrev_b32_e32 v114, 16, v125
	v_and_b32_e32 v115, 0xffff0000, v125
	v_lshlrev_b32_e32 v116, 16, v126
	v_and_b32_e32 v117, 0xffff0000, v126
	v_lshlrev_b32_e32 v118, 16, v127
	v_and_b32_e32 v119, 0xffff0000, v127
	v_lshl_add_u32 v3, v72, 7, v0
	global_load_dwordx4 v[8:11], v3, s[40:41]
	v_lshl_add_u32 v4, v73, 7, v0
	global_load_dwordx4 v[12:15], v4, s[40:41]
	v_lshl_add_u32 v3, v74, 7, v0
	global_load_dwordx4 v[16:19], v3, s[40:41]
	v_lshl_add_u32 v4, v75, 7, v0
	global_load_dwordx4 v[20:23], v4, s[40:41]
	v_lshl_add_u32 v3, v76, 7, v0
	global_load_dwordx4 v[24:27], v3, s[40:41]
	v_lshl_add_u32 v4, v77, 7, v0
	global_load_dwordx4 v[28:31], v4, s[40:41]
	v_lshl_add_u32 v3, v78, 7, v0
	global_load_dwordx4 v[32:35], v3, s[40:41]
	v_lshl_add_u32 v4, v79, 7, v0
	global_load_dwordx4 v[36:39], v4, s[40:41]
	v_lshl_add_u32 v3, v80, 7, v0
	global_load_dwordx4 v[40:43], v3, s[40:41]
	v_lshl_add_u32 v4, v81, 7, v0
	global_load_dwordx4 v[44:47], v4, s[40:41]
	v_lshl_add_u32 v3, v82, 7, v0
	global_load_dwordx4 v[48:51], v3, s[40:41]
	v_lshl_add_u32 v4, v83, 7, v0
	global_load_dwordx4 v[52:55], v4, s[40:41]
	v_lshl_add_u32 v3, v84, 7, v0
	global_load_dwordx4 v[56:59], v3, s[40:41]
	v_lshl_add_u32 v4, v85, 7, v0
	global_load_dwordx4 v[60:63], v4, s[40:41]
	v_lshl_add_u32 v3, v86, 7, v0
	global_load_dwordx4 v[64:67], v3, s[40:41]
	v_lshl_add_u32 v4, v87, 7, v0
	global_load_dwordx4 v[68:71], v4, s[40:41]
.Lpu_loop:
	s_add_u32 s44, s0, 1
	s_min_u32 s44, s44, 0xff
	s_lshr_b32 s46, s44, 7
	s_add_u32 s46, s46, s9
	s_lshl_b32 s46, s46, 21
	s_add_u32 s40, s16, s46
	s_addc_u32 s41, s17, 0
	s_add_u32 s44, s0, 2
	s_min_u32 s44, s44, 0xff
	s_bfe_u32 s45, s44, 0x40003
	s_lshl_b32 s45, s45, 20
	s_and_b32 s46, s44, 7
	s_lshl_b32 s46, s46, 6
	s_add_u32 s45, s45, s46
	s_add_u32 s45, s45, s8
	s_add_u32 s45, s45, 0x6000000
	s_add_u32 s22, s98, s45
	s_addc_u32 s23, s99, 0
	s_and_b32 s47, s0, 7
	s_cmp_eq_u32 s47, 0
	s_cbranch_scc0 .Lpu_b0_nox
	s_lshr_b32 s44, s0, 3
	s_add_u32 s44, s44, 1
	s_min_u32 s44, s44, 31
	s_and_b32 s45, s44, 15
	s_lshl_b32 s45, s45, 23
	s_lshl_b32 s46, s8, 3
	s_add_u32 s45, s45, s46
	s_lshr_b32 s46, s44, 4
	s_add_u32 s46, s46, s9
	s_lshl_b32 s46, s46, 8
	s_add_u32 s45, s45, s46
	s_add_u32 s24, s20, s45
	s_addc_u32 s25, s21, 0
	global_load_dwordx4 v[120:123], v236, s[24:25]
	global_load_dwordx4 v[124:127], v236, s[24:25] offset:16
; #define FP8_LO(w) __builtin_amdgcn_cvt_pk_f32_fp8((int)(w), false)
; #define FP8_HI(w) __builtin_amdgcn_cvt_pk_f32_fp8((int)(w), true)
; DI float dot16p(const u32x4 xa, const u32x4 xb, const u32x4 w) {
;     const f32x2 a0 = FP8_LO(w.x), a1 = FP8_HI(w.x), a2 = FP8_LO(w.y), a3 = FP8_HI(w.y), a4 = FP8_LO(w.z), a5 = FP8_HI(w.z), a6 = FP8_LO(w.w), a7 = FP8_HI(w.w);
;     return (bflo(xa.x) * a0.x + bfhi(xa.x) * a0.y + bflo(xa.y) * a1.x + bfhi(xa.y) * a1.y) + (bflo(xa.z) * a2.x + bfhi(xa.z) * a2.y + bflo(xa.w) * a3.x + bfhi(xa.w) * a3.y)
;          + (bflo(xb.x) * a4.x + bfhi(xb.x) * a4.y + bflo(xb.y) * a5.x + bfhi(xb.y) * a5.y) + (bflo(xb.z) * a6.x + bfhi(xb.z) * a6.y + bflo(xb.w) * a7.x + bfhi(xb.w) * a7.y);
; }
; DI void phase_peer_u(const Args& a, int layer, int ci) {
;     ...
;             for (int g8 = 0; g8 < 16; ++g8) {
;                 u32x4 nxt[8];
;                 if (g8 < 15) gat_loadhu(U, idA, idB, g8 + 1, lo16, nxt); else gat_loadhu(U, idAn, idBn, 0, lo16, nxt);
;                 const float c0 = dots4h(xa, xb, cur[0], cur[1], cur[2], cur[3], lane);
;                 const float c1 = dots4h(xa, xb, cur[4], cur[5], cur[6], cur[7], lane);
.Lpu_b0_nox:
	global_load_dwordx4 v[72:75], v1, s[22:23]
	global_load_dwordx4 v[76:79], v1, s[22:23] offset:16
	global_load_dwordx4 v[80:83], v1, s[22:23] offset:32
	global_load_dwordx4 v[84:87], v1, s[22:23] offset:48
	s_waitcnt vmcnt(19)
	v_cvt_pk_f32_fp8_e32 v[140:141], v8
	v_cvt_pk_f32_fp8_sdwa v[142:143], v8 src0_sel:WORD_1
	v_cvt_pk_f32_fp8_e32 v[144:145], v9
	v_cvt_pk_f32_fp8_sdwa v[146:147], v9 src0_sel:WORD_1
	v_pk_mul_f32 v[148:149], v[140:141], v[104:105]
	v_pk_mul_f32 v[150:151], v[142:143], v[106:107]
	v_pk_fma_f32 v[148:149], v[144:145], v[108:109], v[148:149]
	v_pk_fma_f32 v[150:151], v[146:147], v[110:111], v[150:151]
	v_cvt_pk_f32_fp8_e32 v[140:141], v10
	v_cvt_pk_f32_fp8_sdwa v[142:143], v10 src0_sel:WORD_1
	v_cvt_pk_f32_fp8_e32 v[144:145], v11
	v_cvt_pk_f32_fp8_sdwa v[146:147], v11 src0_sel:WORD_1
	v_pk_fma_f32 v[148:149], v[140:141], v[112:113], v[148:149]
	v_pk_fma_f32 v[150:151], v[142:143], v[114:115], v[150:151]
	v_pk_fma_f32 v[148:149], v[144:145], v[116:117], v[148:149]
	v_pk_fma_f32 v[150:151], v[146:147], v[118:119], v[150:151]
	v_pk_add_f32 v[148:149], v[148:149], v[150:151]
	s_nop 0
	v_add_f32_e32 v156, v148, v149
	v_lshl_add_u32 v3, v88, 7, v0
	global_load_dwordx4 v[8:11], v3, s[40:41]
	s_waitcnt vmcnt(19)
	v_cvt_pk_f32_fp8_e32 v[140:141], v12
	v_cvt_pk_f32_fp8_sdwa v[142:143], v12 src0_sel:WORD_1
	v_cvt_pk_f32_fp8_e32 v[144:145], v13
	v_cvt_pk_f32_fp8_sdwa v[146:147], v13 src0_sel:WORD_1
	v_pk_mul_f32 v[148:149], v[140:141], v[104:105]
	v_pk_mul_f32 v[150:151], v[142:143], v[106:107]
	v_pk_fma_f32 v[148:149], v[144:145], v[108:109], v[148:149]
	v_pk_fma_f32 v[150:151], v[146:147], v[110:111], v[150:151]
	v_cvt_pk_f32_fp8_e32 v[140:141], v14
	v_cvt_pk_f32_fp8_sdwa v[142:143], v14 src0_sel:WORD_1
	v_cvt_pk_f32_fp8_e32 v[144:145], v15
	v_cvt_pk_f32_fp8_sdwa v[146:147], v15 src0_sel:WORD_1
	v_pk_fma_f32 v[148:149], v[140:141], v[112:113], v[148:149]
	v_pk_fma_f32 v[150:151], v[142:143], v[114:115], v[150:151]
	v_pk_fma_f32 v[148:149], v[144:145], v[116:117], v[148:149]
	v_pk_fma_f32 v[150:151], v[146:147], v[118:119], v[150:151]
	v_pk_add_f32 v[148:149], v[148:149], v[150:151]
	s_nop 0
	v_add_f32_e32 v157, v148, v149
	v_lshl_add_u32 v4, v89, 7, v0
	global_load_dwordx4 v[12:15], v4, s[40:41]
	s_waitcnt vmcnt(19)
	v_cvt_pk_f32_fp8_e32 v[140:141], v16
	v_cvt_pk_f32_fp8_sdwa v[142:143], v16 src0_sel:WORD_1
	v_cvt_pk_f32_fp8_e32 v[144:145], v17
	v_cvt_pk_f32_fp8_sdwa v[146:147], v17 src0_sel:WORD_1
	v_pk_mul_f32 v[148:149], v[140:141], v[104:105]
	v_pk_mul_f32 v[150:151], v[142:143], v[106:107]
	v_pk_fma_f32 v[148:149], v[144:145], v[108:109], v[148:149]
	v_pk_fma_f32 v[150:151], v[146:147], v[110:111], v[150:151]
	v_cvt_pk_f32_fp8_e32 v[140:141], v18
	v_cvt_pk_f32_fp8_sdwa v[142:143], v18 src0_sel:WORD_1
	v_cvt_pk_f32_fp8_e32 v[144:145], v19
	v_cvt_pk_f32_fp8_sdwa v[146:147], v19 src0_sel:WORD_1
	v_pk_fma_f32 v[148:149], v[140:141], v[112:113], v[148:149]
	v_pk_fma_f32 v[150:151], v[142:143], v[114:115], v[150:151]
	v_pk_fma_f32 v[148:149], v[144:145], v[116:117], v[148:149]
	v_pk_fma_f32 v[150:151], v[146:147], v[118:119], v[150:151]
	v_pk_add_f32 v[148:149], v[148:149], v[150:151]
	s_nop 0
	v_add_f32_e32 v158, v148, v149
	v_lshl_add_u32 v3, v90, 7, v0
	global_load_dwordx4 v[16:19], v3, s[40:41]
	s_waitcnt vmcnt(19)
	v_cvt_pk_f32_fp8_e32 v[140:141], v20
	v_cvt_pk_f32_fp8_sdwa v[142:143], v20 src0_sel:WORD_1
	v_cvt_pk_f32_fp8_e32 v[144:145], v21
	v_cvt_pk_f32_fp8_sdwa v[146:147], v21 src0_sel:WORD_1
	v_pk_mul_f32 v[148:149], v[140:141], v[104:105]
	v_pk_mul_f32 v[150:151], v[142:143], v[106:107]
	v_pk_fma_f32 v[148:149], v[144:145], v[108:109], v[148:149]
	v_pk_fma_f32 v[150:151], v[146:147], v[110:111], v[150:151]
	v_cvt_pk_f32_fp8_e32 v[140:141], v22
	v_cvt_pk_f32_fp8_sdwa v[142:143], v22 src0_sel:WORD_1
	v_cvt_pk_f32_fp8_e32 v[144:145], v23
	v_cvt_pk_f32_fp8_sdwa v[146:147], v23 src0_sel:WORD_1
	v_pk_fma_f32 v[148:149], v[140:141], v[112:113], v[148:149]
	v_pk_fma_f32 v[150:151], v[142:143], v[114:115], v[150:151]
	v_pk_fma_f32 v[148:149], v[144:145], v[116:117], v[148:149]
	v_pk_fma_f32 v[150:151], v[146:147], v[118:119], v[150:151]
	v_pk_add_f32 v[148:149], v[148:149], v[150:151]
	s_nop 0
	v_add_f32_e32 v159, v148, v149
	v_lshl_add_u32 v4, v91, 7, v0
	global_load_dwordx4 v[20:23], v4, s[40:41]
	s_waitcnt vmcnt(19)
	v_cvt_pk_f32_fp8_e32 v[140:141], v24
	v_cvt_pk_f32_fp8_sdwa v[142:143], v24 src0_sel:WORD_1
	v_cvt_pk_f32_fp8_e32 v[144:145], v25
	v_cvt_pk_f32_fp8_sdwa v[146:147], v25 src0_sel:WORD_1
	v_pk_mul_f32 v[148:149], v[140:141], v[104:105]
	v_pk_mul_f32 v[150:151], v[142:143], v[106:107]
	v_pk_fma_f32 v[148:149], v[144:145], v[108:109], v[148:149]
	v_pk_fma_f32 v[150:151], v[146:147], v[110:111], v[150:151]
	v_cvt_pk_f32_fp8_e32 v[140:141], v26
	v_cvt_pk_f32_fp8_sdwa v[142:143], v26 src0_sel:WORD_1
	v_cvt_pk_f32_fp8_e32 v[144:145], v27
	v_cvt_pk_f32_fp8_sdwa v[146:147], v27 src0_sel:WORD_1
	v_pk_fma_f32 v[148:149], v[140:141], v[112:113], v[148:149]
	v_pk_fma_f32 v[150:151], v[142:143], v[114:115], v[150:151]
	v_pk_fma_f32 v[148:149], v[144:145], v[116:117], v[148:149]
	v_pk_fma_f32 v[150:151], v[146:147], v[118:119], v[150:151]
	v_pk_add_f32 v[148:149], v[148:149], v[150:151]
	s_nop 0
	v_add_f32_e32 v160, v148, v149
	v_lshl_add_u32 v3, v92, 7, v0
	global_load_dwordx4 v[24:27], v3, s[40:41]
	s_waitcnt vmcnt(19)
; #define FP8_LO(w) __builtin_amdgcn_cvt_pk_f32_fp8((int)(w), false)
; #define FP8_HI(w) __builtin_amdgcn_cvt_pk_f32_fp8((int)(w), true)
; DI float dot16p(const u32x4 xa, const u32x4 xb, const u32x4 w) {
;     const f32x2 a0 = FP8_LO(w.x), a1 = FP8_HI(w.x), a2 = FP8_LO(w.y), a3 = FP8_HI(w.y), a4 = FP8_LO(w.z), a5 = FP8_HI(w.z), a6 = FP8_LO(w.w), a7 = FP8_HI(w.w);
;     return (bflo(xa.x) * a0.x + bfhi(xa.x) * a0.y + bflo(xa.y) * a1.x + bfhi(xa.y) * a1.y) + (bflo(xa.z) * a2.x + bfhi(xa.z) * a2.y + bflo(xa.w) * a3.x + bfhi(xa.w) * a3.y)
;          + (bflo(xb.x) * a4.x + bfhi(xb.x) * a4.y + bflo(xb.y) * a5.x + bfhi(xb.y) * a5.y) + (bflo(xb.z) * a6.x + bfhi(xb.z) * a6.y + bflo(xb.w) * a7.x + bfhi(xb.w) * a7.y);
; }
; DI void phase_peer_u(const Args& a, int layer, int ci) {
;     ...
;             for (int g8 = 0; g8 < 16; ++g8) {
;                 u32x4 nxt[8];
;                 if (g8 < 15) gat_loadhu(U, idA, idB, g8 + 1, lo16, nxt); else gat_loadhu(U, idAn, idBn, 0, lo16, nxt);
;                 const float c0 = dots4h(xa, xb, cur[0], cur[1], cur[2], cur[3], lane);
;                 const float c1 = dots4h(xa, xb, cur[4], cur[5], cur[6], cur[7], lane);
	v_cvt_pk_f32_fp8_e32 v[140:141], v28
	v_cvt_pk_f32_fp8_sdwa v[142:143], v28 src0_sel:WORD_1
	v_cvt_pk_f32_fp8_e32 v[144:145], v29
	v_cvt_pk_f32_fp8_sdwa v[146:147], v29 src0_sel:WORD_1
	v_pk_mul_f32 v[148:149], v[140:141], v[104:105]
	v_pk_mul_f32 v[150:151], v[142:143], v[106:107]
	v_pk_fma_f32 v[148:149], v[144:145], v[108:109], v[148:149]
	v_pk_fma_f32 v[150:151], v[146:147], v[110:111], v[150:151]
	v_cvt_pk_f32_fp8_e32 v[140:141], v30
	v_cvt_pk_f32_fp8_sdwa v[142:143], v30 src0_sel:WORD_1
	v_cvt_pk_f32_fp8_e32 v[144:145], v31
	v_cvt_pk_f32_fp8_sdwa v[146:147], v31 src0_sel:WORD_1
	v_pk_fma_f32 v[148:149], v[140:141], v[112:113], v[148:149]
	v_pk_fma_f32 v[150:151], v[142:143], v[114:115], v[150:151]
	v_pk_fma_f32 v[148:149], v[144:145], v[116:117], v[148:149]
	v_pk_fma_f32 v[150:151], v[146:147], v[118:119], v[150:151]
	v_pk_add_f32 v[148:149], v[148:149], v[150:151]
	s_nop 0
	v_add_f32_e32 v161, v148, v149
	v_lshl_add_u32 v4, v93, 7, v0
	global_load_dwordx4 v[28:31], v4, s[40:41]
	s_waitcnt vmcnt(19)
	v_cvt_pk_f32_fp8_e32 v[140:141], v32
	v_cvt_pk_f32_fp8_sdwa v[142:143], v32 src0_sel:WORD_1
	v_cvt_pk_f32_fp8_e32 v[144:145], v33
	v_cvt_pk_f32_fp8_sdwa v[146:147], v33 src0_sel:WORD_1
	v_pk_mul_f32 v[148:149], v[140:141], v[104:105]
	v_pk_mul_f32 v[150:151], v[142:143], v[106:107]
	v_pk_fma_f32 v[148:149], v[144:145], v[108:109], v[148:149]
	v_pk_fma_f32 v[150:151], v[146:147], v[110:111], v[150:151]
	v_cvt_pk_f32_fp8_e32 v[140:141], v34
	v_cvt_pk_f32_fp8_sdwa v[142:143], v34 src0_sel:WORD_1
	v_cvt_pk_f32_fp8_e32 v[144:145], v35
	v_cvt_pk_f32_fp8_sdwa v[146:147], v35 src0_sel:WORD_1
	v_pk_fma_f32 v[148:149], v[140:141], v[112:113], v[148:149]
	v_pk_fma_f32 v[150:151], v[142:143], v[114:115], v[150:151]
	v_pk_fma_f32 v[148:149], v[144:145], v[116:117], v[148:149]
	v_pk_fma_f32 v[150:151], v[146:147], v[118:119], v[150:151]
	v_pk_add_f32 v[148:149], v[148:149], v[150:151]
	s_nop 0
	v_add_f32_e32 v162, v148, v149
	v_lshl_add_u32 v3, v94, 7, v0
	global_load_dwordx4 v[32:35], v3, s[40:41]
	s_waitcnt vmcnt(19)
	v_cvt_pk_f32_fp8_e32 v[140:141], v36
	v_cvt_pk_f32_fp8_sdwa v[142:143], v36 src0_sel:WORD_1
	v_cvt_pk_f32_fp8_e32 v[144:145], v37
	v_cvt_pk_f32_fp8_sdwa v[146:147], v37 src0_sel:WORD_1
	v_pk_mul_f32 v[148:149], v[140:141], v[104:105]
	v_pk_mul_f32 v[150:151], v[142:143], v[106:107]
	v_pk_fma_f32 v[148:149], v[144:145], v[108:109], v[148:149]
	v_pk_fma_f32 v[150:151], v[146:147], v[110:111], v[150:151]
	v_cvt_pk_f32_fp8_e32 v[140:141], v38
	v_cvt_pk_f32_fp8_sdwa v[142:143], v38 src0_sel:WORD_1
	v_cvt_pk_f32_fp8_e32 v[144:145], v39
	v_cvt_pk_f32_fp8_sdwa v[146:147], v39 src0_sel:WORD_1
	v_pk_fma_f32 v[148:149], v[140:141], v[112:113], v[148:149]
	v_pk_fma_f32 v[150:151], v[142:143], v[114:115], v[150:151]
	v_pk_fma_f32 v[148:149], v[144:145], v[116:117], v[148:149]
	v_pk_fma_f32 v[150:151], v[146:147], v[118:119], v[150:151]
	v_pk_add_f32 v[148:149], v[148:149], v[150:151]
	s_nop 0
	v_add_f32_e32 v163, v148, v149
	v_lshl_add_u32 v4, v95, 7, v0
	global_load_dwordx4 v[36:39], v4, s[40:41]
	s_waitcnt vmcnt(19)
	v_cvt_pk_f32_fp8_e32 v[140:141], v40
	v_cvt_pk_f32_fp8_sdwa v[142:143], v40 src0_sel:WORD_1
	v_cvt_pk_f32_fp8_e32 v[144:145], v41
	v_cvt_pk_f32_fp8_sdwa v[146:147], v41 src0_sel:WORD_1
	v_pk_mul_f32 v[148:149], v[140:141], v[104:105]
	v_pk_mul_f32 v[150:151], v[142:143], v[106:107]
	v_pk_fma_f32 v[148:149], v[144:145], v[108:109], v[148:149]
	v_pk_fma_f32 v[150:151], v[146:147], v[110:111], v[150:151]
	v_cvt_pk_f32_fp8_e32 v[140:141], v42
	v_cvt_pk_f32_fp8_sdwa v[142:143], v42 src0_sel:WORD_1
	v_cvt_pk_f32_fp8_e32 v[144:145], v43
	v_cvt_pk_f32_fp8_sdwa v[146:147], v43 src0_sel:WORD_1
	v_pk_fma_f32 v[148:149], v[140:141], v[112:113], v[148:149]
	v_pk_fma_f32 v[150:151], v[142:143], v[114:115], v[150:151]
	v_pk_fma_f32 v[148:149], v[144:145], v[116:117], v[148:149]
	v_pk_fma_f32 v[150:151], v[146:147], v[118:119], v[150:151]
	v_pk_add_f32 v[148:149], v[148:149], v[150:151]
	s_nop 0
	v_add_f32_e32 v166, v148, v149
	v_lshl_add_u32 v3, v96, 7, v0
	global_load_dwordx4 v[40:43], v3, s[40:41]
	s_waitcnt vmcnt(19)
	v_cvt_pk_f32_fp8_e32 v[140:141], v44
	v_cvt_pk_f32_fp8_sdwa v[142:143], v44 src0_sel:WORD_1
	v_cvt_pk_f32_fp8_e32 v[144:145], v45
	v_cvt_pk_f32_fp8_sdwa v[146:147], v45 src0_sel:WORD_1
	v_pk_mul_f32 v[148:149], v[140:141], v[104:105]
	v_pk_mul_f32 v[150:151], v[142:143], v[106:107]
	v_pk_fma_f32 v[148:149], v[144:145], v[108:109], v[148:149]
	v_pk_fma_f32 v[150:151], v[146:147], v[110:111], v[150:151]
	v_cvt_pk_f32_fp8_e32 v[140:141], v46
	v_cvt_pk_f32_fp8_sdwa v[142:143], v46 src0_sel:WORD_1
	v_cvt_pk_f32_fp8_e32 v[144:145], v47
	v_cvt_pk_f32_fp8_sdwa v[146:147], v47 src0_sel:WORD_1
	v_pk_fma_f32 v[148:149], v[140:141], v[112:113], v[148:149]
	v_pk_fma_f32 v[150:151], v[142:143], v[114:115], v[150:151]
	v_pk_fma_f32 v[148:149], v[144:145], v[116:117], v[148:149]
	v_pk_fma_f32 v[150:151], v[146:147], v[118:119], v[150:151]
	v_pk_add_f32 v[148:149], v[148:149], v[150:151]
	s_nop 0
	v_add_f32_e32 v167, v148, v149
	v_lshl_add_u32 v4, v97, 7, v0
	global_load_dwordx4 v[44:47], v4, s[40:41]
	s_waitcnt vmcnt(19)
	v_cvt_pk_f32_fp8_e32 v[140:141], v48
	v_cvt_pk_f32_fp8_sdwa v[142:143], v48 src0_sel:WORD_1
	v_cvt_pk_f32_fp8_e32 v[144:145], v49
	v_cvt_pk_f32_fp8_sdwa v[146:147], v49 src0_sel:WORD_1
	v_pk_mul_f32 v[148:149], v[140:141], v[104:105]
	v_pk_mul_f32 v[150:151], v[142:143], v[106:107]
	v_pk_fma_f32 v[148:149], v[144:145], v[108:109], v[148:149]
	v_pk_fma_f32 v[150:151], v[146:147], v[110:111], v[150:151]
	v_cvt_pk_f32_fp8_e32 v[140:141], v50
	v_cvt_pk_f32_fp8_sdwa v[142:143], v50 src0_sel:WORD_1
	v_cvt_pk_f32_fp8_e32 v[144:145], v51
	v_cvt_pk_f32_fp8_sdwa v[146:147], v51 src0_sel:WORD_1
	v_pk_fma_f32 v[148:149], v[140:141], v[112:113], v[148:149]
	v_pk_fma_f32 v[150:151], v[142:143], v[114:115], v[150:151]
	v_pk_fma_f32 v[148:149], v[144:145], v[116:117], v[148:149]
	v_pk_fma_f32 v[150:151], v[146:147], v[118:119], v[150:151]
	v_pk_add_f32 v[148:149], v[148:149], v[150:151]
	s_nop 0
	v_add_f32_e32 v168, v148, v149
	v_lshl_add_u32 v3, v98, 7, v0
	global_load_dwordx4 v[48:51], v3, s[40:41]
	s_waitcnt vmcnt(19)
; DI float dots4h(const u32x4 xa, const u32x4 xb, const u32x4 b0, const u32x4 b1, const u32x4 b2, const u32x4 b3, int lane) {
;     ...
;     const bool p1 = lane & 1, p2 = lane & 2;
;     const float b0s = (p1 ? d1 : d0) + __shfl_xor(p1 ? d0 : d1, 1);
;     const float b1s = (p1 ? d3 : d2) + __shfl_xor(p1 ? d2 : d3, 1);
;     float cs = (p2 ? b1s : b0s) + __shfl_xor(p2 ? b0s : b1s, 2);
;     cs += __shfl_xor(cs, 4); cs += __shfl_xor(cs, 8); cs += __shfl_xor(cs, 16); cs += __shfl_xor(cs, 32);
;     return cs;
; DI void phase_peer_u(const Args& a, int layer, int ci) {
;     ...
;             for (int g8 = 0; g8 < 16; ++g8) {
;                 u32x4 nxt[8];
;                 if (g8 < 15) gat_loadhu(U, idA, idB, g8 + 1, lo16, nxt); else gat_loadhu(U, idAn, idBn, 0, lo16, nxt);
;                 const float c0 = dots4h(xa, xb, cur[0], cur[1], cur[2], cur[3], lane);
;                 const float c1 = dots4h(xa, xb, cur[4], cur[5], cur[6], cur[7], lane);
	v_cvt_pk_f32_fp8_e32 v[140:141], v52
	v_cvt_pk_f32_fp8_sdwa v[142:143], v52 src0_sel:WORD_1
	v_cvt_pk_f32_fp8_e32 v[144:145], v53
	v_cvt_pk_f32_fp8_sdwa v[146:147], v53 src0_sel:WORD_1
	v_pk_mul_f32 v[148:149], v[140:141], v[104:105]
	v_pk_mul_f32 v[150:151], v[142:143], v[106:107]
	v_pk_fma_f32 v[148:149], v[144:145], v[108:109], v[148:149]
	v_pk_fma_f32 v[150:151], v[146:147], v[110:111], v[150:151]
	v_cvt_pk_f32_fp8_e32 v[140:141], v54
	v_cvt_pk_f32_fp8_sdwa v[142:143], v54 src0_sel:WORD_1
	v_cvt_pk_f32_fp8_e32 v[144:145], v55
	v_cvt_pk_f32_fp8_sdwa v[146:147], v55 src0_sel:WORD_1
	v_pk_fma_f32 v[148:149], v[140:141], v[112:113], v[148:149]
	v_pk_fma_f32 v[150:151], v[142:143], v[114:115], v[150:151]
	v_pk_fma_f32 v[148:149], v[144:145], v[116:117], v[148:149]
	v_pk_fma_f32 v[150:151], v[146:147], v[118:119], v[150:151]
	v_pk_add_f32 v[148:149], v[148:149], v[150:151]
	s_nop 0
	v_add_f32_e32 v169, v148, v149
	v_lshl_add_u32 v4, v99, 7, v0
	global_load_dwordx4 v[52:55], v4, s[40:41]
	s_waitcnt vmcnt(19)
	v_cvt_pk_f32_fp8_e32 v[140:141], v56
	v_cvt_pk_f32_fp8_sdwa v[142:143], v56 src0_sel:WORD_1
	v_cvt_pk_f32_fp8_e32 v[144:145], v57
	v_cvt_pk_f32_fp8_sdwa v[146:147], v57 src0_sel:WORD_1
	v_pk_mul_f32 v[148:149], v[140:141], v[104:105]
	v_pk_mul_f32 v[150:151], v[142:143], v[106:107]
	v_pk_fma_f32 v[148:149], v[144:145], v[108:109], v[148:149]
	v_pk_fma_f32 v[150:151], v[146:147], v[110:111], v[150:151]
	v_cvt_pk_f32_fp8_e32 v[140:141], v58
	v_cvt_pk_f32_fp8_sdwa v[142:143], v58 src0_sel:WORD_1
	v_cvt_pk_f32_fp8_e32 v[144:145], v59
	v_cvt_pk_f32_fp8_sdwa v[146:147], v59 src0_sel:WORD_1
	v_pk_fma_f32 v[148:149], v[140:141], v[112:113], v[148:149]
	v_pk_fma_f32 v[150:151], v[142:143], v[114:115], v[150:151]
	v_pk_fma_f32 v[148:149], v[144:145], v[116:117], v[148:149]
	v_pk_fma_f32 v[150:151], v[146:147], v[118:119], v[150:151]
	v_pk_add_f32 v[148:149], v[148:149], v[150:151]
	s_nop 0
	v_add_f32_e32 v170, v148, v149
	v_lshl_add_u32 v3, v100, 7, v0
	global_load_dwordx4 v[56:59], v3, s[40:41]
	s_waitcnt vmcnt(19)
	v_cvt_pk_f32_fp8_e32 v[140:141], v60
	v_cvt_pk_f32_fp8_sdwa v[142:143], v60 src0_sel:WORD_1
	v_cvt_pk_f32_fp8_e32 v[144:145], v61
	v_cvt_pk_f32_fp8_sdwa v[146:147], v61 src0_sel:WORD_1
	v_pk_mul_f32 v[148:149], v[140:141], v[104:105]
	v_pk_mul_f32 v[150:151], v[142:143], v[106:107]
	v_pk_fma_f32 v[148:149], v[144:145], v[108:109], v[148:149]
	v_pk_fma_f32 v[150:151], v[146:147], v[110:111], v[150:151]
	v_cvt_pk_f32_fp8_e32 v[140:141], v62
	v_cvt_pk_f32_fp8_sdwa v[142:143], v62 src0_sel:WORD_1
	v_cvt_pk_f32_fp8_e32 v[144:145], v63
	v_cvt_pk_f32_fp8_sdwa v[146:147], v63 src0_sel:WORD_1
	v_pk_fma_f32 v[148:149], v[140:141], v[112:113], v[148:149]
	v_pk_fma_f32 v[150:151], v[142:143], v[114:115], v[150:151]
	v_pk_fma_f32 v[148:149], v[144:145], v[116:117], v[148:149]
	v_pk_fma_f32 v[150:151], v[146:147], v[118:119], v[150:151]
	v_pk_add_f32 v[148:149], v[148:149], v[150:151]
	s_nop 0
	v_add_f32_e32 v171, v148, v149
	v_lshl_add_u32 v4, v101, 7, v0
	global_load_dwordx4 v[60:63], v4, s[40:41]
	s_waitcnt vmcnt(19)
	v_cvt_pk_f32_fp8_e32 v[140:141], v64
	v_cvt_pk_f32_fp8_sdwa v[142:143], v64 src0_sel:WORD_1
	v_cvt_pk_f32_fp8_e32 v[144:145], v65
	v_cvt_pk_f32_fp8_sdwa v[146:147], v65 src0_sel:WORD_1
	v_pk_mul_f32 v[148:149], v[140:141], v[104:105]
	v_pk_mul_f32 v[150:151], v[142:143], v[106:107]
	v_pk_fma_f32 v[148:149], v[144:145], v[108:109], v[148:149]
	v_pk_fma_f32 v[150:151], v[146:147], v[110:111], v[150:151]
	v_cvt_pk_f32_fp8_e32 v[140:141], v66
	v_cvt_pk_f32_fp8_sdwa v[142:143], v66 src0_sel:WORD_1
	v_cvt_pk_f32_fp8_e32 v[144:145], v67
	v_cvt_pk_f32_fp8_sdwa v[146:147], v67 src0_sel:WORD_1
	v_pk_fma_f32 v[148:149], v[140:141], v[112:113], v[148:149]
	v_pk_fma_f32 v[150:151], v[142:143], v[114:115], v[150:151]
	v_pk_fma_f32 v[148:149], v[144:145], v[116:117], v[148:149]
	v_pk_fma_f32 v[150:151], v[146:147], v[118:119], v[150:151]
	v_pk_add_f32 v[148:149], v[148:149], v[150:151]
	s_nop 0
	v_add_f32_e32 v172, v148, v149
	v_lshl_add_u32 v3, v102, 7, v0
	global_load_dwordx4 v[64:67], v3, s[40:41]
	s_waitcnt vmcnt(19)
	v_cvt_pk_f32_fp8_e32 v[140:141], v68
	v_cvt_pk_f32_fp8_sdwa v[142:143], v68 src0_sel:WORD_1
	v_cvt_pk_f32_fp8_e32 v[144:145], v69
	v_cvt_pk_f32_fp8_sdwa v[146:147], v69 src0_sel:WORD_1
	v_pk_mul_f32 v[148:149], v[140:141], v[104:105]
	v_pk_mul_f32 v[150:151], v[142:143], v[106:107]
	v_pk_fma_f32 v[148:149], v[144:145], v[108:109], v[148:149]
	v_pk_fma_f32 v[150:151], v[146:147], v[110:111], v[150:151]
	v_cvt_pk_f32_fp8_e32 v[140:141], v70
	v_cvt_pk_f32_fp8_sdwa v[142:143], v70 src0_sel:WORD_1
	v_cvt_pk_f32_fp8_e32 v[144:145], v71
	v_cvt_pk_f32_fp8_sdwa v[146:147], v71 src0_sel:WORD_1
	v_pk_fma_f32 v[148:149], v[140:141], v[112:113], v[148:149]
	v_pk_fma_f32 v[150:151], v[142:143], v[114:115], v[150:151]
	v_pk_fma_f32 v[148:149], v[144:145], v[116:117], v[148:149]
	v_pk_fma_f32 v[150:151], v[146:147], v[118:119], v[150:151]
	v_pk_add_f32 v[148:149], v[148:149], v[150:151]
	s_nop 0
	v_add_f32_e32 v173, v148, v149
	v_lshl_add_u32 v4, v103, 7, v0
	global_load_dwordx4 v[68:71], v4, s[40:41]
	v_cndmask_b32_e64 v152, v156, v157, s[34:35]
	v_cndmask_b32_e64 v174, v157, v156, s[34:35]
	v_cndmask_b32_e64 v153, v158, v159, s[34:35]
	v_cndmask_b32_e64 v175, v159, v158, s[34:35]
	v_cndmask_b32_e64 v154, v160, v161, s[34:35]
	v_cndmask_b32_e64 v176, v161, v160, s[34:35]
	v_cndmask_b32_e64 v155, v162, v163, s[34:35]
	v_cndmask_b32_e64 v177, v163, v162, s[34:35]
	v_add_f32_dpp v156, v174, v152 quad_perm:[1,0,3,2] row_mask:0xf bank_mask:0xf
	v_add_f32_dpp v157, v175, v153 quad_perm:[1,0,3,2] row_mask:0xf bank_mask:0xf
; DI float dots4h(const u32x4 xa, const u32x4 xb, const u32x4 b0, const u32x4 b1, const u32x4 b2, const u32x4 b3, int lane) {
;     ...
;     const bool p1 = lane & 1, p2 = lane & 2;
;     const float b0s = (p1 ? d1 : d0) + __shfl_xor(p1 ? d0 : d1, 1);
;     const float b1s = (p1 ? d3 : d2) + __shfl_xor(p1 ? d2 : d3, 1);
;     float cs = (p2 ? b1s : b0s) + __shfl_xor(p2 ? b0s : b1s, 2);
;     cs += __shfl_xor(cs, 4); cs += __shfl_xor(cs, 8); cs += __shfl_xor(cs, 16); cs += __shfl_xor(cs, 32);
;     return cs;
; DI void phase_peer_u(const Args& a, int layer, int ci) {
;     ...
;                 const float c0 = dots4h(xa, xb, cur[0], cur[1], cur[2], cur[3], lane);
;                 const float c1 = dots4h(xa, xb, cur[4], cur[5], cur[6], cur[7], lane);
;                 const int q4 = (g8 & 7) * 2;
;                 const float cv = (lane >> 2) == q4 ? c0 : c1;
;                 const bool mine = (lane >> 3) == (g8 & 7);
;                 if (ci == 0) { if (g8 < 8) rA = mine ? cv : rA; else rB = mine ? cv : rB; }
;                 else { if (g8 < 8) rA = mine ? gelu_tanh((cv + pdA) * rstdu) * glA : rA; else rB = mine ? gelu_tanh((cv + pdB) * rstdu) * glB : rB; }
; #pragma unroll
;                 for (int j = 0; j < 8; ++j) cur[j] = nxt[j];
;             }
;             if (ci == 0) { PD[(size_t)m * 128 + lane] = rA; PD[(size_t)m * 128 + 64 + lane] = rB; }
	v_add_f32_dpp v158, v176, v154 quad_perm:[1,0,3,2] row_mask:0xf bank_mask:0xf
	v_add_f32_dpp v159, v177, v155 quad_perm:[1,0,3,2] row_mask:0xf bank_mask:0xf
	v_cndmask_b32_e64 v152, v166, v167, s[34:35]
	v_cndmask_b32_e64 v174, v167, v166, s[34:35]
	v_cndmask_b32_e64 v153, v168, v169, s[34:35]
	v_cndmask_b32_e64 v175, v169, v168, s[34:35]
	v_cndmask_b32_e64 v154, v170, v171, s[34:35]
	v_cndmask_b32_e64 v176, v171, v170, s[34:35]
	v_cndmask_b32_e64 v155, v172, v173, s[34:35]
	v_cndmask_b32_e64 v177, v173, v172, s[34:35]
	v_add_f32_dpp v160, v174, v152 quad_perm:[1,0,3,2] row_mask:0xf bank_mask:0xf
	v_add_f32_dpp v161, v175, v153 quad_perm:[1,0,3,2] row_mask:0xf bank_mask:0xf
	v_add_f32_dpp v162, v176, v154 quad_perm:[1,0,3,2] row_mask:0xf bank_mask:0xf
	v_add_f32_dpp v163, v177, v155 quad_perm:[1,0,3,2] row_mask:0xf bank_mask:0xf
	v_cndmask_b32_e64 v152, v156, v157, s[48:49]
	v_cndmask_b32_e64 v174, v157, v156, s[48:49]
	v_cndmask_b32_e64 v153, v158, v159, s[48:49]
	v_cndmask_b32_e64 v175, v159, v158, s[48:49]
	v_cndmask_b32_e64 v154, v160, v161, s[48:49]
	v_cndmask_b32_e64 v176, v161, v160, s[48:49]
	v_cndmask_b32_e64 v155, v162, v163, s[48:49]
	v_cndmask_b32_e64 v177, v163, v162, s[48:49]
	v_add_f32_dpp v156, v174, v152 quad_perm:[2,3,0,1] row_mask:0xf bank_mask:0xf
	v_add_f32_dpp v157, v175, v153 quad_perm:[2,3,0,1] row_mask:0xf bank_mask:0xf
	v_add_f32_dpp v158, v176, v154 quad_perm:[2,3,0,1] row_mask:0xf bank_mask:0xf
	v_add_f32_dpp v159, v177, v155 quad_perm:[2,3,0,1] row_mask:0xf bank_mask:0xf
	v_mov_b64_e32 v[216:217], v[218:219]
	v_mov_b64_e32 v[218:219], v[220:221]
	v_mov_b64_e32 v[220:221], v[222:223]
	v_mov_b64_e32 v[222:223], v[224:225]
	v_mov_b64_e32 v[224:225], v[226:227]
	v_mov_b64_e32 v[226:227], v[232:233]
	v_mov_b64_e32 v[232:233], v[234:235]
	v_cndmask_b32_e64 v152, v156, v157, s[50:51]
	v_cndmask_b32_e64 v174, v157, v156, s[50:51]
	v_cndmask_b32_e64 v153, v158, v159, s[50:51]
	v_cndmask_b32_e64 v175, v159, v158, s[50:51]
	v_add_f32_dpp v234, v174, v152 row_shl:4 row_mask:0xf bank_mask:0x5
	v_add_f32_dpp v234, v174, v152 row_shr:4 row_mask:0xf bank_mask:0xa
	v_add_f32_dpp v235, v175, v153 row_shl:4 row_mask:0xf bank_mask:0x5
	v_add_f32_dpp v235, v175, v153 row_shr:4 row_mask:0xf bank_mask:0xa
	s_cmp_eq_u32 s47, 7
	s_cbranch_scc0 .Lpu_b0_nost
	s_bfe_u32 s45, s0, 0x40003
	s_lshl_b32 s45, s45, 20
	s_add_u32 s45, s45, s8
	s_lshr_b32 s46, s0, 7
	s_add_u32 s46, s46, s9
	s_lshl_b32 s46, s46, 24
	s_add_u32 s45, s45, s46
	s_add_u32 s45, s45, 0x20000000
	s_add_u32 s42, s98, s45
	s_addc_u32 s43, s99, 0
	global_store_dwordx4 v2, v[216:219], s[42:43]
	global_store_dwordx4 v2, v[220:223], s[42:43] offset:128
	global_store_dwordx4 v2, v[224:227], s[42:43] offset:256
	global_store_dwordx4 v2, v[232:235], s[42:43] offset:384
	v_lshlrev_b32_e32 v104, 16, v120
	v_and_b32_e32 v105, 0xffff0000, v120
	v_lshlrev_b32_e32 v106, 16, v121
	v_and_b32_e32 v107, 0xffff0000, v121
	v_lshlrev_b32_e32 v108, 16, v122
	v_and_b32_e32 v109, 0xffff0000, v122
	v_lshlrev_b32_e32 v110, 16, v123
	v_and_b32_e32 v111, 0xffff0000, v123
	v_lshlrev_b32_e32 v112, 16, v124
	v_and_b32_e32 v113, 0xffff0000, v124
	v_lshlrev_b32_e32 v114, 16, v125
	v_and_b32_e32 v115, 0xffff0000, v125
	v_lshlrev_b32_e32 v116, 16, v126
	v_and_b32_e32 v117, 0xffff0000, v126
	v_lshlrev_b32_e32 v118, 16, v127
	v_and_b32_e32 v119, 0xffff0000, v127
.Lpu_b0_nost:
	s_add_u32 s0, s0, 1
	s_add_u32 s44, s0, 1
	s_min_u32 s44, s44, 0xff
	s_lshr_b32 s46, s44, 7
	s_add_u32 s46, s46, s9
	s_lshl_b32 s46, s46, 21
	s_add_u32 s40, s16, s46
	s_addc_u32 s41, s17, 0
	s_add_u32 s44, s0, 2
	s_min_u32 s44, s44, 0xff
	s_bfe_u32 s45, s44, 0x40003
	s_lshl_b32 s45, s45, 20
	s_and_b32 s46, s44, 7
	s_lshl_b32 s46, s46, 6
	s_add_u32 s45, s45, s46
	s_add_u32 s45, s45, s8
	s_add_u32 s45, s45, 0x6000000
	s_add_u32 s22, s98, s45
	s_addc_u32 s23, s99, 0
	s_and_b32 s47, s0, 7
	s_cmp_eq_u32 s47, 0
	s_cbranch_scc0 .Lpu_b1_nox
	s_lshr_b32 s44, s0, 3
	s_add_u32 s44, s44, 1
	s_min_u32 s44, s44, 31
	s_and_b32 s45, s44, 15
	s_lshl_b32 s45, s45, 23
	s_lshl_b32 s46, s8, 3
	s_add_u32 s45, s45, s46
	s_lshr_b32 s46, s44, 4
	s_add_u32 s46, s46, s9
	s_lshl_b32 s46, s46, 8
	s_add_u32 s45, s45, s46
	s_add_u32 s24, s20, s45
	s_addc_u32 s25, s21, 0
	global_load_dwordx4 v[120:123], v236, s[24:25]
	global_load_dwordx4 v[124:127], v236, s[24:25] offset:16
; #define FP8_LO(w) __builtin_amdgcn_cvt_pk_f32_fp8((int)(w), false)
; #define FP8_HI(w) __builtin_amdgcn_cvt_pk_f32_fp8((int)(w), true)
; DI float dot16p(const u32x4 xa, const u32x4 xb, const u32x4 w) {
;     const f32x2 a0 = FP8_LO(w.x), a1 = FP8_HI(w.x), a2 = FP8_LO(w.y), a3 = FP8_HI(w.y), a4 = FP8_LO(w.z), a5 = FP8_HI(w.z), a6 = FP8_LO(w.w), a7 = FP8_HI(w.w);
;     return (bflo(xa.x) * a0.x + bfhi(xa.x) * a0.y + bflo(xa.y) * a1.x + bfhi(xa.y) * a1.y) + (bflo(xa.z) * a2.x + bfhi(xa.z) * a2.y + bflo(xa.w) * a3.x + bfhi(xa.w) * a3.y)
;          + (bflo(xb.x) * a4.x + bfhi(xb.x) * a4.y + bflo(xb.y) * a5.x + bfhi(xb.y) * a5.y) + (bflo(xb.z) * a6.x + bfhi(xb.z) * a6.y + bflo(xb.w) * a7.x + bfhi(xb.w) * a7.y);
; }
; DI void phase_peer_u(const Args& a, int layer, int ci) {
;     ...
;             for (int g8 = 0; g8 < 16; ++g8) {
;                 u32x4 nxt[8];
;                 if (g8 < 15) gat_loadhu(U, idA, idB, g8 + 1, lo16, nxt); else gat_loadhu(U, idAn, idBn, 0, lo16, nxt);
;                 const float c0 = dots4h(xa, xb, cur[0], cur[1], cur[2], cur[3], lane);
;                 const float c1 = dots4h(xa, xb, cur[4], cur[5], cur[6], cur[7], lane);
.Lpu_b1_nox:
	global_load_dwordx4 v[88:91], v1, s[22:23]
	global_load_dwordx4 v[92:95], v1, s[22:23] offset:16
	global_load_dwordx4 v[96:99], v1, s[22:23] offset:32
	global_load_dwordx4 v[100:103], v1, s[22:23] offset:48
	s_waitcnt vmcnt(19)
	v_cvt_pk_f32_fp8_e32 v[140:141], v8
	v_cvt_pk_f32_fp8_sdwa v[142:143], v8 src0_sel:WORD_1
	v_cvt_pk_f32_fp8_e32 v[144:145], v9
	v_cvt_pk_f32_fp8_sdwa v[146:147], v9 src0_sel:WORD_1
	v_pk_mul_f32 v[148:149], v[140:141], v[104:105]
	v_pk_mul_f32 v[150:151], v[142:143], v[106:107]
	v_pk_fma_f32 v[148:149], v[144:145], v[108:109], v[148:149]
	v_pk_fma_f32 v[150:151], v[146:147], v[110:111], v[150:151]
	v_cvt_pk_f32_fp8_e32 v[140:141], v10
	v_cvt_pk_f32_fp8_sdwa v[142:143], v10 src0_sel:WORD_1
	v_cvt_pk_f32_fp8_e32 v[144:145], v11
	v_cvt_pk_f32_fp8_sdwa v[146:147], v11 src0_sel:WORD_1
	v_pk_fma_f32 v[148:149], v[140:141], v[112:113], v[148:149]
	v_pk_fma_f32 v[150:151], v[142:143], v[114:115], v[150:151]
	v_pk_fma_f32 v[148:149], v[144:145], v[116:117], v[148:149]
	v_pk_fma_f32 v[150:151], v[146:147], v[118:119], v[150:151]
	v_pk_add_f32 v[148:149], v[148:149], v[150:151]
	s_nop 0
	v_add_f32_e32 v156, v148, v149
	v_lshl_add_u32 v3, v72, 7, v0
	global_load_dwordx4 v[8:11], v3, s[40:41]
	s_waitcnt vmcnt(19)
	v_cvt_pk_f32_fp8_e32 v[140:141], v12
	v_cvt_pk_f32_fp8_sdwa v[142:143], v12 src0_sel:WORD_1
	v_cvt_pk_f32_fp8_e32 v[144:145], v13
	v_cvt_pk_f32_fp8_sdwa v[146:147], v13 src0_sel:WORD_1
	v_pk_mul_f32 v[148:149], v[140:141], v[104:105]
	v_pk_mul_f32 v[150:151], v[142:143], v[106:107]
	v_pk_fma_f32 v[148:149], v[144:145], v[108:109], v[148:149]
	v_pk_fma_f32 v[150:151], v[146:147], v[110:111], v[150:151]
	v_cvt_pk_f32_fp8_e32 v[140:141], v14
	v_cvt_pk_f32_fp8_sdwa v[142:143], v14 src0_sel:WORD_1
	v_cvt_pk_f32_fp8_e32 v[144:145], v15
	v_cvt_pk_f32_fp8_sdwa v[146:147], v15 src0_sel:WORD_1
	v_pk_fma_f32 v[148:149], v[140:141], v[112:113], v[148:149]
	v_pk_fma_f32 v[150:151], v[142:143], v[114:115], v[150:151]
	v_pk_fma_f32 v[148:149], v[144:145], v[116:117], v[148:149]
	v_pk_fma_f32 v[150:151], v[146:147], v[118:119], v[150:151]
	v_pk_add_f32 v[148:149], v[148:149], v[150:151]
	s_nop 0
	v_add_f32_e32 v157, v148, v149
	v_lshl_add_u32 v4, v73, 7, v0
	global_load_dwordx4 v[12:15], v4, s[40:41]
	s_waitcnt vmcnt(19)
	v_cvt_pk_f32_fp8_e32 v[140:141], v16
	v_cvt_pk_f32_fp8_sdwa v[142:143], v16 src0_sel:WORD_1
	v_cvt_pk_f32_fp8_e32 v[144:145], v17
	v_cvt_pk_f32_fp8_sdwa v[146:147], v17 src0_sel:WORD_1
	v_pk_mul_f32 v[148:149], v[140:141], v[104:105]
	v_pk_mul_f32 v[150:151], v[142:143], v[106:107]
	v_pk_fma_f32 v[148:149], v[144:145], v[108:109], v[148:149]
	v_pk_fma_f32 v[150:151], v[146:147], v[110:111], v[150:151]
	v_cvt_pk_f32_fp8_e32 v[140:141], v18
	v_cvt_pk_f32_fp8_sdwa v[142:143], v18 src0_sel:WORD_1
	v_cvt_pk_f32_fp8_e32 v[144:145], v19
	v_cvt_pk_f32_fp8_sdwa v[146:147], v19 src0_sel:WORD_1
	v_pk_fma_f32 v[148:149], v[140:141], v[112:113], v[148:149]
	v_pk_fma_f32 v[150:151], v[142:143], v[114:115], v[150:151]
	v_pk_fma_f32 v[148:149], v[144:145], v[116:117], v[148:149]
	v_pk_fma_f32 v[150:151], v[146:147], v[118:119], v[150:151]
	v_pk_add_f32 v[148:149], v[148:149], v[150:151]
	s_nop 0
	v_add_f32_e32 v158, v148, v149
	v_lshl_add_u32 v3, v74, 7, v0
	global_load_dwordx4 v[16:19], v3, s[40:41]
	s_waitcnt vmcnt(19)
	v_cvt_pk_f32_fp8_e32 v[140:141], v20
	v_cvt_pk_f32_fp8_sdwa v[142:143], v20 src0_sel:WORD_1
	v_cvt_pk_f32_fp8_e32 v[144:145], v21
	v_cvt_pk_f32_fp8_sdwa v[146:147], v21 src0_sel:WORD_1
	v_pk_mul_f32 v[148:149], v[140:141], v[104:105]
	v_pk_mul_f32 v[150:151], v[142:143], v[106:107]
	v_pk_fma_f32 v[148:149], v[144:145], v[108:109], v[148:149]
	v_pk_fma_f32 v[150:151], v[146:147], v[110:111], v[150:151]
	v_cvt_pk_f32_fp8_e32 v[140:141], v22
	v_cvt_pk_f32_fp8_sdwa v[142:143], v22 src0_sel:WORD_1
	v_cvt_pk_f32_fp8_e32 v[144:145], v23
	v_cvt_pk_f32_fp8_sdwa v[146:147], v23 src0_sel:WORD_1
	v_pk_fma_f32 v[148:149], v[140:141], v[112:113], v[148:149]
	v_pk_fma_f32 v[150:151], v[142:143], v[114:115], v[150:151]
	v_pk_fma_f32 v[148:149], v[144:145], v[116:117], v[148:149]
	v_pk_fma_f32 v[150:151], v[146:147], v[118:119], v[150:151]
	v_pk_add_f32 v[148:149], v[148:149], v[150:151]
	s_nop 0
	v_add_f32_e32 v159, v148, v149
	v_lshl_add_u32 v4, v75, 7, v0
	global_load_dwordx4 v[20:23], v4, s[40:41]
	s_waitcnt vmcnt(19)
	v_cvt_pk_f32_fp8_e32 v[140:141], v24
	v_cvt_pk_f32_fp8_sdwa v[142:143], v24 src0_sel:WORD_1
	v_cvt_pk_f32_fp8_e32 v[144:145], v25
	v_cvt_pk_f32_fp8_sdwa v[146:147], v25 src0_sel:WORD_1
	v_pk_mul_f32 v[148:149], v[140:141], v[104:105]
	v_pk_mul_f32 v[150:151], v[142:143], v[106:107]
	v_pk_fma_f32 v[148:149], v[144:145], v[108:109], v[148:149]
	v_pk_fma_f32 v[150:151], v[146:147], v[110:111], v[150:151]
	v_cvt_pk_f32_fp8_e32 v[140:141], v26
	v_cvt_pk_f32_fp8_sdwa v[142:143], v26 src0_sel:WORD_1
	v_cvt_pk_f32_fp8_e32 v[144:145], v27
	v_cvt_pk_f32_fp8_sdwa v[146:147], v27 src0_sel:WORD_1
	v_pk_fma_f32 v[148:149], v[140:141], v[112:113], v[148:149]
	v_pk_fma_f32 v[150:151], v[142:143], v[114:115], v[150:151]
	v_pk_fma_f32 v[148:149], v[144:145], v[116:117], v[148:149]
	v_pk_fma_f32 v[150:151], v[146:147], v[118:119], v[150:151]
	v_pk_add_f32 v[148:149], v[148:149], v[150:151]
	s_nop 0
	v_add_f32_e32 v160, v148, v149
	v_lshl_add_u32 v3, v76, 7, v0
	global_load_dwordx4 v[24:27], v3, s[40:41]
	s_waitcnt vmcnt(19)
; #define FP8_LO(w) __builtin_amdgcn_cvt_pk_f32_fp8((int)(w), false)
; #define FP8_HI(w) __builtin_amdgcn_cvt_pk_f32_fp8((int)(w), true)
; DI float dot16p(const u32x4 xa, const u32x4 xb, const u32x4 w) {
;     const f32x2 a0 = FP8_LO(w.x), a1 = FP8_HI(w.x), a2 = FP8_LO(w.y), a3 = FP8_HI(w.y), a4 = FP8_LO(w.z), a5 = FP8_HI(w.z), a6 = FP8_LO(w.w), a7 = FP8_HI(w.w);
;     return (bflo(xa.x) * a0.x + bfhi(xa.x) * a0.y + bflo(xa.y) * a1.x + bfhi(xa.y) * a1.y) + (bflo(xa.z) * a2.x + bfhi(xa.z) * a2.y + bflo(xa.w) * a3.x + bfhi(xa.w) * a3.y)
;          + (bflo(xb.x) * a4.x + bfhi(xb.x) * a4.y + bflo(xb.y) * a5.x + bfhi(xb.y) * a5.y) + (bflo(xb.z) * a6.x + bfhi(xb.z) * a6.y + bflo(xb.w) * a7.x + bfhi(xb.w) * a7.y);
; }
; DI void phase_peer_u(const Args& a, int layer, int ci) {
;     ...
;             for (int g8 = 0; g8 < 16; ++g8) {
;                 u32x4 nxt[8];
;                 if (g8 < 15) gat_loadhu(U, idA, idB, g8 + 1, lo16, nxt); else gat_loadhu(U, idAn, idBn, 0, lo16, nxt);
;                 const float c0 = dots4h(xa, xb, cur[0], cur[1], cur[2], cur[3], lane);
;                 const float c1 = dots4h(xa, xb, cur[4], cur[5], cur[6], cur[7], lane);
	v_cvt_pk_f32_fp8_e32 v[140:141], v28
	v_cvt_pk_f32_fp8_sdwa v[142:143], v28 src0_sel:WORD_1
	v_cvt_pk_f32_fp8_e32 v[144:145], v29
	v_cvt_pk_f32_fp8_sdwa v[146:147], v29 src0_sel:WORD_1
	v_pk_mul_f32 v[148:149], v[140:141], v[104:105]
	v_pk_mul_f32 v[150:151], v[142:143], v[106:107]
	v_pk_fma_f32 v[148:149], v[144:145], v[108:109], v[148:149]
	v_pk_fma_f32 v[150:151], v[146:147], v[110:111], v[150:151]
	v_cvt_pk_f32_fp8_e32 v[140:141], v30
	v_cvt_pk_f32_fp8_sdwa v[142:143], v30 src0_sel:WORD_1
	v_cvt_pk_f32_fp8_e32 v[144:145], v31
	v_cvt_pk_f32_fp8_sdwa v[146:147], v31 src0_sel:WORD_1
	v_pk_fma_f32 v[148:149], v[140:141], v[112:113], v[148:149]
	v_pk_fma_f32 v[150:151], v[142:143], v[114:115], v[150:151]
	v_pk_fma_f32 v[148:149], v[144:145], v[116:117], v[148:149]
	v_pk_fma_f32 v[150:151], v[146:147], v[118:119], v[150:151]
	v_pk_add_f32 v[148:149], v[148:149], v[150:151]
	s_nop 0
	v_add_f32_e32 v161, v148, v149
	v_lshl_add_u32 v4, v77, 7, v0
	global_load_dwordx4 v[28:31], v4, s[40:41]
	s_waitcnt vmcnt(19)
	v_cvt_pk_f32_fp8_e32 v[140:141], v32
	v_cvt_pk_f32_fp8_sdwa v[142:143], v32 src0_sel:WORD_1
	v_cvt_pk_f32_fp8_e32 v[144:145], v33
	v_cvt_pk_f32_fp8_sdwa v[146:147], v33 src0_sel:WORD_1
	v_pk_mul_f32 v[148:149], v[140:141], v[104:105]
	v_pk_mul_f32 v[150:151], v[142:143], v[106:107]
	v_pk_fma_f32 v[148:149], v[144:145], v[108:109], v[148:149]
	v_pk_fma_f32 v[150:151], v[146:147], v[110:111], v[150:151]
	v_cvt_pk_f32_fp8_e32 v[140:141], v34
	v_cvt_pk_f32_fp8_sdwa v[142:143], v34 src0_sel:WORD_1
	v_cvt_pk_f32_fp8_e32 v[144:145], v35
	v_cvt_pk_f32_fp8_sdwa v[146:147], v35 src0_sel:WORD_1
	v_pk_fma_f32 v[148:149], v[140:141], v[112:113], v[148:149]
	v_pk_fma_f32 v[150:151], v[142:143], v[114:115], v[150:151]
	v_pk_fma_f32 v[148:149], v[144:145], v[116:117], v[148:149]
	v_pk_fma_f32 v[150:151], v[146:147], v[118:119], v[150:151]
	v_pk_add_f32 v[148:149], v[148:149], v[150:151]
	s_nop 0
	v_add_f32_e32 v162, v148, v149
	v_lshl_add_u32 v3, v78, 7, v0
	global_load_dwordx4 v[32:35], v3, s[40:41]
	s_waitcnt vmcnt(19)
	v_cvt_pk_f32_fp8_e32 v[140:141], v36
	v_cvt_pk_f32_fp8_sdwa v[142:143], v36 src0_sel:WORD_1
	v_cvt_pk_f32_fp8_e32 v[144:145], v37
	v_cvt_pk_f32_fp8_sdwa v[146:147], v37 src0_sel:WORD_1
	v_pk_mul_f32 v[148:149], v[140:141], v[104:105]
	v_pk_mul_f32 v[150:151], v[142:143], v[106:107]
	v_pk_fma_f32 v[148:149], v[144:145], v[108:109], v[148:149]
	v_pk_fma_f32 v[150:151], v[146:147], v[110:111], v[150:151]
	v_cvt_pk_f32_fp8_e32 v[140:141], v38
	v_cvt_pk_f32_fp8_sdwa v[142:143], v38 src0_sel:WORD_1
	v_cvt_pk_f32_fp8_e32 v[144:145], v39
	v_cvt_pk_f32_fp8_sdwa v[146:147], v39 src0_sel:WORD_1
	v_pk_fma_f32 v[148:149], v[140:141], v[112:113], v[148:149]
	v_pk_fma_f32 v[150:151], v[142:143], v[114:115], v[150:151]
	v_pk_fma_f32 v[148:149], v[144:145], v[116:117], v[148:149]
	v_pk_fma_f32 v[150:151], v[146:147], v[118:119], v[150:151]
	v_pk_add_f32 v[148:149], v[148:149], v[150:151]
	s_nop 0
	v_add_f32_e32 v163, v148, v149
	v_lshl_add_u32 v4, v79, 7, v0
	global_load_dwordx4 v[36:39], v4, s[40:41]
	s_waitcnt vmcnt(19)
	v_cvt_pk_f32_fp8_e32 v[140:141], v40
	v_cvt_pk_f32_fp8_sdwa v[142:143], v40 src0_sel:WORD_1
	v_cvt_pk_f32_fp8_e32 v[144:145], v41
	v_cvt_pk_f32_fp8_sdwa v[146:147], v41 src0_sel:WORD_1
	v_pk_mul_f32 v[148:149], v[140:141], v[104:105]
	v_pk_mul_f32 v[150:151], v[142:143], v[106:107]
	v_pk_fma_f32 v[148:149], v[144:145], v[108:109], v[148:149]
	v_pk_fma_f32 v[150:151], v[146:147], v[110:111], v[150:151]
	v_cvt_pk_f32_fp8_e32 v[140:141], v42
	v_cvt_pk_f32_fp8_sdwa v[142:143], v42 src0_sel:WORD_1
	v_cvt_pk_f32_fp8_e32 v[144:145], v43
	v_cvt_pk_f32_fp8_sdwa v[146:147], v43 src0_sel:WORD_1
	v_pk_fma_f32 v[148:149], v[140:141], v[112:113], v[148:149]
	v_pk_fma_f32 v[150:151], v[142:143], v[114:115], v[150:151]
	v_pk_fma_f32 v[148:149], v[144:145], v[116:117], v[148:149]
	v_pk_fma_f32 v[150:151], v[146:147], v[118:119], v[150:151]
	v_pk_add_f32 v[148:149], v[148:149], v[150:151]
	s_nop 0
	v_add_f32_e32 v166, v148, v149
	v_lshl_add_u32 v3, v80, 7, v0
	global_load_dwordx4 v[40:43], v3, s[40:41]
	s_waitcnt vmcnt(19)
	v_cvt_pk_f32_fp8_e32 v[140:141], v44
	v_cvt_pk_f32_fp8_sdwa v[142:143], v44 src0_sel:WORD_1
	v_cvt_pk_f32_fp8_e32 v[144:145], v45
	v_cvt_pk_f32_fp8_sdwa v[146:147], v45 src0_sel:WORD_1
	v_pk_mul_f32 v[148:149], v[140:141], v[104:105]
	v_pk_mul_f32 v[150:151], v[142:143], v[106:107]
	v_pk_fma_f32 v[148:149], v[144:145], v[108:109], v[148:149]
	v_pk_fma_f32 v[150:151], v[146:147], v[110:111], v[150:151]
	v_cvt_pk_f32_fp8_e32 v[140:141], v46
	v_cvt_pk_f32_fp8_sdwa v[142:143], v46 src0_sel:WORD_1
	v_cvt_pk_f32_fp8_e32 v[144:145], v47
	v_cvt_pk_f32_fp8_sdwa v[146:147], v47 src0_sel:WORD_1
	v_pk_fma_f32 v[148:149], v[140:141], v[112:113], v[148:149]
	v_pk_fma_f32 v[150:151], v[142:143], v[114:115], v[150:151]
	v_pk_fma_f32 v[148:149], v[144:145], v[116:117], v[148:149]
	v_pk_fma_f32 v[150:151], v[146:147], v[118:119], v[150:151]
	v_pk_add_f32 v[148:149], v[148:149], v[150:151]
	s_nop 0
	v_add_f32_e32 v167, v148, v149
	v_lshl_add_u32 v4, v81, 7, v0
	global_load_dwordx4 v[44:47], v4, s[40:41]
	s_waitcnt vmcnt(19)
	v_cvt_pk_f32_fp8_e32 v[140:141], v48
	v_cvt_pk_f32_fp8_sdwa v[142:143], v48 src0_sel:WORD_1
	v_cvt_pk_f32_fp8_e32 v[144:145], v49
	v_cvt_pk_f32_fp8_sdwa v[146:147], v49 src0_sel:WORD_1
	v_pk_mul_f32 v[148:149], v[140:141], v[104:105]
	v_pk_mul_f32 v[150:151], v[142:143], v[106:107]
	v_pk_fma_f32 v[148:149], v[144:145], v[108:109], v[148:149]
	v_pk_fma_f32 v[150:151], v[146:147], v[110:111], v[150:151]
	v_cvt_pk_f32_fp8_e32 v[140:141], v50
	v_cvt_pk_f32_fp8_sdwa v[142:143], v50 src0_sel:WORD_1
	v_cvt_pk_f32_fp8_e32 v[144:145], v51
	v_cvt_pk_f32_fp8_sdwa v[146:147], v51 src0_sel:WORD_1
	v_pk_fma_f32 v[148:149], v[140:141], v[112:113], v[148:149]
	v_pk_fma_f32 v[150:151], v[142:143], v[114:115], v[150:151]
	v_pk_fma_f32 v[148:149], v[144:145], v[116:117], v[148:149]
	v_pk_fma_f32 v[150:151], v[146:147], v[118:119], v[150:151]
	v_pk_add_f32 v[148:149], v[148:149], v[150:151]
	s_nop 0
	v_add_f32_e32 v168, v148, v149
	v_lshl_add_u32 v3, v82, 7, v0
	global_load_dwordx4 v[48:51], v3, s[40:41]
	s_waitcnt vmcnt(19)
; #define FP8_LO(w) __builtin_amdgcn_cvt_pk_f32_fp8((int)(w), false)
; #define FP8_HI(w) __builtin_amdgcn_cvt_pk_f32_fp8((int)(w), true)
; DI float dot16p(const u32x4 xa, const u32x4 xb, const u32x4 w) {
;     const f32x2 a0 = FP8_LO(w.x), a1 = FP8_HI(w.x), a2 = FP8_LO(w.y), a3 = FP8_HI(w.y), a4 = FP8_LO(w.z), a5 = FP8_HI(w.z), a6 = FP8_LO(w.w), a7 = FP8_HI(w.w);
;     return (bflo(xa.x) * a0.x + bfhi(xa.x) * a0.y + bflo(xa.y) * a1.x + bfhi(xa.y) * a1.y) + (bflo(xa.z) * a2.x + bfhi(xa.z) * a2.y + bflo(xa.w) * a3.x + bfhi(xa.w) * a3.y)
;          + (bflo(xb.x) * a4.x + bfhi(xb.x) * a4.y + bflo(xb.y) * a5.x + bfhi(xb.y) * a5.y) + (bflo(xb.z) * a6.x + bfhi(xb.z) * a6.y + bflo(xb.w) * a7.x + bfhi(xb.w) * a7.y);
; }
; DI void phase_peer_u(const Args& a, int layer, int ci) {
;     ...
;             for (int g8 = 0; g8 < 16; ++g8) {
;                 u32x4 nxt[8];
;                 if (g8 < 15) gat_loadhu(U, idA, idB, g8 + 1, lo16, nxt); else gat_loadhu(U, idAn, idBn, 0, lo16, nxt);
;                 const float c0 = dots4h(xa, xb, cur[0], cur[1], cur[2], cur[3], lane);
;                 const float c1 = dots4h(xa, xb, cur[4], cur[5], cur[6], cur[7], lane);
	v_cvt_pk_f32_fp8_e32 v[140:141], v52
	v_cvt_pk_f32_fp8_sdwa v[142:143], v52 src0_sel:WORD_1
	v_cvt_pk_f32_fp8_e32 v[144:145], v53
	v_cvt_pk_f32_fp8_sdwa v[146:147], v53 src0_sel:WORD_1
	v_pk_mul_f32 v[148:149], v[140:141], v[104:105]
	v_pk_mul_f32 v[150:151], v[142:143], v[106:107]
	v_pk_fma_f32 v[148:149], v[144:145], v[108:109], v[148:149]
	v_pk_fma_f32 v[150:151], v[146:147], v[110:111], v[150:151]
	v_cvt_pk_f32_fp8_e32 v[140:141], v54
	v_cvt_pk_f32_fp8_sdwa v[142:143], v54 src0_sel:WORD_1
	v_cvt_pk_f32_fp8_e32 v[144:145], v55
	v_cvt_pk_f32_fp8_sdwa v[146:147], v55 src0_sel:WORD_1
	v_pk_fma_f32 v[148:149], v[140:141], v[112:113], v[148:149]
	v_pk_fma_f32 v[150:151], v[142:143], v[114:115], v[150:151]
	v_pk_fma_f32 v[148:149], v[144:145], v[116:117], v[148:149]
	v_pk_fma_f32 v[150:151], v[146:147], v[118:119], v[150:151]
	v_pk_add_f32 v[148:149], v[148:149], v[150:151]
	s_nop 0
	v_add_f32_e32 v169, v148, v149
	v_lshl_add_u32 v4, v83, 7, v0
	global_load_dwordx4 v[52:55], v4, s[40:41]
	s_waitcnt vmcnt(19)
	v_cvt_pk_f32_fp8_e32 v[140:141], v56
	v_cvt_pk_f32_fp8_sdwa v[142:143], v56 src0_sel:WORD_1
	v_cvt_pk_f32_fp8_e32 v[144:145], v57
	v_cvt_pk_f32_fp8_sdwa v[146:147], v57 src0_sel:WORD_1
	v_pk_mul_f32 v[148:149], v[140:141], v[104:105]
	v_pk_mul_f32 v[150:151], v[142:143], v[106:107]
	v_pk_fma_f32 v[148:149], v[144:145], v[108:109], v[148:149]
	v_pk_fma_f32 v[150:151], v[146:147], v[110:111], v[150:151]
	v_cvt_pk_f32_fp8_e32 v[140:141], v58
	v_cvt_pk_f32_fp8_sdwa v[142:143], v58 src0_sel:WORD_1
	v_cvt_pk_f32_fp8_e32 v[144:145], v59
	v_cvt_pk_f32_fp8_sdwa v[146:147], v59 src0_sel:WORD_1
	v_pk_fma_f32 v[148:149], v[140:141], v[112:113], v[148:149]
	v_pk_fma_f32 v[150:151], v[142:143], v[114:115], v[150:151]
	v_pk_fma_f32 v[148:149], v[144:145], v[116:117], v[148:149]
	v_pk_fma_f32 v[150:151], v[146:147], v[118:119], v[150:151]
	v_pk_add_f32 v[148:149], v[148:149], v[150:151]
	s_nop 0
	v_add_f32_e32 v170, v148, v149
	v_lshl_add_u32 v3, v84, 7, v0
	global_load_dwordx4 v[56:59], v3, s[40:41]
	s_waitcnt vmcnt(19)
	v_cvt_pk_f32_fp8_e32 v[140:141], v60
	v_cvt_pk_f32_fp8_sdwa v[142:143], v60 src0_sel:WORD_1
	v_cvt_pk_f32_fp8_e32 v[144:145], v61
	v_cvt_pk_f32_fp8_sdwa v[146:147], v61 src0_sel:WORD_1
	v_pk_mul_f32 v[148:149], v[140:141], v[104:105]
	v_pk_mul_f32 v[150:151], v[142:143], v[106:107]
	v_pk_fma_f32 v[148:149], v[144:145], v[108:109], v[148:149]
	v_pk_fma_f32 v[150:151], v[146:147], v[110:111], v[150:151]
	v_cvt_pk_f32_fp8_e32 v[140:141], v62
	v_cvt_pk_f32_fp8_sdwa v[142:143], v62 src0_sel:WORD_1
	v_cvt_pk_f32_fp8_e32 v[144:145], v63
	v_cvt_pk_f32_fp8_sdwa v[146:147], v63 src0_sel:WORD_1
	v_pk_fma_f32 v[148:149], v[140:141], v[112:113], v[148:149]
	v_pk_fma_f32 v[150:151], v[142:143], v[114:115], v[150:151]
	v_pk_fma_f32 v[148:149], v[144:145], v[116:117], v[148:149]
	v_pk_fma_f32 v[150:151], v[146:147], v[118:119], v[150:151]
	v_pk_add_f32 v[148:149], v[148:149], v[150:151]
	s_nop 0
	v_add_f32_e32 v171, v148, v149
	v_lshl_add_u32 v4, v85, 7, v0
	global_load_dwordx4 v[60:63], v4, s[40:41]
	s_waitcnt vmcnt(19)
	v_cvt_pk_f32_fp8_e32 v[140:141], v64
	v_cvt_pk_f32_fp8_sdwa v[142:143], v64 src0_sel:WORD_1
	v_cvt_pk_f32_fp8_e32 v[144:145], v65
	v_cvt_pk_f32_fp8_sdwa v[146:147], v65 src0_sel:WORD_1
	v_pk_mul_f32 v[148:149], v[140:141], v[104:105]
	v_pk_mul_f32 v[150:151], v[142:143], v[106:107]
	v_pk_fma_f32 v[148:149], v[144:145], v[108:109], v[148:149]
	v_pk_fma_f32 v[150:151], v[146:147], v[110:111], v[150:151]
	v_cvt_pk_f32_fp8_e32 v[140:141], v66
	v_cvt_pk_f32_fp8_sdwa v[142:143], v66 src0_sel:WORD_1
	v_cvt_pk_f32_fp8_e32 v[144:145], v67
	v_cvt_pk_f32_fp8_sdwa v[146:147], v67 src0_sel:WORD_1
	v_pk_fma_f32 v[148:149], v[140:141], v[112:113], v[148:149]
	v_pk_fma_f32 v[150:151], v[142:143], v[114:115], v[150:151]
	v_pk_fma_f32 v[148:149], v[144:145], v[116:117], v[148:149]
	v_pk_fma_f32 v[150:151], v[146:147], v[118:119], v[150:151]
	v_pk_add_f32 v[148:149], v[148:149], v[150:151]
	s_nop 0
	v_add_f32_e32 v172, v148, v149
	v_lshl_add_u32 v3, v86, 7, v0
	global_load_dwordx4 v[64:67], v3, s[40:41]
	s_waitcnt vmcnt(19)
; DI float dots4h(const u32x4 xa, const u32x4 xb, const u32x4 b0, const u32x4 b1, const u32x4 b2, const u32x4 b3, int lane) {
;     ...
;     const bool p1 = lane & 1, p2 = lane & 2;
;     const float b0s = (p1 ? d1 : d0) + __shfl_xor(p1 ? d0 : d1, 1);
;     const float b1s = (p1 ? d3 : d2) + __shfl_xor(p1 ? d2 : d3, 1);
;     float cs = (p2 ? b1s : b0s) + __shfl_xor(p2 ? b0s : b1s, 2);
;     cs += __shfl_xor(cs, 4); cs += __shfl_xor(cs, 8); cs += __shfl_xor(cs, 16); cs += __shfl_xor(cs, 32);
;     return cs;
; DI void phase_peer_u(const Args& a, int layer, int ci) {
;     ...
;                 const float c0 = dots4h(xa, xb, cur[0], cur[1], cur[2], cur[3], lane);
;                 const float c1 = dots4h(xa, xb, cur[4], cur[5], cur[6], cur[7], lane);
;                 const int q4 = (g8 & 7) * 2;
;                 const float cv = (lane >> 2) == q4 ? c0 : c1;
;                 const bool mine = (lane >> 3) == (g8 & 7);
;                 if (ci == 0) { if (g8 < 8) rA = mine ? cv : rA; else rB = mine ? cv : rB; }
;                 else { if (g8 < 8) rA = mine ? gelu_tanh((cv + pdA) * rstdu) * glA : rA; else rB = mine ? gelu_tanh((cv + pdB) * rstdu) * glB : rB; }
; #pragma unroll
;                 for (int j = 0; j < 8; ++j) cur[j] = nxt[j];
;             }
;             if (ci == 0) { PD[(size_t)m * 128 + lane] = rA; PD[(size_t)m * 128 + 64 + lane] = rB; }
	v_cvt_pk_f32_fp8_e32 v[140:141], v68
	v_cvt_pk_f32_fp8_sdwa v[142:143], v68 src0_sel:WORD_1
	v_cvt_pk_f32_fp8_e32 v[144:145], v69
	v_cvt_pk_f32_fp8_sdwa v[146:147], v69 src0_sel:WORD_1
	v_pk_mul_f32 v[148:149], v[140:141], v[104:105]
	v_pk_mul_f32 v[150:151], v[142:143], v[106:107]
	v_pk_fma_f32 v[148:149], v[144:145], v[108:109], v[148:149]
	v_pk_fma_f32 v[150:151], v[146:147], v[110:111], v[150:151]
	v_cvt_pk_f32_fp8_e32 v[140:141], v70
	v_cvt_pk_f32_fp8_sdwa v[142:143], v70 src0_sel:WORD_1
	v_cvt_pk_f32_fp8_e32 v[144:145], v71
	v_cvt_pk_f32_fp8_sdwa v[146:147], v71 src0_sel:WORD_1
	v_pk_fma_f32 v[148:149], v[140:141], v[112:113], v[148:149]
	v_pk_fma_f32 v[150:151], v[142:143], v[114:115], v[150:151]
	v_pk_fma_f32 v[148:149], v[144:145], v[116:117], v[148:149]
	v_pk_fma_f32 v[150:151], v[146:147], v[118:119], v[150:151]
	v_pk_add_f32 v[148:149], v[148:149], v[150:151]
	s_nop 0
	v_add_f32_e32 v173, v148, v149
	v_lshl_add_u32 v4, v87, 7, v0
	global_load_dwordx4 v[68:71], v4, s[40:41]
	v_cndmask_b32_e64 v152, v156, v157, s[34:35]
	v_cndmask_b32_e64 v174, v157, v156, s[34:35]
	v_cndmask_b32_e64 v153, v158, v159, s[34:35]
	v_cndmask_b32_e64 v175, v159, v158, s[34:35]
	v_cndmask_b32_e64 v154, v160, v161, s[34:35]
	v_cndmask_b32_e64 v176, v161, v160, s[34:35]
	v_cndmask_b32_e64 v155, v162, v163, s[34:35]
	v_cndmask_b32_e64 v177, v163, v162, s[34:35]
	v_add_f32_dpp v156, v174, v152 quad_perm:[1,0,3,2] row_mask:0xf bank_mask:0xf
	v_add_f32_dpp v157, v175, v153 quad_perm:[1,0,3,2] row_mask:0xf bank_mask:0xf
	v_add_f32_dpp v158, v176, v154 quad_perm:[1,0,3,2] row_mask:0xf bank_mask:0xf
	v_add_f32_dpp v159, v177, v155 quad_perm:[1,0,3,2] row_mask:0xf bank_mask:0xf
	v_cndmask_b32_e64 v152, v166, v167, s[34:35]
	v_cndmask_b32_e64 v174, v167, v166, s[34:35]
	v_cndmask_b32_e64 v153, v168, v169, s[34:35]
	v_cndmask_b32_e64 v175, v169, v168, s[34:35]
	v_cndmask_b32_e64 v154, v170, v171, s[34:35]
	v_cndmask_b32_e64 v176, v171, v170, s[34:35]
	v_cndmask_b32_e64 v155, v172, v173, s[34:35]
	v_cndmask_b32_e64 v177, v173, v172, s[34:35]
	v_add_f32_dpp v160, v174, v152 quad_perm:[1,0,3,2] row_mask:0xf bank_mask:0xf
	v_add_f32_dpp v161, v175, v153 quad_perm:[1,0,3,2] row_mask:0xf bank_mask:0xf
	v_add_f32_dpp v162, v176, v154 quad_perm:[1,0,3,2] row_mask:0xf bank_mask:0xf
	v_add_f32_dpp v163, v177, v155 quad_perm:[1,0,3,2] row_mask:0xf bank_mask:0xf
	v_cndmask_b32_e64 v152, v156, v157, s[48:49]
	v_cndmask_b32_e64 v174, v157, v156, s[48:49]
	v_cndmask_b32_e64 v153, v158, v159, s[48:49]
	v_cndmask_b32_e64 v175, v159, v158, s[48:49]
	v_cndmask_b32_e64 v154, v160, v161, s[48:49]
	v_cndmask_b32_e64 v176, v161, v160, s[48:49]
	v_cndmask_b32_e64 v155, v162, v163, s[48:49]
	v_cndmask_b32_e64 v177, v163, v162, s[48:49]
	v_add_f32_dpp v156, v174, v152 quad_perm:[2,3,0,1] row_mask:0xf bank_mask:0xf
	v_add_f32_dpp v157, v175, v153 quad_perm:[2,3,0,1] row_mask:0xf bank_mask:0xf
	v_add_f32_dpp v158, v176, v154 quad_perm:[2,3,0,1] row_mask:0xf bank_mask:0xf
	v_add_f32_dpp v159, v177, v155 quad_perm:[2,3,0,1] row_mask:0xf bank_mask:0xf
	v_mov_b64_e32 v[216:217], v[218:219]
	v_mov_b64_e32 v[218:219], v[220:221]
	v_mov_b64_e32 v[220:221], v[222:223]
	v_mov_b64_e32 v[222:223], v[224:225]
	v_mov_b64_e32 v[224:225], v[226:227]
	v_mov_b64_e32 v[226:227], v[232:233]
	v_mov_b64_e32 v[232:233], v[234:235]
	v_cndmask_b32_e64 v152, v156, v157, s[50:51]
	v_cndmask_b32_e64 v174, v157, v156, s[50:51]
	v_cndmask_b32_e64 v153, v158, v159, s[50:51]
	v_cndmask_b32_e64 v175, v159, v158, s[50:51]
	v_add_f32_dpp v234, v174, v152 row_shl:4 row_mask:0xf bank_mask:0x5
	v_add_f32_dpp v234, v174, v152 row_shr:4 row_mask:0xf bank_mask:0xa
	v_add_f32_dpp v235, v175, v153 row_shl:4 row_mask:0xf bank_mask:0x5
	v_add_f32_dpp v235, v175, v153 row_shr:4 row_mask:0xf bank_mask:0xa
	s_cmp_eq_u32 s47, 7
	s_cbranch_scc0 .Lpu_b1_nost
	s_bfe_u32 s45, s0, 0x40003
	s_lshl_b32 s45, s45, 20
	s_add_u32 s45, s45, s8
	s_lshr_b32 s46, s0, 7
	s_add_u32 s46, s46, s9
	s_lshl_b32 s46, s46, 24
	s_add_u32 s45, s45, s46
	s_add_u32 s45, s45, 0x20000000
	s_add_u32 s42, s98, s45
	s_addc_u32 s43, s99, 0
	global_store_dwordx4 v2, v[216:219], s[42:43]
	global_store_dwordx4 v2, v[220:223], s[42:43] offset:128
	global_store_dwordx4 v2, v[224:227], s[42:43] offset:256
	global_store_dwordx4 v2, v[232:235], s[42:43] offset:384
	v_lshlrev_b32_e32 v104, 16, v120
	v_and_b32_e32 v105, 0xffff0000, v120
	v_lshlrev_b32_e32 v106, 16, v121
	v_and_b32_e32 v107, 0xffff0000, v121
	v_lshlrev_b32_e32 v108, 16, v122
	v_and_b32_e32 v109, 0xffff0000, v122
	v_lshlrev_b32_e32 v110, 16, v123
	v_and_b32_e32 v111, 0xffff0000, v123
	v_lshlrev_b32_e32 v112, 16, v124
	v_and_b32_e32 v113, 0xffff0000, v124
	v_lshlrev_b32_e32 v114, 16, v125
	v_and_b32_e32 v115, 0xffff0000, v125
	v_lshlrev_b32_e32 v116, 16, v126
	v_and_b32_e32 v117, 0xffff0000, v126
	v_lshlrev_b32_e32 v118, 16, v127
	v_and_b32_e32 v119, 0xffff0000, v127

; DI void phase_peer_u(const Args& a, int layer, int ci) {
;     ...
;             float glA = 0.f, glB = 0.f, pdA = 0.f, pdB = 0.f, rstdu = 0.f;
;             if (ci == 1) {
;                 glA = GATE[(size_t)m * 128 + lane] * GSUM[(size_t)m * 8 + (lane >> 4)] * (1.f / V_SCALE);
;                 glB = GATE[(size_t)m * 128 + 64 + lane] * GSUM[(size_t)m * 8 + 4 + (lane >> 4)] * (1.f / V_SCALE);
;                 pdA = PD[(size_t)m * 128 + lane]; pdB = PD[(size_t)m * 128 + 64 + lane];
;                 rstdu = __builtin_bit_cast(float, __builtin_amdgcn_readfirstlane(__builtin_bit_cast(int, rsqrtf(wave_sum(lane < 32 ? ((const float*)(ws + WS_RSS))[((size_t)layer * M + m) * 32 + lane] : 0.f) * (1.f / D) + 1e-6f) * (1.f / U_SCALE))));
;             }
;     ...
;                 else { if (g8 < 8) rA = mine ? gelu_tanh((cv + pdA) * rstdu) * glA : rA; else rB = mine ? gelu_tanh((cv + pdB) * rstdu) * glB : rB; }
; #pragma unroll
;                 for (int j = 0; j < 8; ++j) cur[j] = nxt[j];
;             }
;             if (ci == 0) { PD[(size_t)m * 128 + lane] = rA; PD[(size_t)m * 128 + 64 + lane] = rB; }
;             else { GATE[(size_t)m * 128 + lane] = rA; GATE[(size_t)m * 128 + 64 + lane] = rB; }
.Lpuc_entry:
	v_readlane_b32 s1, v252, 0
	v_readlane_b32 s19, v255, 12
	v_lshrrev_b32_e32 v5, 6, v185
	v_and_b32_e32 v6, 63, v185
	v_lshlrev_b32_e32 v0, 2, v6
	v_and_b32_e32 v1, 31, v6
	v_lshlrev_b32_e32 v1, 2, v1
	v_lshrrev_b32_e32 v3, 5, v6
	v_bfe_u32 v4, v6, 1, 1
	v_lshl_or_b32 v3, v3, 1, v4
	v_bfe_u32 v7, v6, 2, 3
	v_and_b32_e32 v4, 1, v6
	v_lshl_or_b32 v2, v3, 4, v7
	v_lshl_or_b32 v2, v4, 3, v2
	v_lshlrev_b32_e32 v2, 2, v2
	v_lshlrev_b32_e32 v3, 2, v3
	v_readfirstlane_b32 s44, v5
	s_lshl_b32 s45, s1, 3
	s_add_u32 s45, s45, s44
	s_lshl_b32 s46, s45, 9
	s_add_u32 s46, s46, 0x20000000
	s_add_u32 s38, s98, s46
	s_addc_u32 s39, s99, 0
	s_lshl_b32 s46, s45, 9
	s_add_u32 s46, s46, 0x7000000
	s_add_u32 s42, s98, s46
	s_addc_u32 s43, s99, 0
	s_mov_b64 s[16:17], s[42:43]
	s_lshl_b32 s46, s19, 22
	s_lshl_b32 s47, s45, 7
	s_add_u32 s46, s46, s47
	s_add_u32 s46, s46, 0xd800000
	s_add_u32 s40, s98, s46
	s_addc_u32 s41, s99, 0
	s_lshl_b32 s46, s45, 5
	s_add_u32 s46, s46, 0x5e00000
	s_add_u32 s24, s98, s46
	s_addc_u32 s25, s99, 0
	s_mov_b32 s101, 0x39800000
	s_mov_b32 s19, 0x3d372713
	s_mov_b32 s100, 0x100000
	s_mov_b32 s0, 0
	s_mov_b64 s[22:23], s[38:39]
	global_load_dword v8, v0, s[22:23]
	global_load_dword v9, v0, s[22:23] offset:256
	s_add_u32 s22, s22, 0x1000000
	s_addc_u32 s23, s23, 0
	global_load_dword v10, v0, s[22:23]
	global_load_dword v11, v0, s[22:23] offset:256
	s_add_u32 s22, s22, 0x1000000
	s_addc_u32 s23, s23, 0
	global_load_dword v12, v0, s[22:23]
	global_load_dword v13, v0, s[22:23] offset:256
	s_add_u32 s22, s22, 0x1000000
	s_addc_u32 s23, s23, 0
	global_load_dword v14, v0, s[22:23]
	global_load_dword v15, v0, s[22:23] offset:256
	s_add_u32 s22, s22, 0x1000000
	s_addc_u32 s23, s23, 0
	global_load_dword v16, v0, s[22:23]
	global_load_dword v17, v0, s[22:23] offset:256
	s_add_u32 s22, s22, 0x1000000
	s_addc_u32 s23, s23, 0
	global_load_dword v18, v0, s[22:23]
	global_load_dword v19, v0, s[22:23] offset:256
	s_add_u32 s22, s22, 0x1000000
	s_addc_u32 s23, s23, 0
	global_load_dword v20, v0, s[22:23]
	global_load_dword v21, v0, s[22:23] offset:256
	s_add_u32 s22, s22, 0x1000000
	s_addc_u32 s23, s23, 0
	global_load_dword v22, v0, s[22:23]
	global_load_dword v23, v0, s[22:23] offset:256
	s_add_u32 s22, s22, 0x1000000
	s_addc_u32 s23, s23, 0
	global_load_dword v24, v0, s[22:23]
	global_load_dword v25, v0, s[22:23] offset:256
	s_add_u32 s22, s22, 0x1000000
	s_addc_u32 s23, s23, 0
	global_load_dword v26, v0, s[22:23]
	global_load_dword v27, v0, s[22:23] offset:256
	s_add_u32 s22, s22, 0x1000000
	s_addc_u32 s23, s23, 0
	global_load_dword v28, v0, s[22:23]
	global_load_dword v29, v0, s[22:23] offset:256
	s_add_u32 s22, s22, 0x1000000
	s_addc_u32 s23, s23, 0
	global_load_dword v30, v0, s[22:23]
	global_load_dword v31, v0, s[22:23] offset:256
	s_add_u32 s22, s22, 0x1000000
	s_addc_u32 s23, s23, 0
	global_load_dword v32, v0, s[22:23]
	global_load_dword v33, v0, s[22:23] offset:256
	s_add_u32 s22, s22, 0x1000000
	s_addc_u32 s23, s23, 0
	global_load_dword v34, v0, s[22:23]
	global_load_dword v35, v0, s[22:23] offset:256
	s_add_u32 s22, s22, 0x1000000
	s_addc_u32 s23, s23, 0
	global_load_dword v36, v0, s[22:23]
	global_load_dword v37, v0, s[22:23] offset:256
	s_add_u32 s22, s22, 0x1000000
	s_addc_u32 s23, s23, 0
	global_load_dword v38, v0, s[22:23]
	global_load_dword v39, v0, s[22:23] offset:256
	global_load_dword v40, v1, s[40:41]
	global_load_dword v41, v2, s[42:43]
	global_load_dword v42, v2, s[42:43] offset:256
	global_load_dword v43, v3, s[24:25]
	global_load_dword v44, v3, s[24:25] offset:16
.Lpuc_loop:
	s_add_u32 s38, s38, s100
	s_addc_u32 s39, s39, 0
	s_lshr_b32 s44, s100, 2
	s_add_u32 s40, s40, s44
	s_addc_u32 s41, s41, 0
	s_lshr_b32 s44, s100, 4
	s_add_u32 s24, s24, s44
	s_addc_u32 s25, s25, 0
	s_add_u32 s42, s42, s100
	s_addc_u32 s43, s43, 0
	s_mov_b64 s[22:23], s[38:39]
	global_load_dword v56, v0, s[22:23]
	global_load_dword v57, v0, s[22:23] offset:256
	s_add_u32 s22, s22, 0x1000000
	s_addc_u32 s23, s23, 0
	global_load_dword v58, v0, s[22:23]
	global_load_dword v59, v0, s[22:23] offset:256
	s_add_u32 s22, s22, 0x1000000
	s_addc_u32 s23, s23, 0
	global_load_dword v60, v0, s[22:23]
	global_load_dword v61, v0, s[22:23] offset:256
	s_add_u32 s22, s22, 0x1000000
	s_addc_u32 s23, s23, 0
	global_load_dword v62, v0, s[22:23]
	global_load_dword v63, v0, s[22:23] offset:256
	s_add_u32 s22, s22, 0x1000000
	s_addc_u32 s23, s23, 0
	global_load_dword v64, v0, s[22:23]
	global_load_dword v65, v0, s[22:23] offset:256
	s_add_u32 s22, s22, 0x1000000
	s_addc_u32 s23, s23, 0
	global_load_dword v66, v0, s[22:23]
	global_load_dword v67, v0, s[22:23] offset:256
	s_add_u32 s22, s22, 0x1000000
	s_addc_u32 s23, s23, 0
	global_load_dword v68, v0, s[22:23]
	global_load_dword v69, v0, s[22:23] offset:256
	s_add_u32 s22, s22, 0x1000000
	s_addc_u32 s23, s23, 0
	global_load_dword v70, v0, s[22:23]
	global_load_dword v71, v0, s[22:23] offset:256
	s_add_u32 s22, s22, 0x1000000
	s_addc_u32 s23, s23, 0
	global_load_dword v72, v0, s[22:23]
	global_load_dword v73, v0, s[22:23] offset:256
	s_add_u32 s22, s22, 0x1000000
	s_addc_u32 s23, s23, 0
	global_load_dword v74, v0, s[22:23]
	global_load_dword v75, v0, s[22:23] offset:256
	s_add_u32 s22, s22, 0x1000000
	s_addc_u32 s23, s23, 0
	global_load_dword v76, v0, s[22:23]
	global_load_dword v77, v0, s[22:23] offset:256
	s_add_u32 s22, s22, 0x1000000
	s_addc_u32 s23, s23, 0
	global_load_dword v78, v0, s[22:23]
	global_load_dword v79, v0, s[22:23] offset:256
	s_add_u32 s22, s22, 0x1000000
	s_addc_u32 s23, s23, 0
	global_load_dword v80, v0, s[22:23]
	global_load_dword v81, v0, s[22:23] offset:256
	s_add_u32 s22, s22, 0x1000000
	s_addc_u32 s23, s23, 0
	global_load_dword v82, v0, s[22:23]
	global_load_dword v83, v0, s[22:23] offset:256
	s_add_u32 s22, s22, 0x1000000
	s_addc_u32 s23, s23, 0
	global_load_dword v84, v0, s[22:23]
	global_load_dword v85, v0, s[22:23] offset:256
	s_add_u32 s22, s22, 0x1000000
	s_addc_u32 s23, s23, 0
	global_load_dword v86, v0, s[22:23]
	global_load_dword v87, v0, s[22:23] offset:256
	global_load_dword v88, v1, s[40:41]
	global_load_dword v89, v2, s[42:43]
	global_load_dword v90, v2, s[42:43] offset:256
	global_load_dword v91, v3, s[24:25]
	global_load_dword v92, v3, s[24:25] offset:16
	s_waitcnt vmcnt(37)
; DI float gelu_tanh(float x) {
;     const float y = 0.7978845608028654f * (x + 0.044715f * x * x * x);
;     const float t = __expf(2.f * y);
;     const float th = 1.f - 2.f / (t + 1.f);
;     return 0.5f * x * (1.f + th);
; }
; DI void phase_peer_u(const Args& a, int layer, int ci) {
;     ...
;             float glA = 0.f, glB = 0.f, pdA = 0.f, pdB = 0.f, rstdu = 0.f;
;             if (ci == 1) {
;                 glA = GATE[(size_t)m * 128 + lane] * GSUM[(size_t)m * 8 + (lane >> 4)] * (1.f / V_SCALE);
;                 glB = GATE[(size_t)m * 128 + 64 + lane] * GSUM[(size_t)m * 8 + 4 + (lane >> 4)] * (1.f / V_SCALE);
;                 pdA = PD[(size_t)m * 128 + lane]; pdB = PD[(size_t)m * 128 + 64 + lane];
;                 rstdu = __builtin_bit_cast(float, __builtin_amdgcn_readfirstlane(__builtin_bit_cast(int, rsqrtf(wave_sum(lane < 32 ? ((const float*)(ws + WS_RSS))[((size_t)layer * M + m) * 32 + lane] : 0.f) * (1.f / D) + 1e-6f) * (1.f / U_SCALE))));
;             }
;             float rA = 0.f, rB = 0.f;
; #pragma unroll 1
;             for (int g8 = 0; g8 < 16; ++g8) {
;                 u32x4 nxt[8];
;                 if (g8 < 15) gat_loadhu(U, idA, idB, g8 + 1, lo16, nxt); else gat_loadhu(U, idAn, idBn, 0, lo16, nxt);
;                 const float c0 = dots4h(xa, xb, cur[0], cur[1], cur[2], cur[3], lane);
;                 const float c1 = dots4h(xa, xb, cur[4], cur[5], cur[6], cur[7], lane);
;                 const int q4 = (g8 & 7) * 2;
;                 const float cv = (lane >> 2) == q4 ? c0 : c1;
;                 const bool mine = (lane >> 3) == (g8 & 7);
;                 if (ci == 0) { if (g8 < 8) rA = mine ? cv : rA; else rB = mine ? cv : rB; }
;                 else { if (g8 < 8) rA = mine ? gelu_tanh((cv + pdA) * rstdu) * glA : rA; else rB = mine ? gelu_tanh((cv + pdB) * rstdu) * glB : rB; }
; #pragma unroll
;                 for (int j = 0; j < 8; ++j) cur[j] = nxt[j];
;             }
;             if (ci == 0) { PD[(size_t)m * 128 + lane] = rA; PD[(size_t)m * 128 + 64 + lane] = rB; }
;             else { GATE[(size_t)m * 128 + lane] = rA; GATE[(size_t)m * 128 + 64 + lane] = rB; }
	v_add_f32_e32 v104, v8, v10
	v_add_f32_e32 v104, v104, v12
	v_add_f32_e32 v104, v104, v14
	v_add_f32_e32 v104, v104, v16
	v_add_f32_e32 v104, v104, v18
	v_add_f32_e32 v104, v104, v20
	v_add_f32_e32 v104, v104, v22
	v_add_f32_e32 v104, v104, v24
	v_add_f32_e32 v104, v104, v26
	v_add_f32_e32 v104, v104, v28
	v_add_f32_e32 v104, v104, v30
	v_add_f32_e32 v104, v104, v32
	v_add_f32_e32 v104, v104, v34
	v_add_f32_e32 v104, v104, v36
	v_add_f32_e32 v104, v104, v38
	v_add_f32_e32 v105, v9, v11
	v_add_f32_e32 v105, v105, v13
	v_add_f32_e32 v105, v105, v15
	v_add_f32_e32 v105, v105, v17
	v_add_f32_e32 v105, v105, v19
	v_add_f32_e32 v105, v105, v21
	v_add_f32_e32 v105, v105, v23
	v_add_f32_e32 v105, v105, v25
	v_add_f32_e32 v105, v105, v27
	v_add_f32_e32 v105, v105, v29
	v_add_f32_e32 v105, v105, v31
	v_add_f32_e32 v105, v105, v33
	v_add_f32_e32 v105, v105, v35
	v_add_f32_e32 v105, v105, v37
	v_add_f32_e32 v105, v105, v39
	v_mov_b32_e32 v106, v40
	s_nop 1
	v_add_f32_dpp v106, v106, v106 quad_perm:[1,0,3,2] row_mask:0xf bank_mask:0xf
	s_nop 1
	v_add_f32_dpp v106, v106, v106 quad_perm:[2,3,0,1] row_mask:0xf bank_mask:0xf
	s_nop 1
	v_add_f32_dpp v106, v106, v106 row_half_mirror row_mask:0xf bank_mask:0xf
	s_nop 1
	v_add_f32_dpp v106, v106, v106 row_mirror row_mask:0xf bank_mask:0xf
	s_nop 1
	v_readlane_b32 s44, v106, 0
	v_readlane_b32 s45, v106, 16
	v_readlane_b32 s46, v106, 32
	v_readlane_b32 s47, v106, 48
	s_nop 1
	v_mov_b32_e32 v107, s44
	v_add_f32_e32 v107, s45, v107
	v_add_f32_e32 v107, s46, v107
	v_add_f32_e32 v107, s47, v107
	v_fma_f32 v107, v107, s101, v190
	v_rsq_f32_e32 v107, v107
	s_nop 0
	v_mul_f32_e32 v107, 0x3b000000, v107
	v_mul_f32_e32 v108, 0x3c800000, v43
	v_mul_f32_e32 v109, 0x3c800000, v44
	v_mul_f32_e32 v108, v108, v41
	v_mul_f32_e32 v109, v109, v42
	v_mul_f32_e32 v104, v104, v107
	v_mul_f32_e32 v110, v104, v104
	v_mul_f32_e32 v110, v110, v104
	v_fma_f32 v110, v110, s19, v104
	v_mul_f32_e32 v110, 0x40135761, v110
	v_exp_f32_e32 v110, v110
	s_nop 0
	v_add_f32_e32 v110, 1.0, v110
	v_rcp_f32_e32 v110, v110
	s_nop 0
	v_fma_f32 v111, -v104, v110, v104
	v_mul_f32_e32 v111, v111, v108
	v_mul_f32_e32 v105, v105, v107
	v_mul_f32_e32 v112, v105, v105
	v_mul_f32_e32 v112, v112, v105
	v_fma_f32 v112, v112, s19, v105
	v_mul_f32_e32 v112, 0x40135761, v112
	v_exp_f32_e32 v112, v112
	s_nop 0
	v_add_f32_e32 v112, 1.0, v112
	v_rcp_f32_e32 v112, v112
	s_nop 0
	v_fma_f32 v113, -v105, v112, v105
	v_mul_f32_e32 v113, v113, v109
	global_store_dword v2, v111, s[16:17]
	global_store_dword v2, v113, s[16:17] offset:256
	s_add_u32 s16, s16, 0x100000
	s_addc_u32 s17, s17, 0
	s_cmp_eq_u32 s0, 7
	s_cselect_b32 s100, 0, s100
	s_add_u32 s38, s38, s100
	s_addc_u32 s39, s39, 0
	s_lshr_b32 s44, s100, 2
	s_add_u32 s40, s40, s44
	s_addc_u32 s41, s41, 0
	s_lshr_b32 s44, s100, 4
	s_add_u32 s24, s24, s44
	s_addc_u32 s25, s25, 0
	s_add_u32 s42, s42, s100
	s_addc_u32 s43, s43, 0
	s_mov_b64 s[22:23], s[38:39]
	global_load_dword v8, v0, s[22:23]
	global_load_dword v9, v0, s[22:23] offset:256
	s_add_u32 s22, s22, 0x1000000
	s_addc_u32 s23, s23, 0
	global_load_dword v10, v0, s[22:23]
	global_load_dword v11, v0, s[22:23] offset:256
	s_add_u32 s22, s22, 0x1000000
	s_addc_u32 s23, s23, 0
	global_load_dword v12, v0, s[22:23]
	global_load_dword v13, v0, s[22:23] offset:256
	s_add_u32 s22, s22, 0x1000000
	s_addc_u32 s23, s23, 0
	global_load_dword v14, v0, s[22:23]
	global_load_dword v15, v0, s[22:23] offset:256
	s_add_u32 s22, s22, 0x1000000
	s_addc_u32 s23, s23, 0
	global_load_dword v16, v0, s[22:23]
	global_load_dword v17, v0, s[22:23] offset:256
	s_add_u32 s22, s22, 0x1000000
	s_addc_u32 s23, s23, 0
	global_load_dword v18, v0, s[22:23]
	global_load_dword v19, v0, s[22:23] offset:256
	s_add_u32 s22, s22, 0x1000000
	s_addc_u32 s23, s23, 0
	global_load_dword v20, v0, s[22:23]
	global_load_dword v21, v0, s[22:23] offset:256
	s_add_u32 s22, s22, 0x1000000
	s_addc_u32 s23, s23, 0
	global_load_dword v22, v0, s[22:23]
	global_load_dword v23, v0, s[22:23] offset:256
	s_add_u32 s22, s22, 0x1000000
	s_addc_u32 s23, s23, 0
	global_load_dword v24, v0, s[22:23]
	global_load_dword v25, v0, s[22:23] offset:256
	s_add_u32 s22, s22, 0x1000000
	s_addc_u32 s23, s23, 0
	global_load_dword v26, v0, s[22:23]
	global_load_dword v27, v0, s[22:23] offset:256
	s_add_u32 s22, s22, 0x1000000
	s_addc_u32 s23, s23, 0
	global_load_dword v28, v0, s[22:23]
	global_load_dword v29, v0, s[22:23] offset:256
	s_add_u32 s22, s22, 0x1000000
	s_addc_u32 s23, s23, 0
	global_load_dword v30, v0, s[22:23]
	global_load_dword v31, v0, s[22:23] offset:256
	s_add_u32 s22, s22, 0x1000000
	s_addc_u32 s23, s23, 0
	global_load_dword v32, v0, s[22:23]
	global_load_dword v33, v0, s[22:23] offset:256
	s_add_u32 s22, s22, 0x1000000
	s_addc_u32 s23, s23, 0
	global_load_dword v34, v0, s[22:23]
	global_load_dword v35, v0, s[22:23] offset:256
	s_add_u32 s22, s22, 0x1000000
	s_addc_u32 s23, s23, 0
	global_load_dword v36, v0, s[22:23]
	global_load_dword v37, v0, s[22:23] offset:256
	s_add_u32 s22, s22, 0x1000000
	s_addc_u32 s23, s23, 0
	global_load_dword v38, v0, s[22:23]
	global_load_dword v39, v0, s[22:23] offset:256
	global_load_dword v40, v1, s[40:41]
	global_load_dword v41, v2, s[42:43]
	global_load_dword v42, v2, s[42:43] offset:256
	global_load_dword v43, v3, s[24:25]
	global_load_dword v44, v3, s[24:25] offset:16
	s_waitcnt vmcnt(37)
; DI float gelu_tanh(float x) {
;     const float y = 0.7978845608028654f * (x + 0.044715f * x * x * x);
;     const float t = __expf(2.f * y);
;     const float th = 1.f - 2.f / (t + 1.f);
;     return 0.5f * x * (1.f + th);
; }
; DI void phase_peer_u(const Args& a, int layer, int ci) {
;     ...
;             float glA = 0.f, glB = 0.f, pdA = 0.f, pdB = 0.f, rstdu = 0.f;
;             if (ci == 1) {
;                 glA = GATE[(size_t)m * 128 + lane] * GSUM[(size_t)m * 8 + (lane >> 4)] * (1.f / V_SCALE);
;                 glB = GATE[(size_t)m * 128 + 64 + lane] * GSUM[(size_t)m * 8 + 4 + (lane >> 4)] * (1.f / V_SCALE);
;                 pdA = PD[(size_t)m * 128 + lane]; pdB = PD[(size_t)m * 128 + 64 + lane];
;                 rstdu = __builtin_bit_cast(float, __builtin_amdgcn_readfirstlane(__builtin_bit_cast(int, rsqrtf(wave_sum(lane < 32 ? ((const float*)(ws + WS_RSS))[((size_t)layer * M + m) * 32 + lane] : 0.f) * (1.f / D) + 1e-6f) * (1.f / U_SCALE))));
;             }
;             float rA = 0.f, rB = 0.f;
; #pragma unroll 1
;             for (int g8 = 0; g8 < 16; ++g8) {
;                 u32x4 nxt[8];
;                 if (g8 < 15) gat_loadhu(U, idA, idB, g8 + 1, lo16, nxt); else gat_loadhu(U, idAn, idBn, 0, lo16, nxt);
;                 const float c0 = dots4h(xa, xb, cur[0], cur[1], cur[2], cur[3], lane);
;                 const float c1 = dots4h(xa, xb, cur[4], cur[5], cur[6], cur[7], lane);
;                 const int q4 = (g8 & 7) * 2;
;                 const float cv = (lane >> 2) == q4 ? c0 : c1;
;                 const bool mine = (lane >> 3) == (g8 & 7);
;                 if (ci == 0) { if (g8 < 8) rA = mine ? cv : rA; else rB = mine ? cv : rB; }
;                 else { if (g8 < 8) rA = mine ? gelu_tanh((cv + pdA) * rstdu) * glA : rA; else rB = mine ? gelu_tanh((cv + pdB) * rstdu) * glB : rB; }
; #pragma unroll
;                 for (int j = 0; j < 8; ++j) cur[j] = nxt[j];
;             }
;             if (ci == 0) { PD[(size_t)m * 128 + lane] = rA; PD[(size_t)m * 128 + 64 + lane] = rB; }
;             else { GATE[(size_t)m * 128 + lane] = rA; GATE[(size_t)m * 128 + 64 + lane] = rB; }
	v_add_f32_e32 v104, v56, v58
	v_add_f32_e32 v104, v104, v60
	v_add_f32_e32 v104, v104, v62
	v_add_f32_e32 v104, v104, v64
	v_add_f32_e32 v104, v104, v66
	v_add_f32_e32 v104, v104, v68
	v_add_f32_e32 v104, v104, v70
	v_add_f32_e32 v104, v104, v72
	v_add_f32_e32 v104, v104, v74
	v_add_f32_e32 v104, v104, v76
	v_add_f32_e32 v104, v104, v78
	v_add_f32_e32 v104, v104, v80
	v_add_f32_e32 v104, v104, v82
	v_add_f32_e32 v104, v104, v84
	v_add_f32_e32 v104, v104, v86
	v_add_f32_e32 v105, v57, v59
	v_add_f32_e32 v105, v105, v61
	v_add_f32_e32 v105, v105, v63
	v_add_f32_e32 v105, v105, v65
	v_add_f32_e32 v105, v105, v67
	v_add_f32_e32 v105, v105, v69
	v_add_f32_e32 v105, v105, v71
	v_add_f32_e32 v105, v105, v73
	v_add_f32_e32 v105, v105, v75
	v_add_f32_e32 v105, v105, v77
	v_add_f32_e32 v105, v105, v79
	v_add_f32_e32 v105, v105, v81
	v_add_f32_e32 v105, v105, v83
	v_add_f32_e32 v105, v105, v85
	v_add_f32_e32 v105, v105, v87
	v_mov_b32_e32 v106, v88
	s_nop 1
	v_add_f32_dpp v106, v106, v106 quad_perm:[1,0,3,2] row_mask:0xf bank_mask:0xf
	s_nop 1
	v_add_f32_dpp v106, v106, v106 quad_perm:[2,3,0,1] row_mask:0xf bank_mask:0xf
	s_nop 1
	v_add_f32_dpp v106, v106, v106 row_half_mirror row_mask:0xf bank_mask:0xf
	s_nop 1
	v_add_f32_dpp v106, v106, v106 row_mirror row_mask:0xf bank_mask:0xf
	s_nop 1
	v_readlane_b32 s44, v106, 0
	v_readlane_b32 s45, v106, 16
	v_readlane_b32 s46, v106, 32
	v_readlane_b32 s47, v106, 48
	s_nop 1
	v_mov_b32_e32 v107, s44
	v_add_f32_e32 v107, s45, v107
	v_add_f32_e32 v107, s46, v107
	v_add_f32_e32 v107, s47, v107
	v_fma_f32 v107, v107, s101, v190
	v_rsq_f32_e32 v107, v107
	s_nop 0
	v_mul_f32_e32 v107, 0x3b000000, v107
	v_mul_f32_e32 v108, 0x3c800000, v91
	v_mul_f32_e32 v109, 0x3c800000, v92
	v_mul_f32_e32 v108, v108, v89
	v_mul_f32_e32 v109, v109, v90
	v_mul_f32_e32 v104, v104, v107
	v_mul_f32_e32 v110, v104, v104
	v_mul_f32_e32 v110, v110, v104
	v_fma_f32 v110, v110, s19, v104
	v_mul_f32_e32 v110, 0x40135761, v110
	v_exp_f32_e32 v110, v110
	s_nop 0
	v_add_f32_e32 v110, 1.0, v110
	v_rcp_f32_e32 v110, v110
	s_nop 0
	v_fma_f32 v111, -v104, v110, v104
	v_mul_f32_e32 v111, v111, v108
	v_mul_f32_e32 v105, v105, v107
	v_mul_f32_e32 v112, v105, v105
	v_mul_f32_e32 v112, v112, v105
	v_fma_f32 v112, v112, s19, v105
	v_mul_f32_e32 v112, 0x40135761, v112
	v_exp_f32_e32 v112, v112
	s_nop 0
	v_add_f32_e32 v112, 1.0, v112
	v_rcp_f32_e32 v112, v112
	s_nop 0
	v_fma_f32 v113, -v105, v112, v105
	v_mul_f32_e32 v113, v113, v109
	global_store_dword v2, v111, s[16:17]
	global_store_dword v2, v113, s[16:17] offset:256
	s_add_u32 s16, s16, 0x100000
	s_addc_u32 s17, s17, 0
	s_add_u32 s0, s0, 1
	s_cmp_lt_u32 s0, 8
	s_cbranch_scc1 .Lpuc_loop
	s_waitcnt vmcnt(0)
	s_branch .LBB0_495

; DI void convert_rows_fp8(const float* src, unsigned char* dst, size_t n16, float scale, size_t gt, size_t ngt, const float* gnorm = nullptr) {
;     for (size_t i = gt; i < n16; i += ngt) {
;         f32x4 a = ((const f32x4*)src)[4 * i] * scale, b = ((const f32x4*)src)[4 * i + 1] * scale, c = ((const f32x4*)src)[4 * i + 2] * scale, d = ((const f32x4*)src)[4 * i + 3] * scale;
;         if (gnorm) { const f32x4* gp = (const f32x4*)(gnorm + ((16 * i) / ((size_t)NEXP * D)) * D + (16 * i) % D); a = a * gp[0]; b = b * gp[1]; c = c * gp[2]; d = d * gp[3]; }
;         u32x4 o;
;         o.x = (unsigned)__builtin_amdgcn_cvt_pk_fp8_f32(a.z, a.w, __builtin_amdgcn_cvt_pk_fp8_f32(a.x, a.y, 0, false), true);
;         o.y = (unsigned)__builtin_amdgcn_cvt_pk_fp8_f32(b.z, b.w, __builtin_amdgcn_cvt_pk_fp8_f32(b.x, b.y, 0, false), true);
;         o.z = (unsigned)__builtin_amdgcn_cvt_pk_fp8_f32(c.z, c.w, __builtin_amdgcn_cvt_pk_fp8_f32(c.x, c.y, 0, false), true);
;         o.w = (unsigned)__builtin_amdgcn_cvt_pk_fp8_f32(d.z, d.w, __builtin_amdgcn_cvt_pk_fp8_f32(d.x, d.y, 0, false), true);
;         ((u32x4*)dst)[i] = o;
;     }
; }
.LBB0_649:
	v_mov_b32_e32 v30, v129
	v_mov_b32_e32 v31, v129
	v_mov_b32_e32 v32, v129
	v_mov_b32_e32 v33, v129
	v_cvt_pk_fp8_f32 v30, v28, v29
	v_cvt_pk_fp8_f32 v31, v26, v27
	v_cvt_pk_fp8_f32 v32, v24, v25
	v_cvt_pk_fp8_f32 v33, v22, v23
	v_cvt_pk_fp8_f32 v30, v14, v15 op_sel:[0,0,1]
	v_cvt_pk_fp8_f32 v31, v16, v17 op_sel:[0,0,1]
	v_cvt_pk_fp8_f32 v32, v20, v21 op_sel:[0,0,1]
	v_cvt_pk_fp8_f32 v33, v18, v19 op_sel:[0,0,1]
	v_readlane_b32 s16, v252, 15
	v_lshl_add_u64 v[12:13], v[12:13], 0, s[0:1]
	v_readlane_b32 s17, v252, 16
	v_cmp_lt_u64_e32 vcc, s[34:35], v[12:13]
	s_or_b64 s[42:43], vcc, s[42:43]
	v_and_b32_e32 v47, 0x2000070, v8
	v_lshlrev_b32_e32 v48, 14, v8
	v_and_b32_e32 v48, 0x1e00000, v48
	v_or_b32_e32 v47, v47, v48
	v_lshrrev_b32_e32 v48, 4, v8
	v_and_b32_e32 v48, 0x1fff80, v48
	v_or_b32_e32 v47, v47, v48
	v_lshl_add_u64 v[8:9], v[8:9], 0, s[38:39]
	v_lshl_add_u64 v[10:11], v[10:11], 0, s[40:41]
	global_store_dwordx4 v47, v[30:33], s[16:17]
	s_andn2_b64 exec, exec, s[42:43]
	s_cbranch_execz .LBB0_652
